# v18 + pipelined gated o-proj epilogues (kinds 3/4): g3/tmp loads 4 combos ahead into freed accumulator regs, counted vmcnt, same IEEE-division sigmoid arithmetic, two division chains interleaved
# speedup vs baseline: 1.0140x; 1.0140x over previous
; #define PG8_STAGE(bufoff, gbase, voff) do { _Pragma("unroll") for (int _i = 0; _i < 2; ++_i) \
;     __builtin_amdgcn_global_load_lds((const unsigned*)((const char*)(gbase) + (voff)[_i]), (LAS unsigned*)(lds + (bufoff) + ldsw + _i * 8192), 16, 0, 0); } while (0)
; #define PG8_LDA(dst, b, h) do { _Pragma("unroll") for (int m = 0; m < 4; ++m) _Pragma("unroll") for (int k = 0; k < 2; ++k) dst[m][k] = *(const LAS bf16x8*)(lds + PG8_SA(b, h) + aoff + m * 2048 + k * 1024); } while (0)
; #define PG8_LDB(dst, b, h) do { _Pragma("unroll") for (int n = 0; n < 2; ++n) _Pragma("unroll") for (int k = 0; k < 2; ++k) dst[n][k] = *(const LAS bf16x8*)(lds + PG8_SB(b, h) + boff + n * 2048 + k * 1024); } while (0)
; #define PG8_MMA(ai, bj, At, Bt) do { __builtin_amdgcn_s_setprio(1); _Pragma("unroll") for (int m = 0; m < 4; ++m) _Pragma("unroll") for (int n = 0; n < 2; ++n) _Pragma("unroll") for (int k = 0; k < 2; ++k) \
;     acc[ai][bj][m][n] = __builtin_amdgcn_mfma_f32_16x16x32_bf16(Bt[n][k], At[m][k], acc[ai][bj][m][n], 0, 0, 0); __builtin_amdgcn_s_setprio(0); } while (0)
; #define PG8_WAIT_L(n) asm volatile("s_waitcnt lgkmcnt(" #n ")" ::: "memory")
; #define PG8_BAR __builtin_amdgcn_s_barrier()
; #define PG8_SCHED __builtin_amdgcn_sched_barrier(0)
; template <class Epi>
; __device__ __forceinline__ void gemm_phase(LAS unsigned char* lds, const Gemm g, const Epi& E) {
;     ...
;       PG8_LDB(B0, 0, 0); PG8_SCHED; PG8_LDA(At, 0, 0); PG8_STAGE(PG8_SA(1, 1), a1 + hstepA, voffA);
;       PG8_WAIT_L(8); PG8_BAR; PG8_WAIT_L(0); PG8_MMA(0, 0, At, B0); PG8_BAR; PG8_SCHED;
;       PG8_LDB(B1, 0, 1); PG8_STAGE(PG8_SB(0, 0), b2, voffB);
;       PG8_BAR; PG8_WAIT_L(0); PG8_MMA(0, 1, At, B1); PG8_BAR;
;       PG8_LDA(At, 0, 1); PG8_STAGE(PG8_SA(0, 0), a2, voffA);
;       PG8_BAR; PG8_WAIT_L(0); PG8_MMA(1, 0, At, B0); PG8_BAR; PG8_SCHED;
.LBB0_579:
	s_add_i32 s76, s26, 2
	s_add_u32 s28, s2, 0x80
	s_addc_u32 s27, s3, 0
	s_add_i32 s83, 0, 0x10000
	v_add_u32_e32 v156, s83, v173
	ds_read_b128 v[128:131], v156
	ds_read_b128 v[148:151], v156 offset:1024
	ds_read_b128 v[152:155], v156 offset:2048
	ds_read_b128 v[156:159], v156 offset:3072
	s_cmp_eq_u32 s89, s26
	s_cselect_b32 s26, s0, s28
	s_cselect_b32 s27, s1, s27
	s_cselect_b32 s29, s21, s39
	s_cselect_b32 s28, s20, s38
	v_lshl_add_u64 v[196:197], s[2:3], 0, v[144:145]
	s_add_i32 m0, s84, 0xc000
	ds_read_b128 v[160:163], v175
	ds_read_b128 v[164:167], v175 offset:1024
	ds_read_b128 v[168:171], v175 offset:2048
	ds_read_b128 v[176:179], v175 offset:3072
	ds_read_b128 v[180:183], v175 offset:4096
	ds_read_b128 v[184:187], v175 offset:5120
	ds_read_b128 v[188:191], v175 offset:6144
	ds_read_b128 v[192:195], v175 offset:7168
	global_load_lds_dwordx4 v[196:197], off
	v_lshl_add_u64 v[196:197], s[2:3], 0, v[146:147]
	s_add_i32 m0, s84, 0xe000
	s_nop 0
	global_load_lds_dwordx4 v[196:197], off
	s_waitcnt lgkmcnt(8)
	s_barrier
	s_waitcnt lgkmcnt(0)
	s_setprio 1
	s_waitcnt lgkmcnt(0)
	v_mfma_f32_16x16x32_bf16 v[124:127], v[128:131], v[160:163], v[124:127]
	v_mfma_f32_16x16x32_bf16 v[120:123], v[152:155], v[160:163], v[120:123]
	v_mfma_f32_16x16x32_bf16 v[108:111], v[128:131], v[168:171], v[108:111]
	v_mfma_f32_16x16x32_bf16 v[104:107], v[152:155], v[168:171], v[104:107]
	v_mfma_f32_16x16x32_bf16 v[92:95], v[128:131], v[180:183], v[92:95]
	v_mfma_f32_16x16x32_bf16 v[88:91], v[152:155], v[180:183], v[88:91]
	v_mfma_f32_16x16x32_bf16 v[76:79], v[128:131], v[188:191], v[76:79]
	v_mfma_f32_16x16x32_bf16 v[72:75], v[152:155], v[188:191], v[72:75]
	v_mfma_f32_16x16x32_bf16 v[124:127], v[148:151], v[164:167], v[124:127]
	v_mfma_f32_16x16x32_bf16 v[120:123], v[156:159], v[164:167], v[120:123]
	v_mfma_f32_16x16x32_bf16 v[108:111], v[148:151], v[176:179], v[108:111]
	v_mfma_f32_16x16x32_bf16 v[104:107], v[156:159], v[176:179], v[104:107]
	v_mfma_f32_16x16x32_bf16 v[92:95], v[148:151], v[184:187], v[92:95]
	v_mfma_f32_16x16x32_bf16 v[88:91], v[156:159], v[184:187], v[88:91]
	v_mfma_f32_16x16x32_bf16 v[76:79], v[148:151], v[192:195], v[76:79]
	v_mfma_f32_16x16x32_bf16 v[72:75], v[156:159], v[192:195], v[72:75]
	s_setprio 0
	s_barrier
	s_add_i32 s94, 0, 0x14000
	s_add_i32 s83, s83, s97
	v_add_u32_e32 v208, s94, v173
	v_lshl_add_u64 v[212:213], s[28:29], 0, v[132:133]
	s_mov_b32 m0, s83
	ds_read_b128 v[196:199], v208
	ds_read_b128 v[200:203], v208 offset:1024
	ds_read_b128 v[204:207], v208 offset:2048
	ds_read_b128 v[208:211], v208 offset:3072
	global_load_lds_dwordx4 v[212:213], off
	v_lshl_add_u64 v[214:215], s[28:29], 0, v[142:143]
	s_add_i32 m0, s83, 0x2000
	s_nop 0
	global_load_lds_dwordx4 v[214:215], off
	s_barrier
	s_waitcnt lgkmcnt(0)
	s_setprio 1
	s_waitcnt lgkmcnt(0)
	v_mfma_f32_16x16x32_bf16 v[116:119], v[196:199], v[160:163], v[116:119]
	v_mfma_f32_16x16x32_bf16 v[112:115], v[204:207], v[160:163], v[112:115]
	v_mfma_f32_16x16x32_bf16 v[100:103], v[196:199], v[168:171], v[100:103]
	v_mfma_f32_16x16x32_bf16 v[96:99], v[204:207], v[168:171], v[96:99]
	v_mfma_f32_16x16x32_bf16 v[84:87], v[196:199], v[180:183], v[84:87]
	v_mfma_f32_16x16x32_bf16 v[80:83], v[204:207], v[180:183], v[80:83]
	v_mfma_f32_16x16x32_bf16 v[68:71], v[196:199], v[188:191], v[68:71]
	v_mfma_f32_16x16x32_bf16 v[64:67], v[204:207], v[188:191], v[64:67]
	v_mfma_f32_16x16x32_bf16 v[116:119], v[200:203], v[164:167], v[116:119]
	v_mfma_f32_16x16x32_bf16 v[112:115], v[208:211], v[164:167], v[112:115]
	v_mfma_f32_16x16x32_bf16 v[100:103], v[200:203], v[176:179], v[100:103]
	v_mfma_f32_16x16x32_bf16 v[96:99], v[208:211], v[176:179], v[96:99]
	v_mfma_f32_16x16x32_bf16 v[84:87], v[200:203], v[184:187], v[84:87]
	v_mfma_f32_16x16x32_bf16 v[80:83], v[208:211], v[184:187], v[80:83]
	v_mfma_f32_16x16x32_bf16 v[68:71], v[200:203], v[192:195], v[68:71]
	v_mfma_f32_16x16x32_bf16 v[64:67], v[208:211], v[192:195], v[64:67]
	s_setprio 0
	s_mov_b32 m0, s84
	v_lshl_add_u64 v[216:217], s[26:27], 0, v[138:139]
	s_barrier
	ds_read_b128 v[160:163], v175 offset:16384
	ds_read_b128 v[164:167], v175 offset:17408
	ds_read_b128 v[168:171], v175 offset:18432
	ds_read_b128 v[176:179], v175 offset:19456
	ds_read_b128 v[180:183], v175 offset:20480
	ds_read_b128 v[184:187], v175 offset:21504
	ds_read_b128 v[188:191], v175 offset:22528
	ds_read_b128 v[192:195], v175 offset:23552
	global_load_lds_dwordx4 v[216:217], off
	v_lshl_add_u64 v[218:219], s[26:27], 0, v[140:141]
	s_mov_b32 m0, s85
	s_nop 0
	global_load_lds_dwordx4 v[218:219], off
	s_barrier
	s_waitcnt lgkmcnt(0)
	s_setprio 1
	s_waitcnt lgkmcnt(0)
	v_mfma_f32_16x16x32_bf16 v[60:63], v[128:131], v[160:163], v[60:63]
	v_mfma_f32_16x16x32_bf16 v[56:59], v[152:155], v[160:163], v[56:59]
	v_mfma_f32_16x16x32_bf16 v[44:47], v[128:131], v[168:171], v[44:47]
	v_mfma_f32_16x16x32_bf16 v[40:43], v[152:155], v[168:171], v[40:43]
	v_mfma_f32_16x16x32_bf16 v[28:31], v[128:131], v[180:183], v[28:31]
	v_mfma_f32_16x16x32_bf16 v[24:27], v[152:155], v[180:183], v[24:27]
	v_mfma_f32_16x16x32_bf16 v[12:15], v[128:131], v[188:191], v[12:15]
	v_mfma_f32_16x16x32_bf16 v[8:11], v[152:155], v[188:191], v[8:11]
	v_mfma_f32_16x16x32_bf16 v[60:63], v[148:151], v[164:167], v[60:63]
	v_mfma_f32_16x16x32_bf16 v[56:59], v[156:159], v[164:167], v[56:59]
	v_mfma_f32_16x16x32_bf16 v[44:47], v[148:151], v[176:179], v[44:47]
	v_mfma_f32_16x16x32_bf16 v[40:43], v[156:159], v[176:179], v[40:43]
	v_mfma_f32_16x16x32_bf16 v[28:31], v[148:151], v[184:187], v[28:31]
	v_mfma_f32_16x16x32_bf16 v[24:27], v[156:159], v[184:187], v[24:27]
	v_mfma_f32_16x16x32_bf16 v[12:15], v[148:151], v[192:195], v[12:15]
	v_mfma_f32_16x16x32_bf16 v[8:11], v[156:159], v[192:195], v[8:11]
	s_setprio 0
	s_barrier
; #define PG8_STAGE(bufoff, gbase, voff) do { _Pragma("unroll") for (int _i = 0; _i < 2; ++_i) \
;     __builtin_amdgcn_global_load_lds((const unsigned*)((const char*)(gbase) + (voff)[_i]), (LAS unsigned*)(lds + (bufoff) + ldsw + _i * 8192), 16, 0, 0); } while (0)
; #define PG8_LDA(dst, b, h) do { _Pragma("unroll") for (int m = 0; m < 4; ++m) _Pragma("unroll") for (int k = 0; k < 2; ++k) dst[m][k] = *(const LAS bf16x8*)(lds + PG8_SA(b, h) + aoff + m * 2048 + k * 1024); } while (0)
; #define PG8_LDB(dst, b, h) do { _Pragma("unroll") for (int n = 0; n < 2; ++n) _Pragma("unroll") for (int k = 0; k < 2; ++k) dst[n][k] = *(const LAS bf16x8*)(lds + PG8_SB(b, h) + boff + n * 2048 + k * 1024); } while (0)
; #define PG8_MMA(ai, bj, At, Bt) do { __builtin_amdgcn_s_setprio(1); _Pragma("unroll") for (int m = 0; m < 4; ++m) _Pragma("unroll") for (int n = 0; n < 2; ++n) _Pragma("unroll") for (int k = 0; k < 2; ++k) \
;     acc[ai][bj][m][n] = __builtin_amdgcn_mfma_f32_16x16x32_bf16(Bt[n][k], At[m][k], acc[ai][bj][m][n], 0, 0, 0); __builtin_amdgcn_s_setprio(0); } while (0)
; #define PG8_WAIT_V(n) asm volatile("s_waitcnt vmcnt(" #n ")" ::: "memory")
; #define PG8_WAIT_L(n) asm volatile("s_waitcnt lgkmcnt(" #n ")" ::: "memory")
; #define PG8_BAR __builtin_amdgcn_s_barrier()
; #define PG8_SCHED __builtin_amdgcn_sched_barrier(0)
; template <class Epi>
; __device__ __forceinline__ void gemm_phase(LAS unsigned char* lds, const Gemm g, const Epi& E) {
;     ...
;       PG8_STAGE(PG8_SB(0, 1), b2 + hstepB, voffB);
;       PG8_WAIT_V(6); PG8_BAR; PG8_MMA(1, 1, At, B1); PG8_BAR;
;       PG8_LDB(B0, 1, 0); PG8_SCHED; PG8_LDA(At, 1, 0); PG8_STAGE(PG8_SA(0, 1), a2 + hstepA, voffA);
;       PG8_WAIT_L(8); PG8_BAR; PG8_WAIT_L(0); PG8_MMA(0, 0, At, B0); PG8_BAR; PG8_SCHED;
;       PG8_LDB(B1, 1, 1); PG8_STAGE(PG8_SB(1, 0), b3, voffB);
;       PG8_BAR; PG8_WAIT_L(0); PG8_MMA(0, 1, At, B1); PG8_BAR;
	s_add_u32 s28, s28, s95
	s_addc_u32 s29, s29, 0
	s_add_i32 s83, s94, s97
	v_lshl_add_u64 v[220:221], s[28:29], 0, v[132:133]
	s_mov_b32 m0, s83
	v_lshl_add_u64 v[222:223], s[28:29], 0, v[142:143]
	global_load_lds_dwordx4 v[220:221], off
	s_add_i32 m0, s83, 0x2000
	s_nop 0
	global_load_lds_dwordx4 v[222:223], off
	s_waitcnt vmcnt(6)
	s_barrier
	s_setprio 1
	v_mfma_f32_16x16x32_bf16 v[52:55], v[196:199], v[160:163], v[52:55]
	v_mfma_f32_16x16x32_bf16 v[48:51], v[204:207], v[160:163], v[48:51]
	v_mfma_f32_16x16x32_bf16 v[36:39], v[196:199], v[168:171], v[36:39]
	v_mfma_f32_16x16x32_bf16 v[32:35], v[204:207], v[168:171], v[32:35]
	v_mfma_f32_16x16x32_bf16 v[20:23], v[196:199], v[180:183], v[20:23]
	v_mfma_f32_16x16x32_bf16 v[16:19], v[204:207], v[180:183], v[16:19]
	v_mfma_f32_16x16x32_bf16 v[4:7], v[196:199], v[188:191], v[4:7]
	v_mfma_f32_16x16x32_bf16 v[0:3], v[204:207], v[188:191], v[0:3]
	v_mfma_f32_16x16x32_bf16 v[52:55], v[200:203], v[164:167], v[52:55]
	v_mfma_f32_16x16x32_bf16 v[48:51], v[208:211], v[164:167], v[48:51]
	v_mfma_f32_16x16x32_bf16 v[36:39], v[200:203], v[176:179], v[36:39]
	v_mfma_f32_16x16x32_bf16 v[32:35], v[208:211], v[176:179], v[32:35]
	v_mfma_f32_16x16x32_bf16 v[20:23], v[200:203], v[184:187], v[20:23]
	v_mfma_f32_16x16x32_bf16 v[16:19], v[208:211], v[184:187], v[16:19]
	v_mfma_f32_16x16x32_bf16 v[4:7], v[200:203], v[192:195], v[4:7]
	v_mfma_f32_16x16x32_bf16 v[0:3], v[208:211], v[192:195], v[0:3]
	s_setprio 0
	s_add_i32 s28, 0, 0x18000
	v_add_u32_e32 v156, s28, v173
	s_barrier
	ds_read_b128 v[128:131], v156
	ds_read_b128 v[148:151], v156 offset:1024
	ds_read_b128 v[152:155], v156 offset:2048
	ds_read_b128 v[156:159], v156 offset:3072
	s_add_u32 s26, s26, s56
	s_addc_u32 s27, s27, 0
	s_mov_b32 m0, s86
	v_lshl_add_u64 v[196:197], s[26:27], 0, v[138:139]
	ds_read_b128 v[160:163], v175 offset:32768
	ds_read_b128 v[164:167], v175 offset:33792
	ds_read_b128 v[168:171], v175 offset:34816
	ds_read_b128 v[176:179], v175 offset:35840
	ds_read_b128 v[180:183], v175 offset:36864
	ds_read_b128 v[184:187], v175 offset:37888
	ds_read_b128 v[188:191], v175 offset:38912
	ds_read_b128 v[192:195], v175 offset:39936
	global_load_lds_dwordx4 v[196:197], off
	v_lshl_add_u64 v[196:197], s[26:27], 0, v[140:141]
	s_mov_b32 m0, s87
	s_nop 0
	global_load_lds_dwordx4 v[196:197], off
	s_waitcnt lgkmcnt(8)
	s_barrier
	s_waitcnt lgkmcnt(0)
	s_setprio 1
	s_waitcnt lgkmcnt(0)
	v_mfma_f32_16x16x32_bf16 v[124:127], v[128:131], v[160:163], v[124:127]
	v_mfma_f32_16x16x32_bf16 v[120:123], v[152:155], v[160:163], v[120:123]
	v_mfma_f32_16x16x32_bf16 v[108:111], v[128:131], v[168:171], v[108:111]
	v_mfma_f32_16x16x32_bf16 v[104:107], v[152:155], v[168:171], v[104:107]
	v_mfma_f32_16x16x32_bf16 v[92:95], v[128:131], v[180:183], v[92:95]
	v_mfma_f32_16x16x32_bf16 v[88:91], v[152:155], v[180:183], v[88:91]
	v_mfma_f32_16x16x32_bf16 v[76:79], v[128:131], v[188:191], v[76:79]
	v_mfma_f32_16x16x32_bf16 v[72:75], v[152:155], v[188:191], v[72:75]
	v_mfma_f32_16x16x32_bf16 v[124:127], v[148:151], v[164:167], v[124:127]
	v_mfma_f32_16x16x32_bf16 v[120:123], v[156:159], v[164:167], v[120:123]
	v_mfma_f32_16x16x32_bf16 v[108:111], v[148:151], v[176:179], v[108:111]
	v_mfma_f32_16x16x32_bf16 v[104:107], v[156:159], v[176:179], v[104:107]
	v_mfma_f32_16x16x32_bf16 v[92:95], v[148:151], v[184:187], v[92:95]
	v_mfma_f32_16x16x32_bf16 v[88:91], v[156:159], v[184:187], v[88:91]
	v_mfma_f32_16x16x32_bf16 v[76:79], v[148:151], v[192:195], v[76:79]
	v_mfma_f32_16x16x32_bf16 v[72:75], v[156:159], v[192:195], v[72:75]
	s_setprio 0
	s_barrier
	s_add_i32 s26, 0, 0x1c000
	s_add_i32 s27, s28, s97
	v_add_u32_e32 v208, s26, v173
	v_lshl_add_u64 v[212:213], v[212:213], 0, s[22:23]
	s_mov_b32 m0, s27
	ds_read_b128 v[196:199], v208
	ds_read_b128 v[200:203], v208 offset:1024
	ds_read_b128 v[204:207], v208 offset:2048
	ds_read_b128 v[208:211], v208 offset:3072
	global_load_lds_dwordx4 v[212:213], off
	v_lshl_add_u64 v[212:213], v[214:215], 0, s[22:23]
	s_add_i32 m0, s27, 0x2000
	s_nop 0
	global_load_lds_dwordx4 v[212:213], off
	s_barrier
	s_waitcnt lgkmcnt(0)
	s_setprio 1
	s_waitcnt lgkmcnt(0)
	v_mfma_f32_16x16x32_bf16 v[116:119], v[196:199], v[160:163], v[116:119]
	v_mfma_f32_16x16x32_bf16 v[112:115], v[204:207], v[160:163], v[112:115]
	v_mfma_f32_16x16x32_bf16 v[100:103], v[196:199], v[168:171], v[100:103]
	v_mfma_f32_16x16x32_bf16 v[96:99], v[204:207], v[168:171], v[96:99]
	v_mfma_f32_16x16x32_bf16 v[84:87], v[196:199], v[180:183], v[84:87]
	v_mfma_f32_16x16x32_bf16 v[80:83], v[204:207], v[180:183], v[80:83]
	v_mfma_f32_16x16x32_bf16 v[68:71], v[196:199], v[188:191], v[68:71]
	v_mfma_f32_16x16x32_bf16 v[64:67], v[204:207], v[188:191], v[64:67]
	v_mfma_f32_16x16x32_bf16 v[116:119], v[200:203], v[164:167], v[116:119]
	v_mfma_f32_16x16x32_bf16 v[112:115], v[208:211], v[164:167], v[112:115]
	v_mfma_f32_16x16x32_bf16 v[100:103], v[200:203], v[176:179], v[100:103]
	v_mfma_f32_16x16x32_bf16 v[96:99], v[208:211], v[176:179], v[96:99]
	v_mfma_f32_16x16x32_bf16 v[84:87], v[200:203], v[184:187], v[84:87]
	v_mfma_f32_16x16x32_bf16 v[80:83], v[208:211], v[184:187], v[80:83]
	v_mfma_f32_16x16x32_bf16 v[68:71], v[200:203], v[192:195], v[68:71]
	v_mfma_f32_16x16x32_bf16 v[64:67], v[208:211], v[192:195], v[64:67]
	s_setprio 0
	s_mov_b32 m0, s74
	v_lshl_add_u64 v[212:213], v[216:217], 0, s[22:23]
	s_barrier
; #define PG8_STAGE(bufoff, gbase, voff) do { _Pragma("unroll") for (int _i = 0; _i < 2; ++_i) \
;     __builtin_amdgcn_global_load_lds((const unsigned*)((const char*)(gbase) + (voff)[_i]), (LAS unsigned*)(lds + (bufoff) + ldsw + _i * 8192), 16, 0, 0); } while (0)
; #define PG8_LDA(dst, b, h) do { _Pragma("unroll") for (int m = 0; m < 4; ++m) _Pragma("unroll") for (int k = 0; k < 2; ++k) dst[m][k] = *(const LAS bf16x8*)(lds + PG8_SA(b, h) + aoff + m * 2048 + k * 1024); } while (0)
; #define PG8_MMA(ai, bj, At, Bt) do { __builtin_amdgcn_s_setprio(1); _Pragma("unroll") for (int m = 0; m < 4; ++m) _Pragma("unroll") for (int n = 0; n < 2; ++n) _Pragma("unroll") for (int k = 0; k < 2; ++k) \
;     acc[ai][bj][m][n] = __builtin_amdgcn_mfma_f32_16x16x32_bf16(Bt[n][k], At[m][k], acc[ai][bj][m][n], 0, 0, 0); __builtin_amdgcn_s_setprio(0); } while (0)
; #define PG8_WAIT_V(n) asm volatile("s_waitcnt vmcnt(" #n ")" ::: "memory")
; #define PG8_WAIT_L(n) asm volatile("s_waitcnt lgkmcnt(" #n ")" ::: "memory")
; #define PG8_BAR __builtin_amdgcn_s_barrier()
; #define PG8_SCHED __builtin_amdgcn_sched_barrier(0)
; template <class Epi>
; __device__ __forceinline__ void gemm_phase(LAS unsigned char* lds, const Gemm g, const Epi& E) {
;     ...
;       PG8_LDA(At, 1, 1); PG8_STAGE(PG8_SA(1, 0), a3, voffA);
;       PG8_BAR; PG8_WAIT_L(0); PG8_MMA(1, 0, At, B0); PG8_BAR; PG8_SCHED;
;       PG8_STAGE(PG8_SB(1, 1), b3 + hstepB, voffB);
;       PG8_WAIT_V(6); PG8_BAR; PG8_MMA(1, 1, At, B1); PG8_BAR;
;     }
;     {
; #pragma unroll
;       for (int ai = 0; ai < 2; ++ai)
; #pragma unroll
;         for (int m = 0; m < 4; ++m)
; #pragma unroll
;           for (int bj = 0; bj < 2; ++bj)
;           { E.st2(cur.w, cur.pm * BM + ai * HALF + wr * 64 + m * 16 + fr, cur.pn * BM + bj * HALF + wc * 32 + 8 * fq, acc[ai][bj][m][0], acc[ai][bj][m][1]); if (bj == 1 && (m & 1)) asm volatile("" ::: "memory"); }
	ds_read_b128 v[160:163], v175 offset:49152
	ds_read_b128 v[164:167], v175 offset:50176
	ds_read_b128 v[168:171], v175 offset:51200
	ds_read_b128 v[176:179], v175 offset:52224
	ds_read_b128 v[180:183], v175 offset:53248
	ds_read_b128 v[184:187], v175 offset:54272
	ds_read_b128 v[188:191], v175 offset:55296
	ds_read_b128 v[192:195], v175 offset:56320
	global_load_lds_dwordx4 v[212:213], off
	v_lshl_add_u64 v[212:213], v[218:219], 0, s[22:23]
	s_mov_b32 m0, s78
	s_nop 0
	global_load_lds_dwordx4 v[212:213], off
	s_barrier
	s_waitcnt lgkmcnt(0)
	s_setprio 1
	s_waitcnt lgkmcnt(0)
	v_mfma_f32_16x16x32_bf16 v[60:63], v[128:131], v[160:163], v[60:63]
	v_mfma_f32_16x16x32_bf16 v[56:59], v[152:155], v[160:163], v[56:59]
	v_mfma_f32_16x16x32_bf16 v[44:47], v[128:131], v[168:171], v[44:47]
	v_mfma_f32_16x16x32_bf16 v[40:43], v[152:155], v[168:171], v[40:43]
	v_mfma_f32_16x16x32_bf16 v[28:31], v[128:131], v[180:183], v[28:31]
	v_mfma_f32_16x16x32_bf16 v[24:27], v[152:155], v[180:183], v[24:27]
	v_mfma_f32_16x16x32_bf16 v[12:15], v[128:131], v[188:191], v[12:15]
	v_mfma_f32_16x16x32_bf16 v[8:11], v[152:155], v[188:191], v[8:11]
	v_mfma_f32_16x16x32_bf16 v[60:63], v[148:151], v[164:167], v[60:63]
	v_mfma_f32_16x16x32_bf16 v[56:59], v[156:159], v[164:167], v[56:59]
	v_mfma_f32_16x16x32_bf16 v[44:47], v[148:151], v[176:179], v[44:47]
	v_mfma_f32_16x16x32_bf16 v[40:43], v[156:159], v[176:179], v[40:43]
	v_mfma_f32_16x16x32_bf16 v[28:31], v[148:151], v[184:187], v[28:31]
	v_mfma_f32_16x16x32_bf16 v[24:27], v[156:159], v[184:187], v[24:27]
	v_mfma_f32_16x16x32_bf16 v[12:15], v[148:151], v[192:195], v[12:15]
	v_mfma_f32_16x16x32_bf16 v[8:11], v[156:159], v[192:195], v[8:11]
	s_setprio 0
	s_barrier
	s_add_i32 s26, s26, s97
	v_lshl_add_u64 v[128:129], v[220:221], 0, s[22:23]
	s_mov_b32 m0, s26
	s_nop 0
	global_load_lds_dwordx4 v[128:129], off
	v_lshl_add_u64 v[128:129], v[222:223], 0, s[22:23]
	s_add_i32 m0, s26, 0x2000
	s_nop 0
	global_load_lds_dwordx4 v[128:129], off
	s_waitcnt vmcnt(6)
	s_barrier
	s_setprio 1
	v_mfma_f32_16x16x32_bf16 v[52:55], v[196:199], v[160:163], v[52:55]
	v_mfma_f32_16x16x32_bf16 v[48:51], v[204:207], v[160:163], v[48:51]
	v_mfma_f32_16x16x32_bf16 v[36:39], v[196:199], v[168:171], v[36:39]
	v_mfma_f32_16x16x32_bf16 v[32:35], v[204:207], v[168:171], v[32:35]
	v_mfma_f32_16x16x32_bf16 v[20:23], v[196:199], v[180:183], v[20:23]
	v_mfma_f32_16x16x32_bf16 v[16:19], v[204:207], v[180:183], v[16:19]
	v_mfma_f32_16x16x32_bf16 v[4:7], v[196:199], v[188:191], v[4:7]
	v_mfma_f32_16x16x32_bf16 v[0:3], v[204:207], v[188:191], v[0:3]
	v_mfma_f32_16x16x32_bf16 v[52:55], v[200:203], v[164:167], v[52:55]
	v_mfma_f32_16x16x32_bf16 v[48:51], v[208:211], v[164:167], v[48:51]
	v_mfma_f32_16x16x32_bf16 v[36:39], v[200:203], v[176:179], v[36:39]
	v_mfma_f32_16x16x32_bf16 v[32:35], v[208:211], v[176:179], v[32:35]
	v_mfma_f32_16x16x32_bf16 v[20:23], v[200:203], v[184:187], v[20:23]
	v_mfma_f32_16x16x32_bf16 v[16:19], v[208:211], v[184:187], v[16:19]
	v_mfma_f32_16x16x32_bf16 v[4:7], v[200:203], v[192:195], v[4:7]
	v_mfma_f32_16x16x32_bf16 v[0:3], v[208:211], v[192:195], v[0:3]
	s_setprio 0
	s_add_u32 s2, s2, 0x100
	s_addc_u32 s3, s3, 0
	s_add_u32 s38, s38, 0x100
	s_addc_u32 s39, s39, 0
	s_cmp_ge_u32 s76, s72
	s_mov_b32 s26, s76
	s_barrier
	s_cbranch_scc0 .LBB0_579
	s_lshl_b32 s28, s53, 8
	v_lshl_add_u32 v150, s75, 8, v172
	s_cmp_eq_u32 s12, 0
	v_ashrrev_i32_e32 v151, 31, v150
	v_mad_i64_i32 v[164:165], s[2:3], v150, s54, 0
	v_mad_i64_i32 v[154:155], s[2:3], v150, s33, 0
	s_cselect_b32 s29, s40, s41
	v_lshlrev_b64 v[162:163], 10, v[150:151]
	v_cmp_gt_i32_e64 s[38:39], s92, v150
	v_lshlrev_b64 v[152:153], 12, v[150:151]
	v_or_b32_e32 v148, s28, v174
	s_cmp_eq_u32 s29, 3
	s_cbranch_scc1 .Lepi3
	s_cmp_eq_u32 s29, 4
	s_cbranch_scc1 .Lepi4
	s_cmp_lt_i32 s29, 4
	s_mov_b64 s[2:3], -1
	s_cbranch_scc1 .LBB0_593
	s_cmp_lt_i32 s29, 6
	s_cbranch_scc1 .LBB0_587
	s_cmp_gt_i32 s29, 6
	s_cbranch_scc0 .LBB0_584
	v_lshl_add_u64 v[128:129], s[58:59], 0, v[152:153]
	v_ashrrev_i32_e32 v149, 31, v148
	v_lshl_add_u64 v[160:161], v[148:149], 2, v[128:129]
	global_load_dwordx4 v[128:131], v[160:161], off nt
	global_load_dwordx4 v[156:159], v[160:161], off offset:16 nt
	s_mov_b64 s[2:3], 0
	s_waitcnt vmcnt(0)
	v_pk_add_f32 v[130:131], v[126:127], v[130:131]
	v_pk_add_f32 v[128:129], v[124:125], v[128:129]
	v_pk_add_f32 v[158:159], v[122:123], v[158:159]
	v_pk_add_f32 v[156:157], v[120:121], v[156:157]
	global_store_dwordx4 v[160:161], v[128:131], off nt
	global_store_dwordx4 v[160:161], v[156:159], off offset:16 nt

; template <class Epi>
; __device__ __forceinline__ void gemm_phase(LAS unsigned char* lds, const Gemm g, const Epi& E) {
;     ...
;       for (int ai = 0; ai < 2; ++ai)
; #pragma unroll
;         for (int m = 0; m < 4; ++m)
; #pragma unroll
;           for (int bj = 0; bj < 2; ++bj)
;           { E.st2(cur.w, cur.pm * BM + ai * HALF + wr * 64 + m * 16 + fr, cur.pn * BM + bj * HALF + wc * 32 + 8 * fq, acc[ai][bj][m][0], acc[ai][bj][m][1]); if (bj == 1 && (m & 1)) asm volatile("" ::: "memory"); }
.Lepi3:
	v_mul_u32_u24_e32 v176, 0x1800, v150
	v_lshl_add_u32 v176, v148, 1, v176
	v_add_u32_e32 v176, 0x800, v176
	v_lshlrev_b32_e32 v184, 11, v150
	v_lshl_add_u32 v184, v148, 1, v184
	v_add_u32_e32 v177, 0x18000, v176
	v_add_u32_e32 v185, 0x8000, v184
	v_add_u32_e32 v178, 0x30000, v176
	v_add_u32_e32 v186, 0x10000, v184
	v_add_u32_e32 v179, 0x48000, v176
	v_add_u32_e32 v187, 0x18000, v184
	v_add_u32_e32 v180, 0xc0000, v176
	v_add_u32_e32 v188, 0x40000, v184
	v_add_u32_e32 v181, 0xd8000, v176
	v_add_u32_e32 v189, 0x48000, v184
	v_add_u32_e32 v182, 0xf0000, v176
	v_add_u32_e32 v190, 0x50000, v184
	v_add_u32_e32 v183, 0x108000, v176
	v_add_u32_e32 v191, 0x58000, v184
	global_load_dwordx4 v[192:195], v176, s[64:65]
	global_load_dwordx4 v[200:203], v176, s[64:65] offset:256
	global_load_dwordx4 v[208:211], v177, s[64:65]
	global_load_dwordx4 v[216:219], v177, s[64:65] offset:256
	s_waitcnt vmcnt(3)
	v_lshlrev_b32_e32 v152, 16, v192
	v_and_b32_e32 v153, 0xffff0000, v192
	v_lshlrev_b32_e32 v154, 16, v193
	v_and_b32_e32 v155, 0xffff0000, v193
	v_lshlrev_b32_e32 v156, 16, v194
	v_and_b32_e32 v157, 0xffff0000, v194
	v_lshlrev_b32_e32 v158, 16, v195
	v_and_b32_e32 v159, 0xffff0000, v195
	v_mul_f32_e32 v152, 0xbfb8aa3b, v152
	v_mul_f32_e32 v153, 0xbfb8aa3b, v153
	v_mul_f32_e32 v154, 0xbfb8aa3b, v154
	v_mul_f32_e32 v155, 0xbfb8aa3b, v155
	v_mul_f32_e32 v156, 0xbfb8aa3b, v156
	v_mul_f32_e32 v157, 0xbfb8aa3b, v157
	v_mul_f32_e32 v158, 0xbfb8aa3b, v158
	v_mul_f32_e32 v159, 0xbfb8aa3b, v159
	v_exp_f32_e32 v152, v152
	v_exp_f32_e32 v153, v153
	v_exp_f32_e32 v154, v154
	v_exp_f32_e32 v155, v155
	v_exp_f32_e32 v156, v156
	v_exp_f32_e32 v157, v157
	v_exp_f32_e32 v158, v158
	v_exp_f32_e32 v159, v159
	v_pk_add_f32 v[152:153], v[152:153], 1.0 op_sel_hi:[1,0]
	v_pk_add_f32 v[154:155], v[154:155], 1.0 op_sel_hi:[1,0]
	v_pk_add_f32 v[156:157], v[156:157], 1.0 op_sel_hi:[1,0]
	v_pk_add_f32 v[158:159], v[158:159], 1.0 op_sel_hi:[1,0]
	v_div_scale_f32 v160, s[2:3], v152, v152, 1.0
	v_rcp_f32_e32 v161, v160
	s_nop 0
	v_fma_f32 v162, -v160, v161, 1.0
	v_fmac_f32_e32 v161, v162, v161
	v_div_scale_f32 v163, vcc, 1.0, v152, 1.0
	v_mul_f32_e32 v164, v163, v161
	v_div_scale_f32 v128, s[2:3], v153, v153, 1.0
	v_fma_f32 v162, -v160, v164, v163
	v_rcp_f32_e32 v129, v128
	v_fmac_f32_e32 v164, v162, v161
	s_nop 0
	v_fma_f32 v160, -v160, v164, v163
	v_fma_f32 v130, -v128, v129, 1.0
	v_div_fmas_f32 v160, v160, v161, v164
	v_fmac_f32_e32 v129, v130, v129
	v_div_fixup_f32 v152, v160, v152, 1.0
	v_div_scale_f32 v131, vcc, 1.0, v153, 1.0
	v_mul_f32_e32 v165, v131, v129
	v_div_scale_f32 v160, s[2:3], v154, v154, 1.0
	v_fma_f32 v130, -v128, v165, v131
	v_rcp_f32_e32 v161, v160
	v_fmac_f32_e32 v165, v130, v129
	s_nop 0
	v_fma_f32 v128, -v128, v165, v131
	v_fma_f32 v162, -v160, v161, 1.0
	v_div_fmas_f32 v128, v128, v129, v165
	v_fmac_f32_e32 v161, v162, v161
	v_div_fixup_f32 v153, v128, v153, 1.0
	v_div_scale_f32 v163, vcc, 1.0, v154, 1.0
	v_mul_f32_e32 v164, v163, v161
	v_div_scale_f32 v128, s[2:3], v155, v155, 1.0
	v_fma_f32 v162, -v160, v164, v163
	v_rcp_f32_e32 v129, v128
	v_fmac_f32_e32 v164, v162, v161
	s_nop 0
	v_fma_f32 v160, -v160, v164, v163
	v_fma_f32 v130, -v128, v129, 1.0
	v_div_fmas_f32 v160, v160, v161, v164
	v_fmac_f32_e32 v129, v130, v129
	v_div_fixup_f32 v154, v160, v154, 1.0
	v_div_scale_f32 v131, vcc, 1.0, v155, 1.0
	v_mul_f32_e32 v165, v131, v129
	v_div_scale_f32 v160, s[2:3], v156, v156, 1.0
	v_fma_f32 v130, -v128, v165, v131
	v_rcp_f32_e32 v161, v160
	v_fmac_f32_e32 v165, v130, v129
	s_nop 0
	v_fma_f32 v128, -v128, v165, v131
	v_fma_f32 v162, -v160, v161, 1.0
	v_div_fmas_f32 v128, v128, v129, v165
	v_fmac_f32_e32 v161, v162, v161
	v_div_fixup_f32 v155, v128, v155, 1.0
	v_div_scale_f32 v163, vcc, 1.0, v156, 1.0
	v_mul_f32_e32 v164, v163, v161
	v_div_scale_f32 v128, s[2:3], v157, v157, 1.0
	v_fma_f32 v162, -v160, v164, v163
	v_rcp_f32_e32 v129, v128
	v_fmac_f32_e32 v164, v162, v161
	s_nop 0
	v_fma_f32 v160, -v160, v164, v163
	v_fma_f32 v130, -v128, v129, 1.0
	v_div_fmas_f32 v160, v160, v161, v164
	v_fmac_f32_e32 v129, v130, v129
	v_div_fixup_f32 v156, v160, v156, 1.0
	v_div_scale_f32 v131, vcc, 1.0, v157, 1.0
	v_mul_f32_e32 v165, v131, v129
	v_div_scale_f32 v160, s[2:3], v158, v158, 1.0
	v_fma_f32 v130, -v128, v165, v131
	v_rcp_f32_e32 v161, v160
	v_fmac_f32_e32 v165, v130, v129
	s_nop 0
	v_fma_f32 v128, -v128, v165, v131
	v_fma_f32 v162, -v160, v161, 1.0
	v_div_fmas_f32 v128, v128, v129, v165
	v_fmac_f32_e32 v161, v162, v161
	v_div_fixup_f32 v157, v128, v157, 1.0
	v_div_scale_f32 v163, vcc, 1.0, v158, 1.0
	v_mul_f32_e32 v164, v163, v161
	v_div_scale_f32 v128, s[2:3], v159, v159, 1.0
	v_fma_f32 v162, -v160, v164, v163
	v_rcp_f32_e32 v129, v128
	v_fmac_f32_e32 v164, v162, v161
	s_nop 0
	v_fma_f32 v160, -v160, v164, v163
	v_fma_f32 v130, -v128, v129, 1.0
	v_div_fmas_f32 v160, v160, v161, v164
	v_fmac_f32_e32 v129, v130, v129
	v_div_fixup_f32 v158, v160, v158, 1.0
	v_div_scale_f32 v131, vcc, 1.0, v159, 1.0
	v_mul_f32_e32 v165, v131, v129
	v_fma_f32 v130, -v128, v165, v131
	v_fmac_f32_e32 v165, v130, v129
	v_fma_f32 v128, -v128, v165, v131
	v_div_fmas_f32 v128, v128, v129, v165
	v_div_fixup_f32 v159, v128, v159, 1.0
	v_pk_mul_f32 v[152:153], v[124:125], v[152:153]
	v_pk_mul_f32 v[154:155], v[126:127], v[154:155]
	v_pk_mul_f32 v[156:157], v[120:121], v[156:157]
	v_pk_mul_f32 v[158:159], v[122:123], v[158:159]
	v_cvt_pk_bf16_f32 v168, v152, v153
	v_cvt_pk_bf16_f32 v169, v154, v155
	v_cvt_pk_bf16_f32 v170, v156, v157
	v_cvt_pk_bf16_f32 v171, v158, v159
	global_store_dwordx4 v184, v[168:171], s[68:69]
	global_load_dwordx4 v[124:127], v178, s[64:65]
	s_waitcnt vmcnt(4)
	v_lshlrev_b32_e32 v152, 16, v200
	v_and_b32_e32 v153, 0xffff0000, v200
	v_lshlrev_b32_e32 v154, 16, v201
	v_and_b32_e32 v155, 0xffff0000, v201
	v_lshlrev_b32_e32 v156, 16, v202
	v_and_b32_e32 v157, 0xffff0000, v202
	v_lshlrev_b32_e32 v158, 16, v203
	v_and_b32_e32 v159, 0xffff0000, v203
	v_mul_f32_e32 v152, 0xbfb8aa3b, v152
	v_mul_f32_e32 v153, 0xbfb8aa3b, v153
	v_mul_f32_e32 v154, 0xbfb8aa3b, v154
	v_mul_f32_e32 v155, 0xbfb8aa3b, v155
	v_mul_f32_e32 v156, 0xbfb8aa3b, v156
	v_mul_f32_e32 v157, 0xbfb8aa3b, v157
	v_mul_f32_e32 v158, 0xbfb8aa3b, v158
	v_mul_f32_e32 v159, 0xbfb8aa3b, v159
	v_exp_f32_e32 v152, v152
	v_exp_f32_e32 v153, v153
	v_exp_f32_e32 v154, v154
	v_exp_f32_e32 v155, v155
	v_exp_f32_e32 v156, v156
	v_exp_f32_e32 v157, v157
	v_exp_f32_e32 v158, v158
	v_exp_f32_e32 v159, v159
	v_pk_add_f32 v[152:153], v[152:153], 1.0 op_sel_hi:[1,0]
	v_pk_add_f32 v[154:155], v[154:155], 1.0 op_sel_hi:[1,0]
	v_pk_add_f32 v[156:157], v[156:157], 1.0 op_sel_hi:[1,0]
	v_pk_add_f32 v[158:159], v[158:159], 1.0 op_sel_hi:[1,0]
	v_div_scale_f32 v160, s[2:3], v152, v152, 1.0
	v_rcp_f32_e32 v161, v160
	s_nop 0
	v_fma_f32 v162, -v160, v161, 1.0
	v_fmac_f32_e32 v161, v162, v161
	v_div_scale_f32 v163, vcc, 1.0, v152, 1.0
	v_mul_f32_e32 v164, v163, v161
	v_div_scale_f32 v128, s[2:3], v153, v153, 1.0
	v_fma_f32 v162, -v160, v164, v163
	v_rcp_f32_e32 v129, v128
	v_fmac_f32_e32 v164, v162, v161
	s_nop 0
	v_fma_f32 v160, -v160, v164, v163
	v_fma_f32 v130, -v128, v129, 1.0
	v_div_fmas_f32 v160, v160, v161, v164
	v_fmac_f32_e32 v129, v130, v129
	v_div_fixup_f32 v152, v160, v152, 1.0
	v_div_scale_f32 v131, vcc, 1.0, v153, 1.0
	v_mul_f32_e32 v165, v131, v129
	v_div_scale_f32 v160, s[2:3], v154, v154, 1.0
	v_fma_f32 v130, -v128, v165, v131
	v_rcp_f32_e32 v161, v160
	v_fmac_f32_e32 v165, v130, v129
	s_nop 0
	v_fma_f32 v128, -v128, v165, v131
	v_fma_f32 v162, -v160, v161, 1.0
	v_div_fmas_f32 v128, v128, v129, v165
	v_fmac_f32_e32 v161, v162, v161
	v_div_fixup_f32 v153, v128, v153, 1.0
	v_div_scale_f32 v163, vcc, 1.0, v154, 1.0
	v_mul_f32_e32 v164, v163, v161
	v_div_scale_f32 v128, s[2:3], v155, v155, 1.0
	v_fma_f32 v162, -v160, v164, v163
	v_rcp_f32_e32 v129, v128
	v_fmac_f32_e32 v164, v162, v161
	s_nop 0
	v_fma_f32 v160, -v160, v164, v163
	v_fma_f32 v130, -v128, v129, 1.0
	v_div_fmas_f32 v160, v160, v161, v164
	v_fmac_f32_e32 v129, v130, v129
	v_div_fixup_f32 v154, v160, v154, 1.0
	v_div_scale_f32 v131, vcc, 1.0, v155, 1.0
	v_mul_f32_e32 v165, v131, v129
	v_div_scale_f32 v160, s[2:3], v156, v156, 1.0
	v_fma_f32 v130, -v128, v165, v131
	v_rcp_f32_e32 v161, v160
	v_fmac_f32_e32 v165, v130, v129
	s_nop 0
	v_fma_f32 v128, -v128, v165, v131
	v_fma_f32 v162, -v160, v161, 1.0
	v_div_fmas_f32 v128, v128, v129, v165
	v_fmac_f32_e32 v161, v162, v161
	v_div_fixup_f32 v155, v128, v155, 1.0
	v_div_scale_f32 v163, vcc, 1.0, v156, 1.0
	v_mul_f32_e32 v164, v163, v161
	v_div_scale_f32 v128, s[2:3], v157, v157, 1.0
	v_fma_f32 v162, -v160, v164, v163
	v_rcp_f32_e32 v129, v128
	v_fmac_f32_e32 v164, v162, v161
	s_nop 0
	v_fma_f32 v160, -v160, v164, v163
	v_fma_f32 v130, -v128, v129, 1.0
	v_div_fmas_f32 v160, v160, v161, v164
	v_fmac_f32_e32 v129, v130, v129
	v_div_fixup_f32 v156, v160, v156, 1.0
	v_div_scale_f32 v131, vcc, 1.0, v157, 1.0
	v_mul_f32_e32 v165, v131, v129
	v_div_scale_f32 v160, s[2:3], v158, v158, 1.0
	v_fma_f32 v130, -v128, v165, v131
	v_rcp_f32_e32 v161, v160
	v_fmac_f32_e32 v165, v130, v129
	s_nop 0
	v_fma_f32 v128, -v128, v165, v131
	v_fma_f32 v162, -v160, v161, 1.0
	v_div_fmas_f32 v128, v128, v129, v165
	v_fmac_f32_e32 v161, v162, v161
	v_div_fixup_f32 v157, v128, v157, 1.0
	v_div_scale_f32 v163, vcc, 1.0, v158, 1.0
	v_mul_f32_e32 v164, v163, v161
	v_div_scale_f32 v128, s[2:3], v159, v159, 1.0
	v_fma_f32 v162, -v160, v164, v163
	v_rcp_f32_e32 v129, v128
	v_fmac_f32_e32 v164, v162, v161
	s_nop 0
	v_fma_f32 v160, -v160, v164, v163
	v_fma_f32 v130, -v128, v129, 1.0
	v_div_fmas_f32 v160, v160, v161, v164
	v_fmac_f32_e32 v129, v130, v129
	v_div_fixup_f32 v158, v160, v158, 1.0
	v_div_scale_f32 v131, vcc, 1.0, v159, 1.0
	v_mul_f32_e32 v165, v131, v129
	v_fma_f32 v130, -v128, v165, v131
	v_fmac_f32_e32 v165, v130, v129
	v_fma_f32 v128, -v128, v165, v131
	v_div_fmas_f32 v128, v128, v129, v165
	v_div_fixup_f32 v159, v128, v159, 1.0
	v_pk_mul_f32 v[152:153], v[116:117], v[152:153]
	v_pk_mul_f32 v[154:155], v[118:119], v[154:155]
	v_pk_mul_f32 v[156:157], v[112:113], v[156:157]
	v_pk_mul_f32 v[158:159], v[114:115], v[158:159]
	v_cvt_pk_bf16_f32 v168, v152, v153
	v_cvt_pk_bf16_f32 v169, v154, v155
	v_cvt_pk_bf16_f32 v170, v156, v157
	v_cvt_pk_bf16_f32 v171, v158, v159
	global_store_dwordx4 v184, v[168:171], s[68:69] offset:256
	global_load_dwordx4 v[116:119], v178, s[64:65] offset:256
	s_waitcnt vmcnt(5)
	v_lshlrev_b32_e32 v152, 16, v208
	v_and_b32_e32 v153, 0xffff0000, v208
	v_lshlrev_b32_e32 v154, 16, v209
	v_and_b32_e32 v155, 0xffff0000, v209
	v_lshlrev_b32_e32 v156, 16, v210
	v_and_b32_e32 v157, 0xffff0000, v210
	v_lshlrev_b32_e32 v158, 16, v211
	v_and_b32_e32 v159, 0xffff0000, v211
	v_mul_f32_e32 v152, 0xbfb8aa3b, v152
	v_mul_f32_e32 v153, 0xbfb8aa3b, v153
	v_mul_f32_e32 v154, 0xbfb8aa3b, v154
	v_mul_f32_e32 v155, 0xbfb8aa3b, v155
	v_mul_f32_e32 v156, 0xbfb8aa3b, v156
	v_mul_f32_e32 v157, 0xbfb8aa3b, v157
	v_mul_f32_e32 v158, 0xbfb8aa3b, v158
	v_mul_f32_e32 v159, 0xbfb8aa3b, v159
	v_exp_f32_e32 v152, v152
	v_exp_f32_e32 v153, v153
	v_exp_f32_e32 v154, v154
	v_exp_f32_e32 v155, v155
	v_exp_f32_e32 v156, v156
	v_exp_f32_e32 v157, v157
	v_exp_f32_e32 v158, v158
	v_exp_f32_e32 v159, v159
	v_pk_add_f32 v[152:153], v[152:153], 1.0 op_sel_hi:[1,0]
	v_pk_add_f32 v[154:155], v[154:155], 1.0 op_sel_hi:[1,0]
	v_pk_add_f32 v[156:157], v[156:157], 1.0 op_sel_hi:[1,0]
	v_pk_add_f32 v[158:159], v[158:159], 1.0 op_sel_hi:[1,0]
	v_div_scale_f32 v160, s[2:3], v152, v152, 1.0
	v_rcp_f32_e32 v161, v160
	s_nop 0
	v_fma_f32 v162, -v160, v161, 1.0
	v_fmac_f32_e32 v161, v162, v161
	v_div_scale_f32 v163, vcc, 1.0, v152, 1.0
	v_mul_f32_e32 v164, v163, v161
	v_div_scale_f32 v128, s[2:3], v153, v153, 1.0
	v_fma_f32 v162, -v160, v164, v163
	v_rcp_f32_e32 v129, v128
	v_fmac_f32_e32 v164, v162, v161
	s_nop 0
	v_fma_f32 v160, -v160, v164, v163
	v_fma_f32 v130, -v128, v129, 1.0
	v_div_fmas_f32 v160, v160, v161, v164
	v_fmac_f32_e32 v129, v130, v129
	v_div_fixup_f32 v152, v160, v152, 1.0
	v_div_scale_f32 v131, vcc, 1.0, v153, 1.0
	v_mul_f32_e32 v165, v131, v129
	v_div_scale_f32 v160, s[2:3], v154, v154, 1.0
	v_fma_f32 v130, -v128, v165, v131
	v_rcp_f32_e32 v161, v160
	v_fmac_f32_e32 v165, v130, v129
	s_nop 0
	v_fma_f32 v128, -v128, v165, v131
	v_fma_f32 v162, -v160, v161, 1.0
	v_div_fmas_f32 v128, v128, v129, v165
	v_fmac_f32_e32 v161, v162, v161
	v_div_fixup_f32 v153, v128, v153, 1.0
	v_div_scale_f32 v163, vcc, 1.0, v154, 1.0
	v_mul_f32_e32 v164, v163, v161
	v_div_scale_f32 v128, s[2:3], v155, v155, 1.0
	v_fma_f32 v162, -v160, v164, v163
	v_rcp_f32_e32 v129, v128
	v_fmac_f32_e32 v164, v162, v161
	s_nop 0
	v_fma_f32 v160, -v160, v164, v163
	v_fma_f32 v130, -v128, v129, 1.0
	v_div_fmas_f32 v160, v160, v161, v164
	v_fmac_f32_e32 v129, v130, v129
	v_div_fixup_f32 v154, v160, v154, 1.0
	v_div_scale_f32 v131, vcc, 1.0, v155, 1.0
	v_mul_f32_e32 v165, v131, v129
	v_div_scale_f32 v160, s[2:3], v156, v156, 1.0
	v_fma_f32 v130, -v128, v165, v131
	v_rcp_f32_e32 v161, v160
	v_fmac_f32_e32 v165, v130, v129
	s_nop 0
	v_fma_f32 v128, -v128, v165, v131
	v_fma_f32 v162, -v160, v161, 1.0
	v_div_fmas_f32 v128, v128, v129, v165
	v_fmac_f32_e32 v161, v162, v161
	v_div_fixup_f32 v155, v128, v155, 1.0
	v_div_scale_f32 v163, vcc, 1.0, v156, 1.0
	v_mul_f32_e32 v164, v163, v161
	v_div_scale_f32 v128, s[2:3], v157, v157, 1.0
	v_fma_f32 v162, -v160, v164, v163
	v_rcp_f32_e32 v129, v128
	v_fmac_f32_e32 v164, v162, v161
	s_nop 0
	v_fma_f32 v160, -v160, v164, v163
	v_fma_f32 v130, -v128, v129, 1.0
	v_div_fmas_f32 v160, v160, v161, v164
	v_fmac_f32_e32 v129, v130, v129
	v_div_fixup_f32 v156, v160, v156, 1.0
	v_div_scale_f32 v131, vcc, 1.0, v157, 1.0
	v_mul_f32_e32 v165, v131, v129
	v_div_scale_f32 v160, s[2:3], v158, v158, 1.0
	v_fma_f32 v130, -v128, v165, v131
	v_rcp_f32_e32 v161, v160
	v_fmac_f32_e32 v165, v130, v129
	s_nop 0
	v_fma_f32 v128, -v128, v165, v131
	v_fma_f32 v162, -v160, v161, 1.0
	v_div_fmas_f32 v128, v128, v129, v165
	v_fmac_f32_e32 v161, v162, v161
	v_div_fixup_f32 v157, v128, v157, 1.0
	v_div_scale_f32 v163, vcc, 1.0, v158, 1.0
	v_mul_f32_e32 v164, v163, v161
	v_div_scale_f32 v128, s[2:3], v159, v159, 1.0
	v_fma_f32 v162, -v160, v164, v163
	v_rcp_f32_e32 v129, v128
	v_fmac_f32_e32 v164, v162, v161
	s_nop 0
	v_fma_f32 v160, -v160, v164, v163
	v_fma_f32 v130, -v128, v129, 1.0
	v_div_fmas_f32 v160, v160, v161, v164
	v_fmac_f32_e32 v129, v130, v129
	v_div_fixup_f32 v158, v160, v158, 1.0
	v_div_scale_f32 v131, vcc, 1.0, v159, 1.0
	v_mul_f32_e32 v165, v131, v129
	v_fma_f32 v130, -v128, v165, v131
	v_fmac_f32_e32 v165, v130, v129
	v_fma_f32 v128, -v128, v165, v131
	v_div_fmas_f32 v128, v128, v129, v165
	v_div_fixup_f32 v159, v128, v159, 1.0
	v_pk_mul_f32 v[152:153], v[108:109], v[152:153]
	v_pk_mul_f32 v[154:155], v[110:111], v[154:155]
	v_pk_mul_f32 v[156:157], v[104:105], v[156:157]
	v_pk_mul_f32 v[158:159], v[106:107], v[158:159]
	v_cvt_pk_bf16_f32 v168, v152, v153
	v_cvt_pk_bf16_f32 v169, v154, v155
	v_cvt_pk_bf16_f32 v170, v156, v157
	v_cvt_pk_bf16_f32 v171, v158, v159
	global_store_dwordx4 v185, v[168:171], s[68:69]
	global_load_dwordx4 v[108:111], v179, s[64:65]
	s_waitcnt vmcnt(6)
	v_lshlrev_b32_e32 v152, 16, v216
	v_and_b32_e32 v153, 0xffff0000, v216
	v_lshlrev_b32_e32 v154, 16, v217
	v_and_b32_e32 v155, 0xffff0000, v217
	v_lshlrev_b32_e32 v156, 16, v218
	v_and_b32_e32 v157, 0xffff0000, v218
	v_lshlrev_b32_e32 v158, 16, v219
	v_and_b32_e32 v159, 0xffff0000, v219
	v_mul_f32_e32 v152, 0xbfb8aa3b, v152
	v_mul_f32_e32 v153, 0xbfb8aa3b, v153
	v_mul_f32_e32 v154, 0xbfb8aa3b, v154
	v_mul_f32_e32 v155, 0xbfb8aa3b, v155
	v_mul_f32_e32 v156, 0xbfb8aa3b, v156
	v_mul_f32_e32 v157, 0xbfb8aa3b, v157
	v_mul_f32_e32 v158, 0xbfb8aa3b, v158
	v_mul_f32_e32 v159, 0xbfb8aa3b, v159
	v_exp_f32_e32 v152, v152
	v_exp_f32_e32 v153, v153
	v_exp_f32_e32 v154, v154
	v_exp_f32_e32 v155, v155
	v_exp_f32_e32 v156, v156
	v_exp_f32_e32 v157, v157
	v_exp_f32_e32 v158, v158
	v_exp_f32_e32 v159, v159
	v_pk_add_f32 v[152:153], v[152:153], 1.0 op_sel_hi:[1,0]
	v_pk_add_f32 v[154:155], v[154:155], 1.0 op_sel_hi:[1,0]
	v_pk_add_f32 v[156:157], v[156:157], 1.0 op_sel_hi:[1,0]
	v_pk_add_f32 v[158:159], v[158:159], 1.0 op_sel_hi:[1,0]
	v_div_scale_f32 v160, s[2:3], v152, v152, 1.0
	v_rcp_f32_e32 v161, v160
	s_nop 0
	v_fma_f32 v162, -v160, v161, 1.0
	v_fmac_f32_e32 v161, v162, v161
	v_div_scale_f32 v163, vcc, 1.0, v152, 1.0
	v_mul_f32_e32 v164, v163, v161
	v_div_scale_f32 v128, s[2:3], v153, v153, 1.0
	v_fma_f32 v162, -v160, v164, v163
	v_rcp_f32_e32 v129, v128
	v_fmac_f32_e32 v164, v162, v161
	s_nop 0
	v_fma_f32 v160, -v160, v164, v163
	v_fma_f32 v130, -v128, v129, 1.0
	v_div_fmas_f32 v160, v160, v161, v164
	v_fmac_f32_e32 v129, v130, v129
	v_div_fixup_f32 v152, v160, v152, 1.0
	v_div_scale_f32 v131, vcc, 1.0, v153, 1.0
	v_mul_f32_e32 v165, v131, v129
	v_div_scale_f32 v160, s[2:3], v154, v154, 1.0
	v_fma_f32 v130, -v128, v165, v131
	v_rcp_f32_e32 v161, v160
	v_fmac_f32_e32 v165, v130, v129
	s_nop 0
	v_fma_f32 v128, -v128, v165, v131
	v_fma_f32 v162, -v160, v161, 1.0
	v_div_fmas_f32 v128, v128, v129, v165
	v_fmac_f32_e32 v161, v162, v161
	v_div_fixup_f32 v153, v128, v153, 1.0
	v_div_scale_f32 v163, vcc, 1.0, v154, 1.0
	v_mul_f32_e32 v164, v163, v161
	v_div_scale_f32 v128, s[2:3], v155, v155, 1.0
	v_fma_f32 v162, -v160, v164, v163
	v_rcp_f32_e32 v129, v128
	v_fmac_f32_e32 v164, v162, v161
	s_nop 0
	v_fma_f32 v160, -v160, v164, v163
	v_fma_f32 v130, -v128, v129, 1.0
	v_div_fmas_f32 v160, v160, v161, v164
	v_fmac_f32_e32 v129, v130, v129
	v_div_fixup_f32 v154, v160, v154, 1.0
	v_div_scale_f32 v131, vcc, 1.0, v155, 1.0
	v_mul_f32_e32 v165, v131, v129
	v_div_scale_f32 v160, s[2:3], v156, v156, 1.0
	v_fma_f32 v130, -v128, v165, v131
	v_rcp_f32_e32 v161, v160
	v_fmac_f32_e32 v165, v130, v129
	s_nop 0
	v_fma_f32 v128, -v128, v165, v131
	v_fma_f32 v162, -v160, v161, 1.0
	v_div_fmas_f32 v128, v128, v129, v165
	v_fmac_f32_e32 v161, v162, v161
	v_div_fixup_f32 v155, v128, v155, 1.0
	v_div_scale_f32 v163, vcc, 1.0, v156, 1.0
	v_mul_f32_e32 v164, v163, v161
	v_div_scale_f32 v128, s[2:3], v157, v157, 1.0
	v_fma_f32 v162, -v160, v164, v163
	v_rcp_f32_e32 v129, v128
	v_fmac_f32_e32 v164, v162, v161
	s_nop 0
	v_fma_f32 v160, -v160, v164, v163
	v_fma_f32 v130, -v128, v129, 1.0
	v_div_fmas_f32 v160, v160, v161, v164
	v_fmac_f32_e32 v129, v130, v129
	v_div_fixup_f32 v156, v160, v156, 1.0
	v_div_scale_f32 v131, vcc, 1.0, v157, 1.0
	v_mul_f32_e32 v165, v131, v129
	v_div_scale_f32 v160, s[2:3], v158, v158, 1.0
	v_fma_f32 v130, -v128, v165, v131
	v_rcp_f32_e32 v161, v160
	v_fmac_f32_e32 v165, v130, v129
	s_nop 0
	v_fma_f32 v128, -v128, v165, v131
	v_fma_f32 v162, -v160, v161, 1.0
	v_div_fmas_f32 v128, v128, v129, v165
	v_fmac_f32_e32 v161, v162, v161
	v_div_fixup_f32 v157, v128, v157, 1.0
	v_div_scale_f32 v163, vcc, 1.0, v158, 1.0
	v_mul_f32_e32 v164, v163, v161
	v_div_scale_f32 v128, s[2:3], v159, v159, 1.0
	v_fma_f32 v162, -v160, v164, v163
	v_rcp_f32_e32 v129, v128
	v_fmac_f32_e32 v164, v162, v161
	s_nop 0
	v_fma_f32 v160, -v160, v164, v163
	v_fma_f32 v130, -v128, v129, 1.0
	v_div_fmas_f32 v160, v160, v161, v164
	v_fmac_f32_e32 v129, v130, v129
	v_div_fixup_f32 v158, v160, v158, 1.0
	v_div_scale_f32 v131, vcc, 1.0, v159, 1.0
	v_mul_f32_e32 v165, v131, v129
	v_fma_f32 v130, -v128, v165, v131
	v_fmac_f32_e32 v165, v130, v129
	v_fma_f32 v128, -v128, v165, v131
	v_div_fmas_f32 v128, v128, v129, v165
	v_div_fixup_f32 v159, v128, v159, 1.0
	v_pk_mul_f32 v[152:153], v[100:101], v[152:153]
	v_pk_mul_f32 v[154:155], v[102:103], v[154:155]
	v_pk_mul_f32 v[156:157], v[96:97], v[156:157]
	v_pk_mul_f32 v[158:159], v[98:99], v[158:159]
	v_cvt_pk_bf16_f32 v168, v152, v153
	v_cvt_pk_bf16_f32 v169, v154, v155
	v_cvt_pk_bf16_f32 v170, v156, v157
	v_cvt_pk_bf16_f32 v171, v158, v159
	global_store_dwordx4 v185, v[168:171], s[68:69] offset:256
	global_load_dwordx4 v[100:103], v179, s[64:65] offset:256
	s_waitcnt vmcnt(6)
	v_lshlrev_b32_e32 v152, 16, v124
	v_and_b32_e32 v153, 0xffff0000, v124
	v_lshlrev_b32_e32 v154, 16, v125
	v_and_b32_e32 v155, 0xffff0000, v125
	v_lshlrev_b32_e32 v156, 16, v126
	v_and_b32_e32 v157, 0xffff0000, v126
	v_lshlrev_b32_e32 v158, 16, v127
	v_and_b32_e32 v159, 0xffff0000, v127
	v_mul_f32_e32 v152, 0xbfb8aa3b, v152
	v_mul_f32_e32 v153, 0xbfb8aa3b, v153
	v_mul_f32_e32 v154, 0xbfb8aa3b, v154
	v_mul_f32_e32 v155, 0xbfb8aa3b, v155
	v_mul_f32_e32 v156, 0xbfb8aa3b, v156
	v_mul_f32_e32 v157, 0xbfb8aa3b, v157
	v_mul_f32_e32 v158, 0xbfb8aa3b, v158
	v_mul_f32_e32 v159, 0xbfb8aa3b, v159
	v_exp_f32_e32 v152, v152
	v_exp_f32_e32 v153, v153
	v_exp_f32_e32 v154, v154
	v_exp_f32_e32 v155, v155
	v_exp_f32_e32 v156, v156
	v_exp_f32_e32 v157, v157
	v_exp_f32_e32 v158, v158
	v_exp_f32_e32 v159, v159
	v_pk_add_f32 v[152:153], v[152:153], 1.0 op_sel_hi:[1,0]
	v_pk_add_f32 v[154:155], v[154:155], 1.0 op_sel_hi:[1,0]
	v_pk_add_f32 v[156:157], v[156:157], 1.0 op_sel_hi:[1,0]
	v_pk_add_f32 v[158:159], v[158:159], 1.0 op_sel_hi:[1,0]
	v_div_scale_f32 v160, s[2:3], v152, v152, 1.0
	v_rcp_f32_e32 v161, v160
	s_nop 0
	v_fma_f32 v162, -v160, v161, 1.0
	v_fmac_f32_e32 v161, v162, v161
	v_div_scale_f32 v163, vcc, 1.0, v152, 1.0
	v_mul_f32_e32 v164, v163, v161
	v_div_scale_f32 v128, s[2:3], v153, v153, 1.0
	v_fma_f32 v162, -v160, v164, v163
	v_rcp_f32_e32 v129, v128
	v_fmac_f32_e32 v164, v162, v161
	s_nop 0
	v_fma_f32 v160, -v160, v164, v163
	v_fma_f32 v130, -v128, v129, 1.0
	v_div_fmas_f32 v160, v160, v161, v164
	v_fmac_f32_e32 v129, v130, v129
	v_div_fixup_f32 v152, v160, v152, 1.0
	v_div_scale_f32 v131, vcc, 1.0, v153, 1.0
	v_mul_f32_e32 v165, v131, v129
	v_div_scale_f32 v160, s[2:3], v154, v154, 1.0
	v_fma_f32 v130, -v128, v165, v131
	v_rcp_f32_e32 v161, v160
	v_fmac_f32_e32 v165, v130, v129
	s_nop 0
	v_fma_f32 v128, -v128, v165, v131
	v_fma_f32 v162, -v160, v161, 1.0
	v_div_fmas_f32 v128, v128, v129, v165
	v_fmac_f32_e32 v161, v162, v161
	v_div_fixup_f32 v153, v128, v153, 1.0
	v_div_scale_f32 v163, vcc, 1.0, v154, 1.0
	v_mul_f32_e32 v164, v163, v161
	v_div_scale_f32 v128, s[2:3], v155, v155, 1.0
	v_fma_f32 v162, -v160, v164, v163
	v_rcp_f32_e32 v129, v128
	v_fmac_f32_e32 v164, v162, v161
	s_nop 0
	v_fma_f32 v160, -v160, v164, v163
	v_fma_f32 v130, -v128, v129, 1.0
	v_div_fmas_f32 v160, v160, v161, v164
	v_fmac_f32_e32 v129, v130, v129
	v_div_fixup_f32 v154, v160, v154, 1.0
	v_div_scale_f32 v131, vcc, 1.0, v155, 1.0
	v_mul_f32_e32 v165, v131, v129
	v_div_scale_f32 v160, s[2:3], v156, v156, 1.0
	v_fma_f32 v130, -v128, v165, v131
	v_rcp_f32_e32 v161, v160
	v_fmac_f32_e32 v165, v130, v129
	s_nop 0
	v_fma_f32 v128, -v128, v165, v131
	v_fma_f32 v162, -v160, v161, 1.0
	v_div_fmas_f32 v128, v128, v129, v165
	v_fmac_f32_e32 v161, v162, v161
	v_div_fixup_f32 v155, v128, v155, 1.0
	v_div_scale_f32 v163, vcc, 1.0, v156, 1.0
	v_mul_f32_e32 v164, v163, v161
	v_div_scale_f32 v128, s[2:3], v157, v157, 1.0
	v_fma_f32 v162, -v160, v164, v163
	v_rcp_f32_e32 v129, v128
	v_fmac_f32_e32 v164, v162, v161
	s_nop 0
	v_fma_f32 v160, -v160, v164, v163
	v_fma_f32 v130, -v128, v129, 1.0
	v_div_fmas_f32 v160, v160, v161, v164
	v_fmac_f32_e32 v129, v130, v129
	v_div_fixup_f32 v156, v160, v156, 1.0
	v_div_scale_f32 v131, vcc, 1.0, v157, 1.0
	v_mul_f32_e32 v165, v131, v129
	v_div_scale_f32 v160, s[2:3], v158, v158, 1.0
	v_fma_f32 v130, -v128, v165, v131
	v_rcp_f32_e32 v161, v160
	v_fmac_f32_e32 v165, v130, v129
	s_nop 0
	v_fma_f32 v128, -v128, v165, v131
	v_fma_f32 v162, -v160, v161, 1.0
	v_div_fmas_f32 v128, v128, v129, v165
	v_fmac_f32_e32 v161, v162, v161
	v_div_fixup_f32 v157, v128, v157, 1.0
	v_div_scale_f32 v163, vcc, 1.0, v158, 1.0
	v_mul_f32_e32 v164, v163, v161
	v_div_scale_f32 v128, s[2:3], v159, v159, 1.0
	v_fma_f32 v162, -v160, v164, v163
	v_rcp_f32_e32 v129, v128
	v_fmac_f32_e32 v164, v162, v161
	s_nop 0
	v_fma_f32 v160, -v160, v164, v163
	v_fma_f32 v130, -v128, v129, 1.0
	v_div_fmas_f32 v160, v160, v161, v164
	v_fmac_f32_e32 v129, v130, v129
	v_div_fixup_f32 v158, v160, v158, 1.0
	v_div_scale_f32 v131, vcc, 1.0, v159, 1.0
	v_mul_f32_e32 v165, v131, v129
	v_fma_f32 v130, -v128, v165, v131
	v_fmac_f32_e32 v165, v130, v129
	v_fma_f32 v128, -v128, v165, v131
	v_div_fmas_f32 v128, v128, v129, v165
	v_div_fixup_f32 v159, v128, v159, 1.0
	v_pk_mul_f32 v[152:153], v[92:93], v[152:153]
	v_pk_mul_f32 v[154:155], v[94:95], v[154:155]
	v_pk_mul_f32 v[156:157], v[88:89], v[156:157]
	v_pk_mul_f32 v[158:159], v[90:91], v[158:159]
	v_cvt_pk_bf16_f32 v168, v152, v153
	v_cvt_pk_bf16_f32 v169, v154, v155
	v_cvt_pk_bf16_f32 v170, v156, v157
	v_cvt_pk_bf16_f32 v171, v158, v159
	global_store_dwordx4 v186, v[168:171], s[68:69]
	global_load_dwordx4 v[92:95], v180, s[64:65]
	s_waitcnt vmcnt(6)
	v_lshlrev_b32_e32 v152, 16, v116
	v_and_b32_e32 v153, 0xffff0000, v116
	v_lshlrev_b32_e32 v154, 16, v117
	v_and_b32_e32 v155, 0xffff0000, v117
	v_lshlrev_b32_e32 v156, 16, v118
	v_and_b32_e32 v157, 0xffff0000, v118
	v_lshlrev_b32_e32 v158, 16, v119
	v_and_b32_e32 v159, 0xffff0000, v119
	v_mul_f32_e32 v152, 0xbfb8aa3b, v152
	v_mul_f32_e32 v153, 0xbfb8aa3b, v153
	v_mul_f32_e32 v154, 0xbfb8aa3b, v154
	v_mul_f32_e32 v155, 0xbfb8aa3b, v155
	v_mul_f32_e32 v156, 0xbfb8aa3b, v156
	v_mul_f32_e32 v157, 0xbfb8aa3b, v157
	v_mul_f32_e32 v158, 0xbfb8aa3b, v158
	v_mul_f32_e32 v159, 0xbfb8aa3b, v159
	v_exp_f32_e32 v152, v152
	v_exp_f32_e32 v153, v153
	v_exp_f32_e32 v154, v154
	v_exp_f32_e32 v155, v155
	v_exp_f32_e32 v156, v156
	v_exp_f32_e32 v157, v157
	v_exp_f32_e32 v158, v158
	v_exp_f32_e32 v159, v159
	v_pk_add_f32 v[152:153], v[152:153], 1.0 op_sel_hi:[1,0]
	v_pk_add_f32 v[154:155], v[154:155], 1.0 op_sel_hi:[1,0]
	v_pk_add_f32 v[156:157], v[156:157], 1.0 op_sel_hi:[1,0]
	v_pk_add_f32 v[158:159], v[158:159], 1.0 op_sel_hi:[1,0]
	v_div_scale_f32 v160, s[2:3], v152, v152, 1.0
	v_rcp_f32_e32 v161, v160
	s_nop 0
	v_fma_f32 v162, -v160, v161, 1.0
	v_fmac_f32_e32 v161, v162, v161
	v_div_scale_f32 v163, vcc, 1.0, v152, 1.0
	v_mul_f32_e32 v164, v163, v161
	v_div_scale_f32 v128, s[2:3], v153, v153, 1.0
	v_fma_f32 v162, -v160, v164, v163
	v_rcp_f32_e32 v129, v128
	v_fmac_f32_e32 v164, v162, v161
	s_nop 0
	v_fma_f32 v160, -v160, v164, v163
	v_fma_f32 v130, -v128, v129, 1.0
	v_div_fmas_f32 v160, v160, v161, v164
	v_fmac_f32_e32 v129, v130, v129
	v_div_fixup_f32 v152, v160, v152, 1.0
	v_div_scale_f32 v131, vcc, 1.0, v153, 1.0
	v_mul_f32_e32 v165, v131, v129
	v_div_scale_f32 v160, s[2:3], v154, v154, 1.0
	v_fma_f32 v130, -v128, v165, v131
	v_rcp_f32_e32 v161, v160
	v_fmac_f32_e32 v165, v130, v129
	s_nop 0
	v_fma_f32 v128, -v128, v165, v131
	v_fma_f32 v162, -v160, v161, 1.0
	v_div_fmas_f32 v128, v128, v129, v165
	v_fmac_f32_e32 v161, v162, v161
	v_div_fixup_f32 v153, v128, v153, 1.0
	v_div_scale_f32 v163, vcc, 1.0, v154, 1.0
	v_mul_f32_e32 v164, v163, v161
	v_div_scale_f32 v128, s[2:3], v155, v155, 1.0
	v_fma_f32 v162, -v160, v164, v163
	v_rcp_f32_e32 v129, v128
	v_fmac_f32_e32 v164, v162, v161
	s_nop 0
	v_fma_f32 v160, -v160, v164, v163
	v_fma_f32 v130, -v128, v129, 1.0
	v_div_fmas_f32 v160, v160, v161, v164
	v_fmac_f32_e32 v129, v130, v129
	v_div_fixup_f32 v154, v160, v154, 1.0
	v_div_scale_f32 v131, vcc, 1.0, v155, 1.0
	v_mul_f32_e32 v165, v131, v129
	v_div_scale_f32 v160, s[2:3], v156, v156, 1.0
	v_fma_f32 v130, -v128, v165, v131
	v_rcp_f32_e32 v161, v160
	v_fmac_f32_e32 v165, v130, v129
	s_nop 0
	v_fma_f32 v128, -v128, v165, v131
	v_fma_f32 v162, -v160, v161, 1.0
	v_div_fmas_f32 v128, v128, v129, v165
	v_fmac_f32_e32 v161, v162, v161
	v_div_fixup_f32 v155, v128, v155, 1.0
	v_div_scale_f32 v163, vcc, 1.0, v156, 1.0
	v_mul_f32_e32 v164, v163, v161
	v_div_scale_f32 v128, s[2:3], v157, v157, 1.0
	v_fma_f32 v162, -v160, v164, v163
	v_rcp_f32_e32 v129, v128
	v_fmac_f32_e32 v164, v162, v161
	s_nop 0
	v_fma_f32 v160, -v160, v164, v163
	v_fma_f32 v130, -v128, v129, 1.0
	v_div_fmas_f32 v160, v160, v161, v164
	v_fmac_f32_e32 v129, v130, v129
	v_div_fixup_f32 v156, v160, v156, 1.0
	v_div_scale_f32 v131, vcc, 1.0, v157, 1.0
	v_mul_f32_e32 v165, v131, v129
	v_div_scale_f32 v160, s[2:3], v158, v158, 1.0
	v_fma_f32 v130, -v128, v165, v131
	v_rcp_f32_e32 v161, v160
	v_fmac_f32_e32 v165, v130, v129
	s_nop 0
	v_fma_f32 v128, -v128, v165, v131
	v_fma_f32 v162, -v160, v161, 1.0
	v_div_fmas_f32 v128, v128, v129, v165
	v_fmac_f32_e32 v161, v162, v161
	v_div_fixup_f32 v157, v128, v157, 1.0
	v_div_scale_f32 v163, vcc, 1.0, v158, 1.0
	v_mul_f32_e32 v164, v163, v161
	v_div_scale_f32 v128, s[2:3], v159, v159, 1.0
	v_fma_f32 v162, -v160, v164, v163
	v_rcp_f32_e32 v129, v128
	v_fmac_f32_e32 v164, v162, v161
	s_nop 0
	v_fma_f32 v160, -v160, v164, v163
	v_fma_f32 v130, -v128, v129, 1.0
	v_div_fmas_f32 v160, v160, v161, v164
	v_fmac_f32_e32 v129, v130, v129
	v_div_fixup_f32 v158, v160, v158, 1.0
	v_div_scale_f32 v131, vcc, 1.0, v159, 1.0
	v_mul_f32_e32 v165, v131, v129
	v_fma_f32 v130, -v128, v165, v131
	v_fmac_f32_e32 v165, v130, v129
	v_fma_f32 v128, -v128, v165, v131
	v_div_fmas_f32 v128, v128, v129, v165
	v_div_fixup_f32 v159, v128, v159, 1.0
	v_pk_mul_f32 v[152:153], v[84:85], v[152:153]
	v_pk_mul_f32 v[154:155], v[86:87], v[154:155]
	v_pk_mul_f32 v[156:157], v[80:81], v[156:157]
	v_pk_mul_f32 v[158:159], v[82:83], v[158:159]
	v_cvt_pk_bf16_f32 v168, v152, v153
	v_cvt_pk_bf16_f32 v169, v154, v155
	v_cvt_pk_bf16_f32 v170, v156, v157
	v_cvt_pk_bf16_f32 v171, v158, v159
	global_store_dwordx4 v186, v[168:171], s[68:69] offset:256
	global_load_dwordx4 v[84:87], v180, s[64:65] offset:256
	s_waitcnt vmcnt(6)
; __device__ __forceinline__ float sigmoidf_(float x) { return 1.f / (1.f + __expf(-x)); }
	v_lshlrev_b32_e32 v152, 16, v108
	v_and_b32_e32 v153, 0xffff0000, v108
	v_lshlrev_b32_e32 v154, 16, v109
	v_and_b32_e32 v155, 0xffff0000, v109
	v_lshlrev_b32_e32 v156, 16, v110
	v_and_b32_e32 v157, 0xffff0000, v110
	v_lshlrev_b32_e32 v158, 16, v111
	v_and_b32_e32 v159, 0xffff0000, v111
	v_mul_f32_e32 v152, 0xbfb8aa3b, v152
	v_mul_f32_e32 v153, 0xbfb8aa3b, v153
	v_mul_f32_e32 v154, 0xbfb8aa3b, v154
	v_mul_f32_e32 v155, 0xbfb8aa3b, v155
	v_mul_f32_e32 v156, 0xbfb8aa3b, v156
	v_mul_f32_e32 v157, 0xbfb8aa3b, v157
	v_mul_f32_e32 v158, 0xbfb8aa3b, v158
	v_mul_f32_e32 v159, 0xbfb8aa3b, v159
	v_exp_f32_e32 v152, v152
	v_exp_f32_e32 v153, v153
	v_exp_f32_e32 v154, v154
	v_exp_f32_e32 v155, v155
	v_exp_f32_e32 v156, v156
	v_exp_f32_e32 v157, v157
	v_exp_f32_e32 v158, v158
	v_exp_f32_e32 v159, v159
	v_pk_add_f32 v[152:153], v[152:153], 1.0 op_sel_hi:[1,0]
	v_pk_add_f32 v[154:155], v[154:155], 1.0 op_sel_hi:[1,0]
	v_pk_add_f32 v[156:157], v[156:157], 1.0 op_sel_hi:[1,0]
	v_pk_add_f32 v[158:159], v[158:159], 1.0 op_sel_hi:[1,0]
	v_div_scale_f32 v160, s[2:3], v152, v152, 1.0
	v_rcp_f32_e32 v161, v160
	s_nop 0
	v_fma_f32 v162, -v160, v161, 1.0
	v_fmac_f32_e32 v161, v162, v161
	v_div_scale_f32 v163, vcc, 1.0, v152, 1.0
	v_mul_f32_e32 v164, v163, v161
	v_div_scale_f32 v128, s[2:3], v153, v153, 1.0
	v_fma_f32 v162, -v160, v164, v163
	v_rcp_f32_e32 v129, v128
	v_fmac_f32_e32 v164, v162, v161
	s_nop 0
	v_fma_f32 v160, -v160, v164, v163
	v_fma_f32 v130, -v128, v129, 1.0
	v_div_fmas_f32 v160, v160, v161, v164
	v_fmac_f32_e32 v129, v130, v129
	v_div_fixup_f32 v152, v160, v152, 1.0
	v_div_scale_f32 v131, vcc, 1.0, v153, 1.0
	v_mul_f32_e32 v165, v131, v129
	v_div_scale_f32 v160, s[2:3], v154, v154, 1.0
	v_fma_f32 v130, -v128, v165, v131
	v_rcp_f32_e32 v161, v160
	v_fmac_f32_e32 v165, v130, v129
	s_nop 0
	v_fma_f32 v128, -v128, v165, v131
	v_fma_f32 v162, -v160, v161, 1.0
	v_div_fmas_f32 v128, v128, v129, v165
	v_fmac_f32_e32 v161, v162, v161
	v_div_fixup_f32 v153, v128, v153, 1.0
	v_div_scale_f32 v163, vcc, 1.0, v154, 1.0
	v_mul_f32_e32 v164, v163, v161
	v_div_scale_f32 v128, s[2:3], v155, v155, 1.0
	v_fma_f32 v162, -v160, v164, v163
	v_rcp_f32_e32 v129, v128
	v_fmac_f32_e32 v164, v162, v161
	s_nop 0
	v_fma_f32 v160, -v160, v164, v163
	v_fma_f32 v130, -v128, v129, 1.0
	v_div_fmas_f32 v160, v160, v161, v164
	v_fmac_f32_e32 v129, v130, v129
	v_div_fixup_f32 v154, v160, v154, 1.0
	v_div_scale_f32 v131, vcc, 1.0, v155, 1.0
	v_mul_f32_e32 v165, v131, v129
	v_div_scale_f32 v160, s[2:3], v156, v156, 1.0
	v_fma_f32 v130, -v128, v165, v131
	v_rcp_f32_e32 v161, v160
	v_fmac_f32_e32 v165, v130, v129
	s_nop 0
	v_fma_f32 v128, -v128, v165, v131
	v_fma_f32 v162, -v160, v161, 1.0
	v_div_fmas_f32 v128, v128, v129, v165
	v_fmac_f32_e32 v161, v162, v161
	v_div_fixup_f32 v155, v128, v155, 1.0
	v_div_scale_f32 v163, vcc, 1.0, v156, 1.0
	v_mul_f32_e32 v164, v163, v161
	v_div_scale_f32 v128, s[2:3], v157, v157, 1.0
	v_fma_f32 v162, -v160, v164, v163
	v_rcp_f32_e32 v129, v128
	v_fmac_f32_e32 v164, v162, v161
	s_nop 0
	v_fma_f32 v160, -v160, v164, v163
	v_fma_f32 v130, -v128, v129, 1.0
	v_div_fmas_f32 v160, v160, v161, v164
	v_fmac_f32_e32 v129, v130, v129
	v_div_fixup_f32 v156, v160, v156, 1.0
	v_div_scale_f32 v131, vcc, 1.0, v157, 1.0
	v_mul_f32_e32 v165, v131, v129
	v_div_scale_f32 v160, s[2:3], v158, v158, 1.0
	v_fma_f32 v130, -v128, v165, v131
	v_rcp_f32_e32 v161, v160
	v_fmac_f32_e32 v165, v130, v129
	s_nop 0
	v_fma_f32 v128, -v128, v165, v131
	v_fma_f32 v162, -v160, v161, 1.0
	v_div_fmas_f32 v128, v128, v129, v165
	v_fmac_f32_e32 v161, v162, v161
	v_div_fixup_f32 v157, v128, v157, 1.0
	v_div_scale_f32 v163, vcc, 1.0, v158, 1.0
	v_mul_f32_e32 v164, v163, v161
	v_div_scale_f32 v128, s[2:3], v159, v159, 1.0
	v_fma_f32 v162, -v160, v164, v163
	v_rcp_f32_e32 v129, v128
	v_fmac_f32_e32 v164, v162, v161
	s_nop 0
	v_fma_f32 v160, -v160, v164, v163
	v_fma_f32 v130, -v128, v129, 1.0
	v_div_fmas_f32 v160, v160, v161, v164
	v_fmac_f32_e32 v129, v130, v129
	v_div_fixup_f32 v158, v160, v158, 1.0
	v_div_scale_f32 v131, vcc, 1.0, v159, 1.0
	v_mul_f32_e32 v165, v131, v129
	v_fma_f32 v130, -v128, v165, v131
	v_fmac_f32_e32 v165, v130, v129
	v_fma_f32 v128, -v128, v165, v131
	v_div_fmas_f32 v128, v128, v129, v165
	v_div_fixup_f32 v159, v128, v159, 1.0
	v_pk_mul_f32 v[152:153], v[76:77], v[152:153]
	v_pk_mul_f32 v[154:155], v[78:79], v[154:155]
	v_pk_mul_f32 v[156:157], v[72:73], v[156:157]
	v_pk_mul_f32 v[158:159], v[74:75], v[158:159]
	v_cvt_pk_bf16_f32 v168, v152, v153
	v_cvt_pk_bf16_f32 v169, v154, v155
	v_cvt_pk_bf16_f32 v170, v156, v157
	v_cvt_pk_bf16_f32 v171, v158, v159
	global_store_dwordx4 v187, v[168:171], s[68:69]
	global_load_dwordx4 v[76:79], v181, s[64:65]
	s_waitcnt vmcnt(6)
; __device__ __forceinline__ float sigmoidf_(float x) { return 1.f / (1.f + __expf(-x)); }
	v_lshlrev_b32_e32 v152, 16, v100
	v_and_b32_e32 v153, 0xffff0000, v100
	v_lshlrev_b32_e32 v154, 16, v101
	v_and_b32_e32 v155, 0xffff0000, v101
	v_lshlrev_b32_e32 v156, 16, v102
	v_and_b32_e32 v157, 0xffff0000, v102
	v_lshlrev_b32_e32 v158, 16, v103
	v_and_b32_e32 v159, 0xffff0000, v103
	v_mul_f32_e32 v152, 0xbfb8aa3b, v152
	v_mul_f32_e32 v153, 0xbfb8aa3b, v153
	v_mul_f32_e32 v154, 0xbfb8aa3b, v154
	v_mul_f32_e32 v155, 0xbfb8aa3b, v155
	v_mul_f32_e32 v156, 0xbfb8aa3b, v156
	v_mul_f32_e32 v157, 0xbfb8aa3b, v157
	v_mul_f32_e32 v158, 0xbfb8aa3b, v158
	v_mul_f32_e32 v159, 0xbfb8aa3b, v159
	v_exp_f32_e32 v152, v152
	v_exp_f32_e32 v153, v153
	v_exp_f32_e32 v154, v154
	v_exp_f32_e32 v155, v155
	v_exp_f32_e32 v156, v156
	v_exp_f32_e32 v157, v157
	v_exp_f32_e32 v158, v158
	v_exp_f32_e32 v159, v159
	v_pk_add_f32 v[152:153], v[152:153], 1.0 op_sel_hi:[1,0]
	v_pk_add_f32 v[154:155], v[154:155], 1.0 op_sel_hi:[1,0]
	v_pk_add_f32 v[156:157], v[156:157], 1.0 op_sel_hi:[1,0]
	v_pk_add_f32 v[158:159], v[158:159], 1.0 op_sel_hi:[1,0]
	v_div_scale_f32 v160, s[2:3], v152, v152, 1.0
	v_rcp_f32_e32 v161, v160
	s_nop 0
	v_fma_f32 v162, -v160, v161, 1.0
	v_fmac_f32_e32 v161, v162, v161
	v_div_scale_f32 v163, vcc, 1.0, v152, 1.0
	v_mul_f32_e32 v164, v163, v161
	v_div_scale_f32 v128, s[2:3], v153, v153, 1.0
	v_fma_f32 v162, -v160, v164, v163
	v_rcp_f32_e32 v129, v128
	v_fmac_f32_e32 v164, v162, v161
	s_nop 0
	v_fma_f32 v160, -v160, v164, v163
	v_fma_f32 v130, -v128, v129, 1.0
	v_div_fmas_f32 v160, v160, v161, v164
	v_fmac_f32_e32 v129, v130, v129
	v_div_fixup_f32 v152, v160, v152, 1.0
	v_div_scale_f32 v131, vcc, 1.0, v153, 1.0
	v_mul_f32_e32 v165, v131, v129
	v_div_scale_f32 v160, s[2:3], v154, v154, 1.0
	v_fma_f32 v130, -v128, v165, v131
	v_rcp_f32_e32 v161, v160
	v_fmac_f32_e32 v165, v130, v129
	s_nop 0
	v_fma_f32 v128, -v128, v165, v131
	v_fma_f32 v162, -v160, v161, 1.0
	v_div_fmas_f32 v128, v128, v129, v165
	v_fmac_f32_e32 v161, v162, v161
	v_div_fixup_f32 v153, v128, v153, 1.0
	v_div_scale_f32 v163, vcc, 1.0, v154, 1.0
	v_mul_f32_e32 v164, v163, v161
	v_div_scale_f32 v128, s[2:3], v155, v155, 1.0
	v_fma_f32 v162, -v160, v164, v163
	v_rcp_f32_e32 v129, v128
	v_fmac_f32_e32 v164, v162, v161
	s_nop 0
	v_fma_f32 v160, -v160, v164, v163
	v_fma_f32 v130, -v128, v129, 1.0
	v_div_fmas_f32 v160, v160, v161, v164
	v_fmac_f32_e32 v129, v130, v129
	v_div_fixup_f32 v154, v160, v154, 1.0
	v_div_scale_f32 v131, vcc, 1.0, v155, 1.0
	v_mul_f32_e32 v165, v131, v129
	v_div_scale_f32 v160, s[2:3], v156, v156, 1.0
	v_fma_f32 v130, -v128, v165, v131
	v_rcp_f32_e32 v161, v160
	v_fmac_f32_e32 v165, v130, v129
	s_nop 0
	v_fma_f32 v128, -v128, v165, v131
	v_fma_f32 v162, -v160, v161, 1.0
	v_div_fmas_f32 v128, v128, v129, v165
	v_fmac_f32_e32 v161, v162, v161
	v_div_fixup_f32 v155, v128, v155, 1.0
	v_div_scale_f32 v163, vcc, 1.0, v156, 1.0
	v_mul_f32_e32 v164, v163, v161
	v_div_scale_f32 v128, s[2:3], v157, v157, 1.0
	v_fma_f32 v162, -v160, v164, v163
	v_rcp_f32_e32 v129, v128
	v_fmac_f32_e32 v164, v162, v161
	s_nop 0
	v_fma_f32 v160, -v160, v164, v163
	v_fma_f32 v130, -v128, v129, 1.0
	v_div_fmas_f32 v160, v160, v161, v164
	v_fmac_f32_e32 v129, v130, v129
	v_div_fixup_f32 v156, v160, v156, 1.0
	v_div_scale_f32 v131, vcc, 1.0, v157, 1.0
	v_mul_f32_e32 v165, v131, v129
	v_div_scale_f32 v160, s[2:3], v158, v158, 1.0
	v_fma_f32 v130, -v128, v165, v131
	v_rcp_f32_e32 v161, v160
	v_fmac_f32_e32 v165, v130, v129
	s_nop 0
	v_fma_f32 v128, -v128, v165, v131
	v_fma_f32 v162, -v160, v161, 1.0
	v_div_fmas_f32 v128, v128, v129, v165
	v_fmac_f32_e32 v161, v162, v161
	v_div_fixup_f32 v157, v128, v157, 1.0
	v_div_scale_f32 v163, vcc, 1.0, v158, 1.0
	v_mul_f32_e32 v164, v163, v161
	v_div_scale_f32 v128, s[2:3], v159, v159, 1.0
	v_fma_f32 v162, -v160, v164, v163
	v_rcp_f32_e32 v129, v128
	v_fmac_f32_e32 v164, v162, v161
	s_nop 0
	v_fma_f32 v160, -v160, v164, v163
	v_fma_f32 v130, -v128, v129, 1.0
	v_div_fmas_f32 v160, v160, v161, v164
	v_fmac_f32_e32 v129, v130, v129
	v_div_fixup_f32 v158, v160, v158, 1.0
	v_div_scale_f32 v131, vcc, 1.0, v159, 1.0
	v_mul_f32_e32 v165, v131, v129
	v_fma_f32 v130, -v128, v165, v131
	v_fmac_f32_e32 v165, v130, v129
	v_fma_f32 v128, -v128, v165, v131
	v_div_fmas_f32 v128, v128, v129, v165
	v_div_fixup_f32 v159, v128, v159, 1.0
	v_pk_mul_f32 v[152:153], v[68:69], v[152:153]
	v_pk_mul_f32 v[154:155], v[70:71], v[154:155]
	v_pk_mul_f32 v[156:157], v[64:65], v[156:157]
	v_pk_mul_f32 v[158:159], v[66:67], v[158:159]
	v_cvt_pk_bf16_f32 v168, v152, v153
	v_cvt_pk_bf16_f32 v169, v154, v155
	v_cvt_pk_bf16_f32 v170, v156, v157
	v_cvt_pk_bf16_f32 v171, v158, v159
	global_store_dwordx4 v187, v[168:171], s[68:69] offset:256
	global_load_dwordx4 v[68:71], v181, s[64:65] offset:256
	s_waitcnt vmcnt(6)
; __device__ __forceinline__ float sigmoidf_(float x) { return 1.f / (1.f + __expf(-x)); }
	v_lshlrev_b32_e32 v152, 16, v92
	v_and_b32_e32 v153, 0xffff0000, v92
	v_lshlrev_b32_e32 v154, 16, v93
	v_and_b32_e32 v155, 0xffff0000, v93
	v_lshlrev_b32_e32 v156, 16, v94
	v_and_b32_e32 v157, 0xffff0000, v94
	v_lshlrev_b32_e32 v158, 16, v95
	v_and_b32_e32 v159, 0xffff0000, v95
	v_mul_f32_e32 v152, 0xbfb8aa3b, v152
	v_mul_f32_e32 v153, 0xbfb8aa3b, v153
	v_mul_f32_e32 v154, 0xbfb8aa3b, v154
	v_mul_f32_e32 v155, 0xbfb8aa3b, v155
	v_mul_f32_e32 v156, 0xbfb8aa3b, v156
	v_mul_f32_e32 v157, 0xbfb8aa3b, v157
	v_mul_f32_e32 v158, 0xbfb8aa3b, v158
	v_mul_f32_e32 v159, 0xbfb8aa3b, v159
	v_exp_f32_e32 v152, v152
	v_exp_f32_e32 v153, v153
	v_exp_f32_e32 v154, v154
	v_exp_f32_e32 v155, v155
	v_exp_f32_e32 v156, v156
	v_exp_f32_e32 v157, v157
	v_exp_f32_e32 v158, v158
	v_exp_f32_e32 v159, v159
	v_pk_add_f32 v[152:153], v[152:153], 1.0 op_sel_hi:[1,0]
	v_pk_add_f32 v[154:155], v[154:155], 1.0 op_sel_hi:[1,0]
	v_pk_add_f32 v[156:157], v[156:157], 1.0 op_sel_hi:[1,0]
	v_pk_add_f32 v[158:159], v[158:159], 1.0 op_sel_hi:[1,0]
	v_div_scale_f32 v160, s[2:3], v152, v152, 1.0
	v_rcp_f32_e32 v161, v160
	s_nop 0
	v_fma_f32 v162, -v160, v161, 1.0
	v_fmac_f32_e32 v161, v162, v161
	v_div_scale_f32 v163, vcc, 1.0, v152, 1.0
	v_mul_f32_e32 v164, v163, v161
	v_div_scale_f32 v128, s[2:3], v153, v153, 1.0
	v_fma_f32 v162, -v160, v164, v163
	v_rcp_f32_e32 v129, v128
	v_fmac_f32_e32 v164, v162, v161
	s_nop 0
	v_fma_f32 v160, -v160, v164, v163
	v_fma_f32 v130, -v128, v129, 1.0
	v_div_fmas_f32 v160, v160, v161, v164
	v_fmac_f32_e32 v129, v130, v129
	v_div_fixup_f32 v152, v160, v152, 1.0
	v_div_scale_f32 v131, vcc, 1.0, v153, 1.0
	v_mul_f32_e32 v165, v131, v129
	v_div_scale_f32 v160, s[2:3], v154, v154, 1.0
	v_fma_f32 v130, -v128, v165, v131
	v_rcp_f32_e32 v161, v160
	v_fmac_f32_e32 v165, v130, v129
	s_nop 0
	v_fma_f32 v128, -v128, v165, v131
	v_fma_f32 v162, -v160, v161, 1.0
	v_div_fmas_f32 v128, v128, v129, v165
	v_fmac_f32_e32 v161, v162, v161
	v_div_fixup_f32 v153, v128, v153, 1.0
	v_div_scale_f32 v163, vcc, 1.0, v154, 1.0
	v_mul_f32_e32 v164, v163, v161
	v_div_scale_f32 v128, s[2:3], v155, v155, 1.0
	v_fma_f32 v162, -v160, v164, v163
	v_rcp_f32_e32 v129, v128
	v_fmac_f32_e32 v164, v162, v161
	s_nop 0
	v_fma_f32 v160, -v160, v164, v163
	v_fma_f32 v130, -v128, v129, 1.0
	v_div_fmas_f32 v160, v160, v161, v164
	v_fmac_f32_e32 v129, v130, v129
	v_div_fixup_f32 v154, v160, v154, 1.0
	v_div_scale_f32 v131, vcc, 1.0, v155, 1.0
	v_mul_f32_e32 v165, v131, v129
	v_div_scale_f32 v160, s[2:3], v156, v156, 1.0
	v_fma_f32 v130, -v128, v165, v131
	v_rcp_f32_e32 v161, v160
	v_fmac_f32_e32 v165, v130, v129
	s_nop 0
	v_fma_f32 v128, -v128, v165, v131
	v_fma_f32 v162, -v160, v161, 1.0
	v_div_fmas_f32 v128, v128, v129, v165
	v_fmac_f32_e32 v161, v162, v161
	v_div_fixup_f32 v155, v128, v155, 1.0
	v_div_scale_f32 v163, vcc, 1.0, v156, 1.0
	v_mul_f32_e32 v164, v163, v161
	v_div_scale_f32 v128, s[2:3], v157, v157, 1.0
	v_fma_f32 v162, -v160, v164, v163
	v_rcp_f32_e32 v129, v128
	v_fmac_f32_e32 v164, v162, v161
	s_nop 0
	v_fma_f32 v160, -v160, v164, v163
	v_fma_f32 v130, -v128, v129, 1.0
	v_div_fmas_f32 v160, v160, v161, v164
	v_fmac_f32_e32 v129, v130, v129
	v_div_fixup_f32 v156, v160, v156, 1.0
	v_div_scale_f32 v131, vcc, 1.0, v157, 1.0
	v_mul_f32_e32 v165, v131, v129
	v_div_scale_f32 v160, s[2:3], v158, v158, 1.0
	v_fma_f32 v130, -v128, v165, v131
	v_rcp_f32_e32 v161, v160
	v_fmac_f32_e32 v165, v130, v129
	s_nop 0
	v_fma_f32 v128, -v128, v165, v131
	v_fma_f32 v162, -v160, v161, 1.0
	v_div_fmas_f32 v128, v128, v129, v165
	v_fmac_f32_e32 v161, v162, v161
	v_div_fixup_f32 v157, v128, v157, 1.0
	v_div_scale_f32 v163, vcc, 1.0, v158, 1.0
	v_mul_f32_e32 v164, v163, v161
	v_div_scale_f32 v128, s[2:3], v159, v159, 1.0
	v_fma_f32 v162, -v160, v164, v163
	v_rcp_f32_e32 v129, v128
	v_fmac_f32_e32 v164, v162, v161
	s_nop 0
	v_fma_f32 v160, -v160, v164, v163
	v_fma_f32 v130, -v128, v129, 1.0
	v_div_fmas_f32 v160, v160, v161, v164
	v_fmac_f32_e32 v129, v130, v129
	v_div_fixup_f32 v158, v160, v158, 1.0
	v_div_scale_f32 v131, vcc, 1.0, v159, 1.0
	v_mul_f32_e32 v165, v131, v129
	v_fma_f32 v130, -v128, v165, v131
	v_fmac_f32_e32 v165, v130, v129
	v_fma_f32 v128, -v128, v165, v131
	v_div_fmas_f32 v128, v128, v129, v165
	v_div_fixup_f32 v159, v128, v159, 1.0
	v_pk_mul_f32 v[152:153], v[60:61], v[152:153]
	v_pk_mul_f32 v[154:155], v[62:63], v[154:155]
	v_pk_mul_f32 v[156:157], v[56:57], v[156:157]
	v_pk_mul_f32 v[158:159], v[58:59], v[158:159]
	v_cvt_pk_bf16_f32 v168, v152, v153
	v_cvt_pk_bf16_f32 v169, v154, v155
	v_cvt_pk_bf16_f32 v170, v156, v157
	v_cvt_pk_bf16_f32 v171, v158, v159
	global_store_dwordx4 v188, v[168:171], s[68:69]
	global_load_dwordx4 v[60:63], v182, s[64:65]
	s_waitcnt vmcnt(6)
; __device__ __forceinline__ float sigmoidf_(float x) { return 1.f / (1.f + __expf(-x)); }
	v_lshlrev_b32_e32 v152, 16, v84
	v_and_b32_e32 v153, 0xffff0000, v84
	v_lshlrev_b32_e32 v154, 16, v85
	v_and_b32_e32 v155, 0xffff0000, v85
	v_lshlrev_b32_e32 v156, 16, v86
	v_and_b32_e32 v157, 0xffff0000, v86
	v_lshlrev_b32_e32 v158, 16, v87
	v_and_b32_e32 v159, 0xffff0000, v87
	v_mul_f32_e32 v152, 0xbfb8aa3b, v152
	v_mul_f32_e32 v153, 0xbfb8aa3b, v153
	v_mul_f32_e32 v154, 0xbfb8aa3b, v154
	v_mul_f32_e32 v155, 0xbfb8aa3b, v155
	v_mul_f32_e32 v156, 0xbfb8aa3b, v156
	v_mul_f32_e32 v157, 0xbfb8aa3b, v157
	v_mul_f32_e32 v158, 0xbfb8aa3b, v158
	v_mul_f32_e32 v159, 0xbfb8aa3b, v159
	v_exp_f32_e32 v152, v152
	v_exp_f32_e32 v153, v153
	v_exp_f32_e32 v154, v154
	v_exp_f32_e32 v155, v155
	v_exp_f32_e32 v156, v156
	v_exp_f32_e32 v157, v157
	v_exp_f32_e32 v158, v158
	v_exp_f32_e32 v159, v159
	v_pk_add_f32 v[152:153], v[152:153], 1.0 op_sel_hi:[1,0]
	v_pk_add_f32 v[154:155], v[154:155], 1.0 op_sel_hi:[1,0]
	v_pk_add_f32 v[156:157], v[156:157], 1.0 op_sel_hi:[1,0]
	v_pk_add_f32 v[158:159], v[158:159], 1.0 op_sel_hi:[1,0]
	v_div_scale_f32 v160, s[2:3], v152, v152, 1.0
	v_rcp_f32_e32 v161, v160
	s_nop 0
	v_fma_f32 v162, -v160, v161, 1.0
	v_fmac_f32_e32 v161, v162, v161
	v_div_scale_f32 v163, vcc, 1.0, v152, 1.0
	v_mul_f32_e32 v164, v163, v161
	v_div_scale_f32 v128, s[2:3], v153, v153, 1.0
	v_fma_f32 v162, -v160, v164, v163
	v_rcp_f32_e32 v129, v128
	v_fmac_f32_e32 v164, v162, v161
	s_nop 0
	v_fma_f32 v160, -v160, v164, v163
	v_fma_f32 v130, -v128, v129, 1.0
	v_div_fmas_f32 v160, v160, v161, v164
	v_fmac_f32_e32 v129, v130, v129
	v_div_fixup_f32 v152, v160, v152, 1.0
	v_div_scale_f32 v131, vcc, 1.0, v153, 1.0
	v_mul_f32_e32 v165, v131, v129
	v_div_scale_f32 v160, s[2:3], v154, v154, 1.0
	v_fma_f32 v130, -v128, v165, v131
	v_rcp_f32_e32 v161, v160
	v_fmac_f32_e32 v165, v130, v129
	s_nop 0
	v_fma_f32 v128, -v128, v165, v131
	v_fma_f32 v162, -v160, v161, 1.0
	v_div_fmas_f32 v128, v128, v129, v165
	v_fmac_f32_e32 v161, v162, v161
	v_div_fixup_f32 v153, v128, v153, 1.0
	v_div_scale_f32 v163, vcc, 1.0, v154, 1.0
	v_mul_f32_e32 v164, v163, v161
	v_div_scale_f32 v128, s[2:3], v155, v155, 1.0
	v_fma_f32 v162, -v160, v164, v163
	v_rcp_f32_e32 v129, v128
	v_fmac_f32_e32 v164, v162, v161
	s_nop 0
	v_fma_f32 v160, -v160, v164, v163
	v_fma_f32 v130, -v128, v129, 1.0
	v_div_fmas_f32 v160, v160, v161, v164
	v_fmac_f32_e32 v129, v130, v129
	v_div_fixup_f32 v154, v160, v154, 1.0
	v_div_scale_f32 v131, vcc, 1.0, v155, 1.0
	v_mul_f32_e32 v165, v131, v129
	v_div_scale_f32 v160, s[2:3], v156, v156, 1.0
	v_fma_f32 v130, -v128, v165, v131
	v_rcp_f32_e32 v161, v160
	v_fmac_f32_e32 v165, v130, v129
	s_nop 0
	v_fma_f32 v128, -v128, v165, v131
	v_fma_f32 v162, -v160, v161, 1.0
	v_div_fmas_f32 v128, v128, v129, v165
	v_fmac_f32_e32 v161, v162, v161
	v_div_fixup_f32 v155, v128, v155, 1.0
	v_div_scale_f32 v163, vcc, 1.0, v156, 1.0
	v_mul_f32_e32 v164, v163, v161
	v_div_scale_f32 v128, s[2:3], v157, v157, 1.0
	v_fma_f32 v162, -v160, v164, v163
	v_rcp_f32_e32 v129, v128
	v_fmac_f32_e32 v164, v162, v161
	s_nop 0
	v_fma_f32 v160, -v160, v164, v163
	v_fma_f32 v130, -v128, v129, 1.0
	v_div_fmas_f32 v160, v160, v161, v164
	v_fmac_f32_e32 v129, v130, v129
	v_div_fixup_f32 v156, v160, v156, 1.0
	v_div_scale_f32 v131, vcc, 1.0, v157, 1.0
	v_mul_f32_e32 v165, v131, v129
	v_div_scale_f32 v160, s[2:3], v158, v158, 1.0
	v_fma_f32 v130, -v128, v165, v131
	v_rcp_f32_e32 v161, v160
	v_fmac_f32_e32 v165, v130, v129
	s_nop 0
	v_fma_f32 v128, -v128, v165, v131
	v_fma_f32 v162, -v160, v161, 1.0
	v_div_fmas_f32 v128, v128, v129, v165
	v_fmac_f32_e32 v161, v162, v161
	v_div_fixup_f32 v157, v128, v157, 1.0
	v_div_scale_f32 v163, vcc, 1.0, v158, 1.0
	v_mul_f32_e32 v164, v163, v161
	v_div_scale_f32 v128, s[2:3], v159, v159, 1.0
	v_fma_f32 v162, -v160, v164, v163
	v_rcp_f32_e32 v129, v128
	v_fmac_f32_e32 v164, v162, v161
	s_nop 0
	v_fma_f32 v160, -v160, v164, v163
	v_fma_f32 v130, -v128, v129, 1.0
	v_div_fmas_f32 v160, v160, v161, v164
	v_fmac_f32_e32 v129, v130, v129
	v_div_fixup_f32 v158, v160, v158, 1.0
	v_div_scale_f32 v131, vcc, 1.0, v159, 1.0
	v_mul_f32_e32 v165, v131, v129
	v_fma_f32 v130, -v128, v165, v131
	v_fmac_f32_e32 v165, v130, v129
	v_fma_f32 v128, -v128, v165, v131
	v_div_fmas_f32 v128, v128, v129, v165
	v_div_fixup_f32 v159, v128, v159, 1.0
	v_pk_mul_f32 v[152:153], v[52:53], v[152:153]
	v_pk_mul_f32 v[154:155], v[54:55], v[154:155]
	v_pk_mul_f32 v[156:157], v[48:49], v[156:157]
	v_pk_mul_f32 v[158:159], v[50:51], v[158:159]
	v_cvt_pk_bf16_f32 v168, v152, v153
	v_cvt_pk_bf16_f32 v169, v154, v155
	v_cvt_pk_bf16_f32 v170, v156, v157
	v_cvt_pk_bf16_f32 v171, v158, v159
	global_store_dwordx4 v188, v[168:171], s[68:69] offset:256
	global_load_dwordx4 v[52:55], v182, s[64:65] offset:256
	s_waitcnt vmcnt(6)
; __device__ __forceinline__ float sigmoidf_(float x) { return 1.f / (1.f + __expf(-x)); }
	v_lshlrev_b32_e32 v152, 16, v76
	v_and_b32_e32 v153, 0xffff0000, v76
	v_lshlrev_b32_e32 v154, 16, v77
	v_and_b32_e32 v155, 0xffff0000, v77
	v_lshlrev_b32_e32 v156, 16, v78
	v_and_b32_e32 v157, 0xffff0000, v78
	v_lshlrev_b32_e32 v158, 16, v79
	v_and_b32_e32 v159, 0xffff0000, v79
	v_mul_f32_e32 v152, 0xbfb8aa3b, v152
	v_mul_f32_e32 v153, 0xbfb8aa3b, v153
	v_mul_f32_e32 v154, 0xbfb8aa3b, v154
	v_mul_f32_e32 v155, 0xbfb8aa3b, v155
	v_mul_f32_e32 v156, 0xbfb8aa3b, v156
	v_mul_f32_e32 v157, 0xbfb8aa3b, v157
	v_mul_f32_e32 v158, 0xbfb8aa3b, v158
	v_mul_f32_e32 v159, 0xbfb8aa3b, v159
	v_exp_f32_e32 v152, v152
	v_exp_f32_e32 v153, v153
	v_exp_f32_e32 v154, v154
	v_exp_f32_e32 v155, v155
	v_exp_f32_e32 v156, v156
	v_exp_f32_e32 v157, v157
	v_exp_f32_e32 v158, v158
	v_exp_f32_e32 v159, v159
	v_pk_add_f32 v[152:153], v[152:153], 1.0 op_sel_hi:[1,0]
	v_pk_add_f32 v[154:155], v[154:155], 1.0 op_sel_hi:[1,0]
	v_pk_add_f32 v[156:157], v[156:157], 1.0 op_sel_hi:[1,0]
	v_pk_add_f32 v[158:159], v[158:159], 1.0 op_sel_hi:[1,0]
	v_div_scale_f32 v160, s[2:3], v152, v152, 1.0
	v_rcp_f32_e32 v161, v160
	s_nop 0
	v_fma_f32 v162, -v160, v161, 1.0
	v_fmac_f32_e32 v161, v162, v161
	v_div_scale_f32 v163, vcc, 1.0, v152, 1.0
	v_mul_f32_e32 v164, v163, v161
	v_div_scale_f32 v128, s[2:3], v153, v153, 1.0
	v_fma_f32 v162, -v160, v164, v163
	v_rcp_f32_e32 v129, v128
	v_fmac_f32_e32 v164, v162, v161
	s_nop 0
	v_fma_f32 v160, -v160, v164, v163
	v_fma_f32 v130, -v128, v129, 1.0
	v_div_fmas_f32 v160, v160, v161, v164
	v_fmac_f32_e32 v129, v130, v129
	v_div_fixup_f32 v152, v160, v152, 1.0
	v_div_scale_f32 v131, vcc, 1.0, v153, 1.0
	v_mul_f32_e32 v165, v131, v129
	v_div_scale_f32 v160, s[2:3], v154, v154, 1.0
	v_fma_f32 v130, -v128, v165, v131
	v_rcp_f32_e32 v161, v160
	v_fmac_f32_e32 v165, v130, v129
	s_nop 0
	v_fma_f32 v128, -v128, v165, v131
	v_fma_f32 v162, -v160, v161, 1.0
	v_div_fmas_f32 v128, v128, v129, v165
	v_fmac_f32_e32 v161, v162, v161
	v_div_fixup_f32 v153, v128, v153, 1.0
	v_div_scale_f32 v163, vcc, 1.0, v154, 1.0
	v_mul_f32_e32 v164, v163, v161
	v_div_scale_f32 v128, s[2:3], v155, v155, 1.0
	v_fma_f32 v162, -v160, v164, v163
	v_rcp_f32_e32 v129, v128
	v_fmac_f32_e32 v164, v162, v161
	s_nop 0
	v_fma_f32 v160, -v160, v164, v163
	v_fma_f32 v130, -v128, v129, 1.0
	v_div_fmas_f32 v160, v160, v161, v164
	v_fmac_f32_e32 v129, v130, v129
	v_div_fixup_f32 v154, v160, v154, 1.0
	v_div_scale_f32 v131, vcc, 1.0, v155, 1.0
	v_mul_f32_e32 v165, v131, v129
	v_div_scale_f32 v160, s[2:3], v156, v156, 1.0
	v_fma_f32 v130, -v128, v165, v131
	v_rcp_f32_e32 v161, v160
	v_fmac_f32_e32 v165, v130, v129
	s_nop 0
	v_fma_f32 v128, -v128, v165, v131
	v_fma_f32 v162, -v160, v161, 1.0
	v_div_fmas_f32 v128, v128, v129, v165
	v_fmac_f32_e32 v161, v162, v161
	v_div_fixup_f32 v155, v128, v155, 1.0
	v_div_scale_f32 v163, vcc, 1.0, v156, 1.0
	v_mul_f32_e32 v164, v163, v161
	v_div_scale_f32 v128, s[2:3], v157, v157, 1.0
	v_fma_f32 v162, -v160, v164, v163
	v_rcp_f32_e32 v129, v128
	v_fmac_f32_e32 v164, v162, v161
	s_nop 0
	v_fma_f32 v160, -v160, v164, v163
	v_fma_f32 v130, -v128, v129, 1.0
	v_div_fmas_f32 v160, v160, v161, v164
	v_fmac_f32_e32 v129, v130, v129
	v_div_fixup_f32 v156, v160, v156, 1.0
	v_div_scale_f32 v131, vcc, 1.0, v157, 1.0
	v_mul_f32_e32 v165, v131, v129
	v_div_scale_f32 v160, s[2:3], v158, v158, 1.0
	v_fma_f32 v130, -v128, v165, v131
	v_rcp_f32_e32 v161, v160
	v_fmac_f32_e32 v165, v130, v129
	s_nop 0
	v_fma_f32 v128, -v128, v165, v131
	v_fma_f32 v162, -v160, v161, 1.0
	v_div_fmas_f32 v128, v128, v129, v165
	v_fmac_f32_e32 v161, v162, v161
	v_div_fixup_f32 v157, v128, v157, 1.0
	v_div_scale_f32 v163, vcc, 1.0, v158, 1.0
	v_mul_f32_e32 v164, v163, v161
	v_div_scale_f32 v128, s[2:3], v159, v159, 1.0
	v_fma_f32 v162, -v160, v164, v163
	v_rcp_f32_e32 v129, v128
	v_fmac_f32_e32 v164, v162, v161
	s_nop 0
	v_fma_f32 v160, -v160, v164, v163
	v_fma_f32 v130, -v128, v129, 1.0
	v_div_fmas_f32 v160, v160, v161, v164
	v_fmac_f32_e32 v129, v130, v129
	v_div_fixup_f32 v158, v160, v158, 1.0
	v_div_scale_f32 v131, vcc, 1.0, v159, 1.0
	v_mul_f32_e32 v165, v131, v129
	v_fma_f32 v130, -v128, v165, v131
	v_fmac_f32_e32 v165, v130, v129
	v_fma_f32 v128, -v128, v165, v131
	v_div_fmas_f32 v128, v128, v129, v165
	v_div_fixup_f32 v159, v128, v159, 1.0
	v_pk_mul_f32 v[152:153], v[44:45], v[152:153]
	v_pk_mul_f32 v[154:155], v[46:47], v[154:155]
	v_pk_mul_f32 v[156:157], v[40:41], v[156:157]
	v_pk_mul_f32 v[158:159], v[42:43], v[158:159]
	v_cvt_pk_bf16_f32 v168, v152, v153
	v_cvt_pk_bf16_f32 v169, v154, v155
	v_cvt_pk_bf16_f32 v170, v156, v157
	v_cvt_pk_bf16_f32 v171, v158, v159
	global_store_dwordx4 v189, v[168:171], s[68:69]
	global_load_dwordx4 v[44:47], v183, s[64:65]
	s_waitcnt vmcnt(6)
; __device__ __forceinline__ float sigmoidf_(float x) { return 1.f / (1.f + __expf(-x)); }
	v_lshlrev_b32_e32 v152, 16, v68
	v_and_b32_e32 v153, 0xffff0000, v68
	v_lshlrev_b32_e32 v154, 16, v69
	v_and_b32_e32 v155, 0xffff0000, v69
	v_lshlrev_b32_e32 v156, 16, v70
	v_and_b32_e32 v157, 0xffff0000, v70
	v_lshlrev_b32_e32 v158, 16, v71
	v_and_b32_e32 v159, 0xffff0000, v71
	v_mul_f32_e32 v152, 0xbfb8aa3b, v152
	v_mul_f32_e32 v153, 0xbfb8aa3b, v153
	v_mul_f32_e32 v154, 0xbfb8aa3b, v154
	v_mul_f32_e32 v155, 0xbfb8aa3b, v155
	v_mul_f32_e32 v156, 0xbfb8aa3b, v156
	v_mul_f32_e32 v157, 0xbfb8aa3b, v157
	v_mul_f32_e32 v158, 0xbfb8aa3b, v158
	v_mul_f32_e32 v159, 0xbfb8aa3b, v159
	v_exp_f32_e32 v152, v152
	v_exp_f32_e32 v153, v153
	v_exp_f32_e32 v154, v154
	v_exp_f32_e32 v155, v155
	v_exp_f32_e32 v156, v156
	v_exp_f32_e32 v157, v157
	v_exp_f32_e32 v158, v158
	v_exp_f32_e32 v159, v159
	v_pk_add_f32 v[152:153], v[152:153], 1.0 op_sel_hi:[1,0]
	v_pk_add_f32 v[154:155], v[154:155], 1.0 op_sel_hi:[1,0]
	v_pk_add_f32 v[156:157], v[156:157], 1.0 op_sel_hi:[1,0]
	v_pk_add_f32 v[158:159], v[158:159], 1.0 op_sel_hi:[1,0]
	v_div_scale_f32 v160, s[2:3], v152, v152, 1.0
	v_rcp_f32_e32 v161, v160
	s_nop 0
	v_fma_f32 v162, -v160, v161, 1.0
	v_fmac_f32_e32 v161, v162, v161
	v_div_scale_f32 v163, vcc, 1.0, v152, 1.0
	v_mul_f32_e32 v164, v163, v161
	v_div_scale_f32 v128, s[2:3], v153, v153, 1.0
	v_fma_f32 v162, -v160, v164, v163
	v_rcp_f32_e32 v129, v128
	v_fmac_f32_e32 v164, v162, v161
	s_nop 0
	v_fma_f32 v160, -v160, v164, v163
	v_fma_f32 v130, -v128, v129, 1.0
	v_div_fmas_f32 v160, v160, v161, v164
	v_fmac_f32_e32 v129, v130, v129
	v_div_fixup_f32 v152, v160, v152, 1.0
	v_div_scale_f32 v131, vcc, 1.0, v153, 1.0
	v_mul_f32_e32 v165, v131, v129
	v_div_scale_f32 v160, s[2:3], v154, v154, 1.0
	v_fma_f32 v130, -v128, v165, v131
	v_rcp_f32_e32 v161, v160
	v_fmac_f32_e32 v165, v130, v129
	s_nop 0
	v_fma_f32 v128, -v128, v165, v131
	v_fma_f32 v162, -v160, v161, 1.0
	v_div_fmas_f32 v128, v128, v129, v165
	v_fmac_f32_e32 v161, v162, v161
	v_div_fixup_f32 v153, v128, v153, 1.0
	v_div_scale_f32 v163, vcc, 1.0, v154, 1.0
	v_mul_f32_e32 v164, v163, v161
	v_div_scale_f32 v128, s[2:3], v155, v155, 1.0
	v_fma_f32 v162, -v160, v164, v163
	v_rcp_f32_e32 v129, v128
	v_fmac_f32_e32 v164, v162, v161
	s_nop 0
	v_fma_f32 v160, -v160, v164, v163
	v_fma_f32 v130, -v128, v129, 1.0
	v_div_fmas_f32 v160, v160, v161, v164
	v_fmac_f32_e32 v129, v130, v129
	v_div_fixup_f32 v154, v160, v154, 1.0
	v_div_scale_f32 v131, vcc, 1.0, v155, 1.0
	v_mul_f32_e32 v165, v131, v129
	v_div_scale_f32 v160, s[2:3], v156, v156, 1.0
	v_fma_f32 v130, -v128, v165, v131
	v_rcp_f32_e32 v161, v160
	v_fmac_f32_e32 v165, v130, v129
	s_nop 0
	v_fma_f32 v128, -v128, v165, v131
	v_fma_f32 v162, -v160, v161, 1.0
	v_div_fmas_f32 v128, v128, v129, v165
	v_fmac_f32_e32 v161, v162, v161
	v_div_fixup_f32 v155, v128, v155, 1.0
	v_div_scale_f32 v163, vcc, 1.0, v156, 1.0
	v_mul_f32_e32 v164, v163, v161
	v_div_scale_f32 v128, s[2:3], v157, v157, 1.0
	v_fma_f32 v162, -v160, v164, v163
	v_rcp_f32_e32 v129, v128
	v_fmac_f32_e32 v164, v162, v161
	s_nop 0
	v_fma_f32 v160, -v160, v164, v163
	v_fma_f32 v130, -v128, v129, 1.0
	v_div_fmas_f32 v160, v160, v161, v164
	v_fmac_f32_e32 v129, v130, v129
	v_div_fixup_f32 v156, v160, v156, 1.0
	v_div_scale_f32 v131, vcc, 1.0, v157, 1.0
	v_mul_f32_e32 v165, v131, v129
	v_div_scale_f32 v160, s[2:3], v158, v158, 1.0
	v_fma_f32 v130, -v128, v165, v131
	v_rcp_f32_e32 v161, v160
	v_fmac_f32_e32 v165, v130, v129
	s_nop 0
	v_fma_f32 v128, -v128, v165, v131
	v_fma_f32 v162, -v160, v161, 1.0
	v_div_fmas_f32 v128, v128, v129, v165
	v_fmac_f32_e32 v161, v162, v161
	v_div_fixup_f32 v157, v128, v157, 1.0
	v_div_scale_f32 v163, vcc, 1.0, v158, 1.0
	v_mul_f32_e32 v164, v163, v161
	v_div_scale_f32 v128, s[2:3], v159, v159, 1.0
	v_fma_f32 v162, -v160, v164, v163
	v_rcp_f32_e32 v129, v128
	v_fmac_f32_e32 v164, v162, v161
	s_nop 0
	v_fma_f32 v160, -v160, v164, v163
	v_fma_f32 v130, -v128, v129, 1.0
	v_div_fmas_f32 v160, v160, v161, v164
	v_fmac_f32_e32 v129, v130, v129
	v_div_fixup_f32 v158, v160, v158, 1.0
	v_div_scale_f32 v131, vcc, 1.0, v159, 1.0
	v_mul_f32_e32 v165, v131, v129
	v_fma_f32 v130, -v128, v165, v131
	v_fmac_f32_e32 v165, v130, v129
	v_fma_f32 v128, -v128, v165, v131
	v_div_fmas_f32 v128, v128, v129, v165
	v_div_fixup_f32 v159, v128, v159, 1.0
	v_pk_mul_f32 v[152:153], v[36:37], v[152:153]
	v_pk_mul_f32 v[154:155], v[38:39], v[154:155]
	v_pk_mul_f32 v[156:157], v[32:33], v[156:157]
	v_pk_mul_f32 v[158:159], v[34:35], v[158:159]
	v_cvt_pk_bf16_f32 v168, v152, v153
	v_cvt_pk_bf16_f32 v169, v154, v155
	v_cvt_pk_bf16_f32 v170, v156, v157
	v_cvt_pk_bf16_f32 v171, v158, v159
	global_store_dwordx4 v189, v[168:171], s[68:69] offset:256
	global_load_dwordx4 v[36:39], v183, s[64:65] offset:256
	s_waitcnt vmcnt(6)
; __device__ __forceinline__ float sigmoidf_(float x) { return 1.f / (1.f + __expf(-x)); }
	v_lshlrev_b32_e32 v152, 16, v60
	v_and_b32_e32 v153, 0xffff0000, v60
	v_lshlrev_b32_e32 v154, 16, v61
	v_and_b32_e32 v155, 0xffff0000, v61
	v_lshlrev_b32_e32 v156, 16, v62
	v_and_b32_e32 v157, 0xffff0000, v62
	v_lshlrev_b32_e32 v158, 16, v63
	v_and_b32_e32 v159, 0xffff0000, v63
	v_mul_f32_e32 v152, 0xbfb8aa3b, v152
	v_mul_f32_e32 v153, 0xbfb8aa3b, v153
	v_mul_f32_e32 v154, 0xbfb8aa3b, v154
	v_mul_f32_e32 v155, 0xbfb8aa3b, v155
	v_mul_f32_e32 v156, 0xbfb8aa3b, v156
	v_mul_f32_e32 v157, 0xbfb8aa3b, v157
	v_mul_f32_e32 v158, 0xbfb8aa3b, v158
	v_mul_f32_e32 v159, 0xbfb8aa3b, v159
	v_exp_f32_e32 v152, v152
	v_exp_f32_e32 v153, v153
	v_exp_f32_e32 v154, v154
	v_exp_f32_e32 v155, v155
	v_exp_f32_e32 v156, v156
	v_exp_f32_e32 v157, v157
	v_exp_f32_e32 v158, v158
	v_exp_f32_e32 v159, v159
	v_pk_add_f32 v[152:153], v[152:153], 1.0 op_sel_hi:[1,0]
	v_pk_add_f32 v[154:155], v[154:155], 1.0 op_sel_hi:[1,0]
	v_pk_add_f32 v[156:157], v[156:157], 1.0 op_sel_hi:[1,0]
	v_pk_add_f32 v[158:159], v[158:159], 1.0 op_sel_hi:[1,0]
	v_div_scale_f32 v160, s[2:3], v152, v152, 1.0
	v_rcp_f32_e32 v161, v160
	s_nop 0
	v_fma_f32 v162, -v160, v161, 1.0
	v_fmac_f32_e32 v161, v162, v161
	v_div_scale_f32 v163, vcc, 1.0, v152, 1.0
	v_mul_f32_e32 v164, v163, v161
	v_div_scale_f32 v128, s[2:3], v153, v153, 1.0
	v_fma_f32 v162, -v160, v164, v163
	v_rcp_f32_e32 v129, v128
	v_fmac_f32_e32 v164, v162, v161
	s_nop 0
	v_fma_f32 v160, -v160, v164, v163
	v_fma_f32 v130, -v128, v129, 1.0
	v_div_fmas_f32 v160, v160, v161, v164
	v_fmac_f32_e32 v129, v130, v129
	v_div_fixup_f32 v152, v160, v152, 1.0
	v_div_scale_f32 v131, vcc, 1.0, v153, 1.0
	v_mul_f32_e32 v165, v131, v129
	v_div_scale_f32 v160, s[2:3], v154, v154, 1.0
	v_fma_f32 v130, -v128, v165, v131
	v_rcp_f32_e32 v161, v160
	v_fmac_f32_e32 v165, v130, v129
	s_nop 0
	v_fma_f32 v128, -v128, v165, v131
	v_fma_f32 v162, -v160, v161, 1.0
	v_div_fmas_f32 v128, v128, v129, v165
	v_fmac_f32_e32 v161, v162, v161
	v_div_fixup_f32 v153, v128, v153, 1.0
	v_div_scale_f32 v163, vcc, 1.0, v154, 1.0
	v_mul_f32_e32 v164, v163, v161
	v_div_scale_f32 v128, s[2:3], v155, v155, 1.0
	v_fma_f32 v162, -v160, v164, v163
	v_rcp_f32_e32 v129, v128
	v_fmac_f32_e32 v164, v162, v161
	s_nop 0
	v_fma_f32 v160, -v160, v164, v163
	v_fma_f32 v130, -v128, v129, 1.0
	v_div_fmas_f32 v160, v160, v161, v164
	v_fmac_f32_e32 v129, v130, v129
	v_div_fixup_f32 v154, v160, v154, 1.0
	v_div_scale_f32 v131, vcc, 1.0, v155, 1.0
	v_mul_f32_e32 v165, v131, v129
	v_div_scale_f32 v160, s[2:3], v156, v156, 1.0
	v_fma_f32 v130, -v128, v165, v131
	v_rcp_f32_e32 v161, v160
	v_fmac_f32_e32 v165, v130, v129
	s_nop 0
	v_fma_f32 v128, -v128, v165, v131
	v_fma_f32 v162, -v160, v161, 1.0
	v_div_fmas_f32 v128, v128, v129, v165
	v_fmac_f32_e32 v161, v162, v161
	v_div_fixup_f32 v155, v128, v155, 1.0
	v_div_scale_f32 v163, vcc, 1.0, v156, 1.0
	v_mul_f32_e32 v164, v163, v161
	v_div_scale_f32 v128, s[2:3], v157, v157, 1.0
	v_fma_f32 v162, -v160, v164, v163
	v_rcp_f32_e32 v129, v128
	v_fmac_f32_e32 v164, v162, v161
	s_nop 0
	v_fma_f32 v160, -v160, v164, v163
	v_fma_f32 v130, -v128, v129, 1.0
	v_div_fmas_f32 v160, v160, v161, v164
	v_fmac_f32_e32 v129, v130, v129
	v_div_fixup_f32 v156, v160, v156, 1.0
	v_div_scale_f32 v131, vcc, 1.0, v157, 1.0
	v_mul_f32_e32 v165, v131, v129
	v_div_scale_f32 v160, s[2:3], v158, v158, 1.0
	v_fma_f32 v130, -v128, v165, v131
	v_rcp_f32_e32 v161, v160
	v_fmac_f32_e32 v165, v130, v129
	s_nop 0
	v_fma_f32 v128, -v128, v165, v131
	v_fma_f32 v162, -v160, v161, 1.0
	v_div_fmas_f32 v128, v128, v129, v165
	v_fmac_f32_e32 v161, v162, v161
	v_div_fixup_f32 v157, v128, v157, 1.0
	v_div_scale_f32 v163, vcc, 1.0, v158, 1.0
	v_mul_f32_e32 v164, v163, v161
	v_div_scale_f32 v128, s[2:3], v159, v159, 1.0
	v_fma_f32 v162, -v160, v164, v163
	v_rcp_f32_e32 v129, v128
	v_fmac_f32_e32 v164, v162, v161
	s_nop 0
	v_fma_f32 v160, -v160, v164, v163
	v_fma_f32 v130, -v128, v129, 1.0
	v_div_fmas_f32 v160, v160, v161, v164
	v_fmac_f32_e32 v129, v130, v129
	v_div_fixup_f32 v158, v160, v158, 1.0
	v_div_scale_f32 v131, vcc, 1.0, v159, 1.0
	v_mul_f32_e32 v165, v131, v129
	v_fma_f32 v130, -v128, v165, v131
	v_fmac_f32_e32 v165, v130, v129
	v_fma_f32 v128, -v128, v165, v131
	v_div_fmas_f32 v128, v128, v129, v165
	v_div_fixup_f32 v159, v128, v159, 1.0
	v_pk_mul_f32 v[152:153], v[28:29], v[152:153]
	v_pk_mul_f32 v[154:155], v[30:31], v[154:155]
	v_pk_mul_f32 v[156:157], v[24:25], v[156:157]
	v_pk_mul_f32 v[158:159], v[26:27], v[158:159]
	v_cvt_pk_bf16_f32 v168, v152, v153
	v_cvt_pk_bf16_f32 v169, v154, v155
	v_cvt_pk_bf16_f32 v170, v156, v157
	v_cvt_pk_bf16_f32 v171, v158, v159
	global_store_dwordx4 v190, v[168:171], s[68:69]
	s_waitcnt vmcnt(5)
; __device__ __forceinline__ float sigmoidf_(float x) { return 1.f / (1.f + __expf(-x)); }
	v_lshlrev_b32_e32 v152, 16, v52
	v_and_b32_e32 v153, 0xffff0000, v52
	v_lshlrev_b32_e32 v154, 16, v53
	v_and_b32_e32 v155, 0xffff0000, v53
	v_lshlrev_b32_e32 v156, 16, v54
	v_and_b32_e32 v157, 0xffff0000, v54
	v_lshlrev_b32_e32 v158, 16, v55
	v_and_b32_e32 v159, 0xffff0000, v55
	v_mul_f32_e32 v152, 0xbfb8aa3b, v152
	v_mul_f32_e32 v153, 0xbfb8aa3b, v153
	v_mul_f32_e32 v154, 0xbfb8aa3b, v154
	v_mul_f32_e32 v155, 0xbfb8aa3b, v155
	v_mul_f32_e32 v156, 0xbfb8aa3b, v156
	v_mul_f32_e32 v157, 0xbfb8aa3b, v157
	v_mul_f32_e32 v158, 0xbfb8aa3b, v158
	v_mul_f32_e32 v159, 0xbfb8aa3b, v159
	v_exp_f32_e32 v152, v152
	v_exp_f32_e32 v153, v153
	v_exp_f32_e32 v154, v154
	v_exp_f32_e32 v155, v155
	v_exp_f32_e32 v156, v156
	v_exp_f32_e32 v157, v157
	v_exp_f32_e32 v158, v158
	v_exp_f32_e32 v159, v159
	v_pk_add_f32 v[152:153], v[152:153], 1.0 op_sel_hi:[1,0]
	v_pk_add_f32 v[154:155], v[154:155], 1.0 op_sel_hi:[1,0]
	v_pk_add_f32 v[156:157], v[156:157], 1.0 op_sel_hi:[1,0]
	v_pk_add_f32 v[158:159], v[158:159], 1.0 op_sel_hi:[1,0]
	v_div_scale_f32 v160, s[2:3], v152, v152, 1.0
	v_rcp_f32_e32 v161, v160
	s_nop 0
	v_fma_f32 v162, -v160, v161, 1.0
	v_fmac_f32_e32 v161, v162, v161
	v_div_scale_f32 v163, vcc, 1.0, v152, 1.0
	v_mul_f32_e32 v164, v163, v161
	v_div_scale_f32 v128, s[2:3], v153, v153, 1.0
	v_fma_f32 v162, -v160, v164, v163
	v_rcp_f32_e32 v129, v128
	v_fmac_f32_e32 v164, v162, v161
	s_nop 0
	v_fma_f32 v160, -v160, v164, v163
	v_fma_f32 v130, -v128, v129, 1.0
	v_div_fmas_f32 v160, v160, v161, v164
	v_fmac_f32_e32 v129, v130, v129
	v_div_fixup_f32 v152, v160, v152, 1.0
	v_div_scale_f32 v131, vcc, 1.0, v153, 1.0
	v_mul_f32_e32 v165, v131, v129
	v_div_scale_f32 v160, s[2:3], v154, v154, 1.0
	v_fma_f32 v130, -v128, v165, v131
	v_rcp_f32_e32 v161, v160
	v_fmac_f32_e32 v165, v130, v129
	s_nop 0
	v_fma_f32 v128, -v128, v165, v131
	v_fma_f32 v162, -v160, v161, 1.0
	v_div_fmas_f32 v128, v128, v129, v165
	v_fmac_f32_e32 v161, v162, v161
	v_div_fixup_f32 v153, v128, v153, 1.0
	v_div_scale_f32 v163, vcc, 1.0, v154, 1.0
	v_mul_f32_e32 v164, v163, v161
	v_div_scale_f32 v128, s[2:3], v155, v155, 1.0
	v_fma_f32 v162, -v160, v164, v163
	v_rcp_f32_e32 v129, v128
	v_fmac_f32_e32 v164, v162, v161
	s_nop 0
	v_fma_f32 v160, -v160, v164, v163
	v_fma_f32 v130, -v128, v129, 1.0
	v_div_fmas_f32 v160, v160, v161, v164
	v_fmac_f32_e32 v129, v130, v129
	v_div_fixup_f32 v154, v160, v154, 1.0
	v_div_scale_f32 v131, vcc, 1.0, v155, 1.0
	v_mul_f32_e32 v165, v131, v129
	v_div_scale_f32 v160, s[2:3], v156, v156, 1.0
	v_fma_f32 v130, -v128, v165, v131
	v_rcp_f32_e32 v161, v160
	v_fmac_f32_e32 v165, v130, v129
	s_nop 0
	v_fma_f32 v128, -v128, v165, v131
	v_fma_f32 v162, -v160, v161, 1.0
	v_div_fmas_f32 v128, v128, v129, v165
	v_fmac_f32_e32 v161, v162, v161
	v_div_fixup_f32 v155, v128, v155, 1.0
	v_div_scale_f32 v163, vcc, 1.0, v156, 1.0
	v_mul_f32_e32 v164, v163, v161
	v_div_scale_f32 v128, s[2:3], v157, v157, 1.0
	v_fma_f32 v162, -v160, v164, v163
	v_rcp_f32_e32 v129, v128
	v_fmac_f32_e32 v164, v162, v161
	s_nop 0
	v_fma_f32 v160, -v160, v164, v163
	v_fma_f32 v130, -v128, v129, 1.0
	v_div_fmas_f32 v160, v160, v161, v164
	v_fmac_f32_e32 v129, v130, v129
	v_div_fixup_f32 v156, v160, v156, 1.0
	v_div_scale_f32 v131, vcc, 1.0, v157, 1.0
	v_mul_f32_e32 v165, v131, v129
	v_div_scale_f32 v160, s[2:3], v158, v158, 1.0
	v_fma_f32 v130, -v128, v165, v131
	v_rcp_f32_e32 v161, v160
	v_fmac_f32_e32 v165, v130, v129
	s_nop 0
	v_fma_f32 v128, -v128, v165, v131
	v_fma_f32 v162, -v160, v161, 1.0
	v_div_fmas_f32 v128, v128, v129, v165
	v_fmac_f32_e32 v161, v162, v161
	v_div_fixup_f32 v157, v128, v157, 1.0
	v_div_scale_f32 v163, vcc, 1.0, v158, 1.0
	v_mul_f32_e32 v164, v163, v161
	v_div_scale_f32 v128, s[2:3], v159, v159, 1.0
	v_fma_f32 v162, -v160, v164, v163
	v_rcp_f32_e32 v129, v128
	v_fmac_f32_e32 v164, v162, v161
	s_nop 0
	v_fma_f32 v160, -v160, v164, v163
	v_fma_f32 v130, -v128, v129, 1.0
	v_div_fmas_f32 v160, v160, v161, v164
	v_fmac_f32_e32 v129, v130, v129
	v_div_fixup_f32 v158, v160, v158, 1.0
	v_div_scale_f32 v131, vcc, 1.0, v159, 1.0
	v_mul_f32_e32 v165, v131, v129
	v_fma_f32 v130, -v128, v165, v131
	v_fmac_f32_e32 v165, v130, v129
	v_fma_f32 v128, -v128, v165, v131
	v_div_fmas_f32 v128, v128, v129, v165
	v_div_fixup_f32 v159, v128, v159, 1.0
	v_pk_mul_f32 v[152:153], v[20:21], v[152:153]
	v_pk_mul_f32 v[154:155], v[22:23], v[154:155]
	v_pk_mul_f32 v[156:157], v[16:17], v[156:157]
	v_pk_mul_f32 v[158:159], v[18:19], v[158:159]
	v_cvt_pk_bf16_f32 v168, v152, v153
	v_cvt_pk_bf16_f32 v169, v154, v155
	v_cvt_pk_bf16_f32 v170, v156, v157
	v_cvt_pk_bf16_f32 v171, v158, v159
	global_store_dwordx4 v190, v[168:171], s[68:69] offset:256
	s_waitcnt vmcnt(4)
; __device__ __forceinline__ float sigmoidf_(float x) { return 1.f / (1.f + __expf(-x)); }
	v_lshlrev_b32_e32 v152, 16, v44
	v_and_b32_e32 v153, 0xffff0000, v44
	v_lshlrev_b32_e32 v154, 16, v45
	v_and_b32_e32 v155, 0xffff0000, v45
	v_lshlrev_b32_e32 v156, 16, v46
	v_and_b32_e32 v157, 0xffff0000, v46
	v_lshlrev_b32_e32 v158, 16, v47
	v_and_b32_e32 v159, 0xffff0000, v47
	v_mul_f32_e32 v152, 0xbfb8aa3b, v152
	v_mul_f32_e32 v153, 0xbfb8aa3b, v153
	v_mul_f32_e32 v154, 0xbfb8aa3b, v154
	v_mul_f32_e32 v155, 0xbfb8aa3b, v155
	v_mul_f32_e32 v156, 0xbfb8aa3b, v156
	v_mul_f32_e32 v157, 0xbfb8aa3b, v157
	v_mul_f32_e32 v158, 0xbfb8aa3b, v158
	v_mul_f32_e32 v159, 0xbfb8aa3b, v159
	v_exp_f32_e32 v152, v152
	v_exp_f32_e32 v153, v153
	v_exp_f32_e32 v154, v154
	v_exp_f32_e32 v155, v155
	v_exp_f32_e32 v156, v156
	v_exp_f32_e32 v157, v157
	v_exp_f32_e32 v158, v158
	v_exp_f32_e32 v159, v159
	v_pk_add_f32 v[152:153], v[152:153], 1.0 op_sel_hi:[1,0]
	v_pk_add_f32 v[154:155], v[154:155], 1.0 op_sel_hi:[1,0]
	v_pk_add_f32 v[156:157], v[156:157], 1.0 op_sel_hi:[1,0]
	v_pk_add_f32 v[158:159], v[158:159], 1.0 op_sel_hi:[1,0]
	v_div_scale_f32 v160, s[2:3], v152, v152, 1.0
	v_rcp_f32_e32 v161, v160
	s_nop 0
	v_fma_f32 v162, -v160, v161, 1.0
	v_fmac_f32_e32 v161, v162, v161
	v_div_scale_f32 v163, vcc, 1.0, v152, 1.0
	v_mul_f32_e32 v164, v163, v161
	v_div_scale_f32 v128, s[2:3], v153, v153, 1.0
	v_fma_f32 v162, -v160, v164, v163
	v_rcp_f32_e32 v129, v128
	v_fmac_f32_e32 v164, v162, v161
	s_nop 0
	v_fma_f32 v160, -v160, v164, v163
	v_fma_f32 v130, -v128, v129, 1.0
	v_div_fmas_f32 v160, v160, v161, v164
	v_fmac_f32_e32 v129, v130, v129
	v_div_fixup_f32 v152, v160, v152, 1.0
	v_div_scale_f32 v131, vcc, 1.0, v153, 1.0
	v_mul_f32_e32 v165, v131, v129
	v_div_scale_f32 v160, s[2:3], v154, v154, 1.0
	v_fma_f32 v130, -v128, v165, v131
	v_rcp_f32_e32 v161, v160
	v_fmac_f32_e32 v165, v130, v129
	s_nop 0
	v_fma_f32 v128, -v128, v165, v131
	v_fma_f32 v162, -v160, v161, 1.0
	v_div_fmas_f32 v128, v128, v129, v165
	v_fmac_f32_e32 v161, v162, v161
	v_div_fixup_f32 v153, v128, v153, 1.0
	v_div_scale_f32 v163, vcc, 1.0, v154, 1.0
	v_mul_f32_e32 v164, v163, v161
	v_div_scale_f32 v128, s[2:3], v155, v155, 1.0
	v_fma_f32 v162, -v160, v164, v163
	v_rcp_f32_e32 v129, v128
	v_fmac_f32_e32 v164, v162, v161
	s_nop 0
	v_fma_f32 v160, -v160, v164, v163
	v_fma_f32 v130, -v128, v129, 1.0
	v_div_fmas_f32 v160, v160, v161, v164
	v_fmac_f32_e32 v129, v130, v129
	v_div_fixup_f32 v154, v160, v154, 1.0
	v_div_scale_f32 v131, vcc, 1.0, v155, 1.0
	v_mul_f32_e32 v165, v131, v129
	v_div_scale_f32 v160, s[2:3], v156, v156, 1.0
	v_fma_f32 v130, -v128, v165, v131
	v_rcp_f32_e32 v161, v160
	v_fmac_f32_e32 v165, v130, v129
	s_nop 0
	v_fma_f32 v128, -v128, v165, v131
	v_fma_f32 v162, -v160, v161, 1.0
	v_div_fmas_f32 v128, v128, v129, v165
	v_fmac_f32_e32 v161, v162, v161
	v_div_fixup_f32 v155, v128, v155, 1.0
	v_div_scale_f32 v163, vcc, 1.0, v156, 1.0
	v_mul_f32_e32 v164, v163, v161
	v_div_scale_f32 v128, s[2:3], v157, v157, 1.0
	v_fma_f32 v162, -v160, v164, v163
	v_rcp_f32_e32 v129, v128
	v_fmac_f32_e32 v164, v162, v161
	s_nop 0
	v_fma_f32 v160, -v160, v164, v163
	v_fma_f32 v130, -v128, v129, 1.0
	v_div_fmas_f32 v160, v160, v161, v164
	v_fmac_f32_e32 v129, v130, v129
	v_div_fixup_f32 v156, v160, v156, 1.0
	v_div_scale_f32 v131, vcc, 1.0, v157, 1.0
	v_mul_f32_e32 v165, v131, v129
	v_div_scale_f32 v160, s[2:3], v158, v158, 1.0
	v_fma_f32 v130, -v128, v165, v131
	v_rcp_f32_e32 v161, v160
	v_fmac_f32_e32 v165, v130, v129
	s_nop 0
	v_fma_f32 v128, -v128, v165, v131
	v_fma_f32 v162, -v160, v161, 1.0
	v_div_fmas_f32 v128, v128, v129, v165
	v_fmac_f32_e32 v161, v162, v161
	v_div_fixup_f32 v157, v128, v157, 1.0
	v_div_scale_f32 v163, vcc, 1.0, v158, 1.0
	v_mul_f32_e32 v164, v163, v161
	v_div_scale_f32 v128, s[2:3], v159, v159, 1.0
	v_fma_f32 v162, -v160, v164, v163
	v_rcp_f32_e32 v129, v128
	v_fmac_f32_e32 v164, v162, v161
	s_nop 0
	v_fma_f32 v160, -v160, v164, v163
	v_fma_f32 v130, -v128, v129, 1.0
	v_div_fmas_f32 v160, v160, v161, v164
	v_fmac_f32_e32 v129, v130, v129
	v_div_fixup_f32 v158, v160, v158, 1.0
	v_div_scale_f32 v131, vcc, 1.0, v159, 1.0
	v_mul_f32_e32 v165, v131, v129
	v_fma_f32 v130, -v128, v165, v131
	v_fmac_f32_e32 v165, v130, v129
	v_fma_f32 v128, -v128, v165, v131
	v_div_fmas_f32 v128, v128, v129, v165
	v_div_fixup_f32 v159, v128, v159, 1.0
	v_pk_mul_f32 v[152:153], v[12:13], v[152:153]
	v_pk_mul_f32 v[154:155], v[14:15], v[154:155]
	v_pk_mul_f32 v[156:157], v[8:9], v[156:157]
	v_pk_mul_f32 v[158:159], v[10:11], v[158:159]
	v_cvt_pk_bf16_f32 v168, v152, v153
	v_cvt_pk_bf16_f32 v169, v154, v155
	v_cvt_pk_bf16_f32 v170, v156, v157
	v_cvt_pk_bf16_f32 v171, v158, v159
	global_store_dwordx4 v191, v[168:171], s[68:69]
	s_waitcnt vmcnt(3)
; __device__ __forceinline__ float sigmoidf_(float x) { return 1.f / (1.f + __expf(-x)); }
	v_lshlrev_b32_e32 v152, 16, v36
	v_and_b32_e32 v153, 0xffff0000, v36
	v_lshlrev_b32_e32 v154, 16, v37
	v_and_b32_e32 v155, 0xffff0000, v37
	v_lshlrev_b32_e32 v156, 16, v38
	v_and_b32_e32 v157, 0xffff0000, v38
	v_lshlrev_b32_e32 v158, 16, v39
	v_and_b32_e32 v159, 0xffff0000, v39
	v_mul_f32_e32 v152, 0xbfb8aa3b, v152
	v_mul_f32_e32 v153, 0xbfb8aa3b, v153
	v_mul_f32_e32 v154, 0xbfb8aa3b, v154
	v_mul_f32_e32 v155, 0xbfb8aa3b, v155
	v_mul_f32_e32 v156, 0xbfb8aa3b, v156
	v_mul_f32_e32 v157, 0xbfb8aa3b, v157
	v_mul_f32_e32 v158, 0xbfb8aa3b, v158
	v_mul_f32_e32 v159, 0xbfb8aa3b, v159
	v_exp_f32_e32 v152, v152
	v_exp_f32_e32 v153, v153
	v_exp_f32_e32 v154, v154
	v_exp_f32_e32 v155, v155
	v_exp_f32_e32 v156, v156
	v_exp_f32_e32 v157, v157
	v_exp_f32_e32 v158, v158
	v_exp_f32_e32 v159, v159
	v_pk_add_f32 v[152:153], v[152:153], 1.0 op_sel_hi:[1,0]
	v_pk_add_f32 v[154:155], v[154:155], 1.0 op_sel_hi:[1,0]
	v_pk_add_f32 v[156:157], v[156:157], 1.0 op_sel_hi:[1,0]
	v_pk_add_f32 v[158:159], v[158:159], 1.0 op_sel_hi:[1,0]
	v_div_scale_f32 v160, s[2:3], v152, v152, 1.0
	v_rcp_f32_e32 v161, v160
	s_nop 0
	v_fma_f32 v162, -v160, v161, 1.0
	v_fmac_f32_e32 v161, v162, v161
	v_div_scale_f32 v163, vcc, 1.0, v152, 1.0
	v_mul_f32_e32 v164, v163, v161
	v_div_scale_f32 v128, s[2:3], v153, v153, 1.0
	v_fma_f32 v162, -v160, v164, v163
	v_rcp_f32_e32 v129, v128
	v_fmac_f32_e32 v164, v162, v161
	s_nop 0
	v_fma_f32 v160, -v160, v164, v163
	v_fma_f32 v130, -v128, v129, 1.0
	v_div_fmas_f32 v160, v160, v161, v164
	v_fmac_f32_e32 v129, v130, v129
	v_div_fixup_f32 v152, v160, v152, 1.0
	v_div_scale_f32 v131, vcc, 1.0, v153, 1.0
	v_mul_f32_e32 v165, v131, v129
	v_div_scale_f32 v160, s[2:3], v154, v154, 1.0
	v_fma_f32 v130, -v128, v165, v131
	v_rcp_f32_e32 v161, v160
	v_fmac_f32_e32 v165, v130, v129
	s_nop 0
	v_fma_f32 v128, -v128, v165, v131
	v_fma_f32 v162, -v160, v161, 1.0
	v_div_fmas_f32 v128, v128, v129, v165
	v_fmac_f32_e32 v161, v162, v161
	v_div_fixup_f32 v153, v128, v153, 1.0
	v_div_scale_f32 v163, vcc, 1.0, v154, 1.0
	v_mul_f32_e32 v164, v163, v161
	v_div_scale_f32 v128, s[2:3], v155, v155, 1.0
	v_fma_f32 v162, -v160, v164, v163
	v_rcp_f32_e32 v129, v128
	v_fmac_f32_e32 v164, v162, v161
	s_nop 0
	v_fma_f32 v160, -v160, v164, v163
	v_fma_f32 v130, -v128, v129, 1.0
	v_div_fmas_f32 v160, v160, v161, v164
	v_fmac_f32_e32 v129, v130, v129
	v_div_fixup_f32 v154, v160, v154, 1.0
	v_div_scale_f32 v131, vcc, 1.0, v155, 1.0
	v_mul_f32_e32 v165, v131, v129
	v_div_scale_f32 v160, s[2:3], v156, v156, 1.0
	v_fma_f32 v130, -v128, v165, v131
	v_rcp_f32_e32 v161, v160
	v_fmac_f32_e32 v165, v130, v129
	s_nop 0
	v_fma_f32 v128, -v128, v165, v131
	v_fma_f32 v162, -v160, v161, 1.0
	v_div_fmas_f32 v128, v128, v129, v165
	v_fmac_f32_e32 v161, v162, v161
	v_div_fixup_f32 v155, v128, v155, 1.0
	v_div_scale_f32 v163, vcc, 1.0, v156, 1.0
	v_mul_f32_e32 v164, v163, v161
	v_div_scale_f32 v128, s[2:3], v157, v157, 1.0
	v_fma_f32 v162, -v160, v164, v163
	v_rcp_f32_e32 v129, v128
	v_fmac_f32_e32 v164, v162, v161
	s_nop 0
	v_fma_f32 v160, -v160, v164, v163
	v_fma_f32 v130, -v128, v129, 1.0
	v_div_fmas_f32 v160, v160, v161, v164
	v_fmac_f32_e32 v129, v130, v129
	v_div_fixup_f32 v156, v160, v156, 1.0
	v_div_scale_f32 v131, vcc, 1.0, v157, 1.0
	v_mul_f32_e32 v165, v131, v129
	v_div_scale_f32 v160, s[2:3], v158, v158, 1.0
	v_fma_f32 v130, -v128, v165, v131
	v_rcp_f32_e32 v161, v160
	v_fmac_f32_e32 v165, v130, v129
	s_nop 0
	v_fma_f32 v128, -v128, v165, v131
	v_fma_f32 v162, -v160, v161, 1.0
	v_div_fmas_f32 v128, v128, v129, v165
	v_fmac_f32_e32 v161, v162, v161
	v_div_fixup_f32 v157, v128, v157, 1.0
	v_div_scale_f32 v163, vcc, 1.0, v158, 1.0
	v_mul_f32_e32 v164, v163, v161
	v_div_scale_f32 v128, s[2:3], v159, v159, 1.0
	v_fma_f32 v162, -v160, v164, v163
	v_rcp_f32_e32 v129, v128
	v_fmac_f32_e32 v164, v162, v161
	s_nop 0
	v_fma_f32 v160, -v160, v164, v163
	v_fma_f32 v130, -v128, v129, 1.0
	v_div_fmas_f32 v160, v160, v161, v164
	v_fmac_f32_e32 v129, v130, v129
	v_div_fixup_f32 v158, v160, v158, 1.0
	v_div_scale_f32 v131, vcc, 1.0, v159, 1.0
	v_mul_f32_e32 v165, v131, v129
	v_fma_f32 v130, -v128, v165, v131
	v_fmac_f32_e32 v165, v130, v129
	v_fma_f32 v128, -v128, v165, v131
	v_div_fmas_f32 v128, v128, v129, v165
	v_div_fixup_f32 v159, v128, v159, 1.0
	v_pk_mul_f32 v[152:153], v[4:5], v[152:153]
	v_pk_mul_f32 v[154:155], v[6:7], v[154:155]
	v_pk_mul_f32 v[156:157], v[0:1], v[156:157]
	v_pk_mul_f32 v[158:159], v[2:3], v[158:159]
	v_cvt_pk_bf16_f32 v168, v152, v153
	v_cvt_pk_bf16_f32 v169, v154, v155
	v_cvt_pk_bf16_f32 v170, v156, v157
	v_cvt_pk_bf16_f32 v171, v158, v159
	global_store_dwordx4 v191, v[168:171], s[68:69] offset:256
	s_branch .LBB0_567
; template <class Epi>
; __device__ __forceinline__ void gemm_phase(LAS unsigned char* lds, const Gemm g, const Epi& E) {
;     ...
;       for (int ai = 0; ai < 2; ++ai)
; #pragma unroll
;         for (int m = 0; m < 4; ++m)
; #pragma unroll
;           for (int bj = 0; bj < 2; ++bj)
;           { E.st2(cur.w, cur.pm * BM + ai * HALF + wr * 64 + m * 16 + fr, cur.pn * BM + bj * HALF + wc * 32 + 8 * fq, acc[ai][bj][m][0], acc[ai][bj][m][1]); if (bj == 1 && (m & 1)) asm volatile("" ::: "memory"); }
.Lepi4:
	v_mul_u32_u24_e32 v176, 0x1800, v150
	v_lshl_add_u32 v176, v148, 1, v176
	v_add_u32_e32 v176, 0x1000, v176
	v_lshlrev_b32_e32 v184, 11, v150
	v_lshl_add_u32 v184, v148, 1, v184
	v_add_u32_e32 v177, 0x18000, v176
	v_add_u32_e32 v185, 0x8000, v184
	v_add_u32_e32 v178, 0x30000, v176
	v_add_u32_e32 v186, 0x10000, v184
	v_add_u32_e32 v179, 0x48000, v176
	v_add_u32_e32 v187, 0x18000, v184
	v_add_u32_e32 v180, 0xc0000, v176
	v_add_u32_e32 v188, 0x40000, v184
	v_add_u32_e32 v181, 0xd8000, v176
	v_add_u32_e32 v189, 0x48000, v184
	v_add_u32_e32 v182, 0xf0000, v176
	v_add_u32_e32 v190, 0x50000, v184
	v_add_u32_e32 v183, 0x108000, v176
	v_add_u32_e32 v191, 0x58000, v184
	global_load_dwordx4 v[192:195], v176, s[64:65]
	global_load_dwordx4 v[196:199], v184, s[68:69]
	global_load_dwordx4 v[200:203], v176, s[64:65] offset:256
	global_load_dwordx4 v[204:207], v184, s[68:69] offset:256
	global_load_dwordx4 v[208:211], v177, s[64:65]
	global_load_dwordx4 v[212:215], v185, s[68:69]
	global_load_dwordx4 v[216:219], v177, s[64:65] offset:256
	global_load_dwordx4 v[220:223], v185, s[68:69] offset:256
	s_waitcnt vmcnt(6)
	v_lshlrev_b32_e32 v152, 16, v192
	v_and_b32_e32 v153, 0xffff0000, v192
	v_lshlrev_b32_e32 v154, 16, v193
	v_and_b32_e32 v155, 0xffff0000, v193
	v_lshlrev_b32_e32 v156, 16, v194
	v_and_b32_e32 v157, 0xffff0000, v194
	v_lshlrev_b32_e32 v158, 16, v195
	v_and_b32_e32 v159, 0xffff0000, v195
	v_mul_f32_e32 v152, 0xbfb8aa3b, v152
	v_mul_f32_e32 v153, 0xbfb8aa3b, v153
	v_mul_f32_e32 v154, 0xbfb8aa3b, v154
	v_mul_f32_e32 v155, 0xbfb8aa3b, v155
	v_mul_f32_e32 v156, 0xbfb8aa3b, v156
	v_mul_f32_e32 v157, 0xbfb8aa3b, v157
	v_mul_f32_e32 v158, 0xbfb8aa3b, v158
	v_mul_f32_e32 v159, 0xbfb8aa3b, v159
	v_exp_f32_e32 v152, v152
	v_exp_f32_e32 v153, v153
	v_exp_f32_e32 v154, v154
	v_exp_f32_e32 v155, v155
	v_exp_f32_e32 v156, v156
	v_exp_f32_e32 v157, v157
	v_exp_f32_e32 v158, v158
	v_exp_f32_e32 v159, v159
	v_pk_add_f32 v[152:153], v[152:153], 1.0 op_sel_hi:[1,0]
	v_pk_add_f32 v[154:155], v[154:155], 1.0 op_sel_hi:[1,0]
	v_pk_add_f32 v[156:157], v[156:157], 1.0 op_sel_hi:[1,0]
	v_pk_add_f32 v[158:159], v[158:159], 1.0 op_sel_hi:[1,0]
	v_div_scale_f32 v160, s[2:3], v152, v152, 1.0
	v_rcp_f32_e32 v161, v160
	s_nop 0
	v_fma_f32 v162, -v160, v161, 1.0
	v_fmac_f32_e32 v161, v162, v161
	v_div_scale_f32 v163, vcc, 1.0, v152, 1.0
	v_mul_f32_e32 v164, v163, v161
	v_div_scale_f32 v128, s[2:3], v153, v153, 1.0
	v_fma_f32 v162, -v160, v164, v163
	v_rcp_f32_e32 v129, v128
	v_fmac_f32_e32 v164, v162, v161
	s_nop 0
	v_fma_f32 v160, -v160, v164, v163
	v_fma_f32 v130, -v128, v129, 1.0
	v_div_fmas_f32 v160, v160, v161, v164
	v_fmac_f32_e32 v129, v130, v129
	v_div_fixup_f32 v152, v160, v152, 1.0
	v_div_scale_f32 v131, vcc, 1.0, v153, 1.0
	v_mul_f32_e32 v165, v131, v129
	v_div_scale_f32 v160, s[2:3], v154, v154, 1.0
	v_fma_f32 v130, -v128, v165, v131
	v_rcp_f32_e32 v161, v160
	v_fmac_f32_e32 v165, v130, v129
	s_nop 0
	v_fma_f32 v128, -v128, v165, v131
	v_fma_f32 v162, -v160, v161, 1.0
	v_div_fmas_f32 v128, v128, v129, v165
	v_fmac_f32_e32 v161, v162, v161
	v_div_fixup_f32 v153, v128, v153, 1.0
	v_div_scale_f32 v163, vcc, 1.0, v154, 1.0
	v_mul_f32_e32 v164, v163, v161
	v_div_scale_f32 v128, s[2:3], v155, v155, 1.0
	v_fma_f32 v162, -v160, v164, v163
	v_rcp_f32_e32 v129, v128
	v_fmac_f32_e32 v164, v162, v161
	s_nop 0
	v_fma_f32 v160, -v160, v164, v163
	v_fma_f32 v130, -v128, v129, 1.0
	v_div_fmas_f32 v160, v160, v161, v164
	v_fmac_f32_e32 v129, v130, v129
	v_div_fixup_f32 v154, v160, v154, 1.0
	v_div_scale_f32 v131, vcc, 1.0, v155, 1.0
	v_mul_f32_e32 v165, v131, v129
	v_div_scale_f32 v160, s[2:3], v156, v156, 1.0
	v_fma_f32 v130, -v128, v165, v131
	v_rcp_f32_e32 v161, v160
	v_fmac_f32_e32 v165, v130, v129
	s_nop 0
	v_fma_f32 v128, -v128, v165, v131
	v_fma_f32 v162, -v160, v161, 1.0
	v_div_fmas_f32 v128, v128, v129, v165
	v_fmac_f32_e32 v161, v162, v161
	v_div_fixup_f32 v155, v128, v155, 1.0
	v_div_scale_f32 v163, vcc, 1.0, v156, 1.0
	v_mul_f32_e32 v164, v163, v161
	v_div_scale_f32 v128, s[2:3], v157, v157, 1.0
	v_fma_f32 v162, -v160, v164, v163
	v_rcp_f32_e32 v129, v128
	v_fmac_f32_e32 v164, v162, v161
	s_nop 0
	v_fma_f32 v160, -v160, v164, v163
	v_fma_f32 v130, -v128, v129, 1.0
	v_div_fmas_f32 v160, v160, v161, v164
	v_fmac_f32_e32 v129, v130, v129
	v_div_fixup_f32 v156, v160, v156, 1.0
	v_div_scale_f32 v131, vcc, 1.0, v157, 1.0
	v_mul_f32_e32 v165, v131, v129
	v_div_scale_f32 v160, s[2:3], v158, v158, 1.0
	v_fma_f32 v130, -v128, v165, v131
	v_rcp_f32_e32 v161, v160
	v_fmac_f32_e32 v165, v130, v129
	s_nop 0
	v_fma_f32 v128, -v128, v165, v131
	v_fma_f32 v162, -v160, v161, 1.0
	v_div_fmas_f32 v128, v128, v129, v165
	v_fmac_f32_e32 v161, v162, v161
	v_div_fixup_f32 v157, v128, v157, 1.0
	v_div_scale_f32 v163, vcc, 1.0, v158, 1.0
	v_mul_f32_e32 v164, v163, v161
	v_div_scale_f32 v128, s[2:3], v159, v159, 1.0
	v_fma_f32 v162, -v160, v164, v163
	v_rcp_f32_e32 v129, v128
	v_fmac_f32_e32 v164, v162, v161
	s_nop 0
	v_fma_f32 v160, -v160, v164, v163
	v_fma_f32 v130, -v128, v129, 1.0
	v_div_fmas_f32 v160, v160, v161, v164
	v_fmac_f32_e32 v129, v130, v129
	v_div_fixup_f32 v158, v160, v158, 1.0
	v_div_scale_f32 v131, vcc, 1.0, v159, 1.0
	v_mul_f32_e32 v165, v131, v129
	v_fma_f32 v130, -v128, v165, v131
	v_fmac_f32_e32 v165, v130, v129
	v_fma_f32 v128, -v128, v165, v131
	v_div_fmas_f32 v128, v128, v129, v165
	v_div_fixup_f32 v159, v128, v159, 1.0
	v_lshlrev_b32_e32 v166, 16, v196
	v_and_b32_e32 v167, 0xffff0000, v196
	v_pk_fma_f32 v[152:153], v[124:125], v[152:153], v[166:167]
	v_lshlrev_b32_e32 v166, 16, v197
	v_and_b32_e32 v167, 0xffff0000, v197
	v_pk_fma_f32 v[154:155], v[126:127], v[154:155], v[166:167]
	v_lshlrev_b32_e32 v166, 16, v198
	v_and_b32_e32 v167, 0xffff0000, v198
	v_pk_fma_f32 v[156:157], v[120:121], v[156:157], v[166:167]
	v_lshlrev_b32_e32 v166, 16, v199
	v_and_b32_e32 v167, 0xffff0000, v199
	v_pk_fma_f32 v[158:159], v[122:123], v[158:159], v[166:167]
	v_cvt_pk_bf16_f32 v168, v152, v153
	v_cvt_pk_bf16_f32 v169, v154, v155
	v_cvt_pk_bf16_f32 v170, v156, v157
	v_cvt_pk_bf16_f32 v171, v158, v159
	global_store_dwordx4 v184, v[168:171], s[66:67]
	global_load_dwordx4 v[124:127], v178, s[64:65]
	global_load_dwordx4 v[120:123], v186, s[68:69]
	s_waitcnt vmcnt(7)
	v_lshlrev_b32_e32 v152, 16, v200
	v_and_b32_e32 v153, 0xffff0000, v200
	v_lshlrev_b32_e32 v154, 16, v201
	v_and_b32_e32 v155, 0xffff0000, v201
	v_lshlrev_b32_e32 v156, 16, v202
	v_and_b32_e32 v157, 0xffff0000, v202
	v_lshlrev_b32_e32 v158, 16, v203
	v_and_b32_e32 v159, 0xffff0000, v203
	v_mul_f32_e32 v152, 0xbfb8aa3b, v152
	v_mul_f32_e32 v153, 0xbfb8aa3b, v153
	v_mul_f32_e32 v154, 0xbfb8aa3b, v154
	v_mul_f32_e32 v155, 0xbfb8aa3b, v155
	v_mul_f32_e32 v156, 0xbfb8aa3b, v156
	v_mul_f32_e32 v157, 0xbfb8aa3b, v157
	v_mul_f32_e32 v158, 0xbfb8aa3b, v158
	v_mul_f32_e32 v159, 0xbfb8aa3b, v159
	v_exp_f32_e32 v152, v152
	v_exp_f32_e32 v153, v153
	v_exp_f32_e32 v154, v154
	v_exp_f32_e32 v155, v155
	v_exp_f32_e32 v156, v156
	v_exp_f32_e32 v157, v157
	v_exp_f32_e32 v158, v158
	v_exp_f32_e32 v159, v159
	v_pk_add_f32 v[152:153], v[152:153], 1.0 op_sel_hi:[1,0]
	v_pk_add_f32 v[154:155], v[154:155], 1.0 op_sel_hi:[1,0]
	v_pk_add_f32 v[156:157], v[156:157], 1.0 op_sel_hi:[1,0]
	v_pk_add_f32 v[158:159], v[158:159], 1.0 op_sel_hi:[1,0]
	v_div_scale_f32 v160, s[2:3], v152, v152, 1.0
	v_rcp_f32_e32 v161, v160
	s_nop 0
	v_fma_f32 v162, -v160, v161, 1.0
	v_fmac_f32_e32 v161, v162, v161
	v_div_scale_f32 v163, vcc, 1.0, v152, 1.0
	v_mul_f32_e32 v164, v163, v161
	v_div_scale_f32 v128, s[2:3], v153, v153, 1.0
	v_fma_f32 v162, -v160, v164, v163
	v_rcp_f32_e32 v129, v128
	v_fmac_f32_e32 v164, v162, v161
	s_nop 0
	v_fma_f32 v160, -v160, v164, v163
	v_fma_f32 v130, -v128, v129, 1.0
	v_div_fmas_f32 v160, v160, v161, v164
	v_fmac_f32_e32 v129, v130, v129
	v_div_fixup_f32 v152, v160, v152, 1.0
	v_div_scale_f32 v131, vcc, 1.0, v153, 1.0
	v_mul_f32_e32 v165, v131, v129
	v_div_scale_f32 v160, s[2:3], v154, v154, 1.0
	v_fma_f32 v130, -v128, v165, v131
	v_rcp_f32_e32 v161, v160
	v_fmac_f32_e32 v165, v130, v129
	s_nop 0
	v_fma_f32 v128, -v128, v165, v131
	v_fma_f32 v162, -v160, v161, 1.0
	v_div_fmas_f32 v128, v128, v129, v165
	v_fmac_f32_e32 v161, v162, v161
	v_div_fixup_f32 v153, v128, v153, 1.0
	v_div_scale_f32 v163, vcc, 1.0, v154, 1.0
	v_mul_f32_e32 v164, v163, v161
	v_div_scale_f32 v128, s[2:3], v155, v155, 1.0
	v_fma_f32 v162, -v160, v164, v163
	v_rcp_f32_e32 v129, v128
	v_fmac_f32_e32 v164, v162, v161
	s_nop 0
	v_fma_f32 v160, -v160, v164, v163
	v_fma_f32 v130, -v128, v129, 1.0
	v_div_fmas_f32 v160, v160, v161, v164
	v_fmac_f32_e32 v129, v130, v129
	v_div_fixup_f32 v154, v160, v154, 1.0
	v_div_scale_f32 v131, vcc, 1.0, v155, 1.0
	v_mul_f32_e32 v165, v131, v129
	v_div_scale_f32 v160, s[2:3], v156, v156, 1.0
	v_fma_f32 v130, -v128, v165, v131
	v_rcp_f32_e32 v161, v160
	v_fmac_f32_e32 v165, v130, v129
	s_nop 0
	v_fma_f32 v128, -v128, v165, v131
	v_fma_f32 v162, -v160, v161, 1.0
	v_div_fmas_f32 v128, v128, v129, v165
	v_fmac_f32_e32 v161, v162, v161
	v_div_fixup_f32 v155, v128, v155, 1.0
	v_div_scale_f32 v163, vcc, 1.0, v156, 1.0
	v_mul_f32_e32 v164, v163, v161
	v_div_scale_f32 v128, s[2:3], v157, v157, 1.0
	v_fma_f32 v162, -v160, v164, v163
	v_rcp_f32_e32 v129, v128
	v_fmac_f32_e32 v164, v162, v161
	s_nop 0
	v_fma_f32 v160, -v160, v164, v163
	v_fma_f32 v130, -v128, v129, 1.0
	v_div_fmas_f32 v160, v160, v161, v164
	v_fmac_f32_e32 v129, v130, v129
	v_div_fixup_f32 v156, v160, v156, 1.0
	v_div_scale_f32 v131, vcc, 1.0, v157, 1.0
	v_mul_f32_e32 v165, v131, v129
	v_div_scale_f32 v160, s[2:3], v158, v158, 1.0
	v_fma_f32 v130, -v128, v165, v131
	v_rcp_f32_e32 v161, v160
	v_fmac_f32_e32 v165, v130, v129
	s_nop 0
	v_fma_f32 v128, -v128, v165, v131
	v_fma_f32 v162, -v160, v161, 1.0
	v_div_fmas_f32 v128, v128, v129, v165
	v_fmac_f32_e32 v161, v162, v161
	v_div_fixup_f32 v157, v128, v157, 1.0
	v_div_scale_f32 v163, vcc, 1.0, v158, 1.0
	v_mul_f32_e32 v164, v163, v161
	v_div_scale_f32 v128, s[2:3], v159, v159, 1.0
	v_fma_f32 v162, -v160, v164, v163
	v_rcp_f32_e32 v129, v128
	v_fmac_f32_e32 v164, v162, v161
	s_nop 0
	v_fma_f32 v160, -v160, v164, v163
	v_fma_f32 v130, -v128, v129, 1.0
	v_div_fmas_f32 v160, v160, v161, v164
	v_fmac_f32_e32 v129, v130, v129
	v_div_fixup_f32 v158, v160, v158, 1.0
	v_div_scale_f32 v131, vcc, 1.0, v159, 1.0
	v_mul_f32_e32 v165, v131, v129
	v_fma_f32 v130, -v128, v165, v131
	v_fmac_f32_e32 v165, v130, v129
	v_fma_f32 v128, -v128, v165, v131
	v_div_fmas_f32 v128, v128, v129, v165
	v_div_fixup_f32 v159, v128, v159, 1.0
	v_lshlrev_b32_e32 v166, 16, v204
	v_and_b32_e32 v167, 0xffff0000, v204
	v_pk_fma_f32 v[152:153], v[116:117], v[152:153], v[166:167]
	v_lshlrev_b32_e32 v166, 16, v205
	v_and_b32_e32 v167, 0xffff0000, v205
	v_pk_fma_f32 v[154:155], v[118:119], v[154:155], v[166:167]
	v_lshlrev_b32_e32 v166, 16, v206
	v_and_b32_e32 v167, 0xffff0000, v206
	v_pk_fma_f32 v[156:157], v[112:113], v[156:157], v[166:167]
	v_lshlrev_b32_e32 v166, 16, v207
	v_and_b32_e32 v167, 0xffff0000, v207
	v_pk_fma_f32 v[158:159], v[114:115], v[158:159], v[166:167]
	v_cvt_pk_bf16_f32 v168, v152, v153
	v_cvt_pk_bf16_f32 v169, v154, v155
	v_cvt_pk_bf16_f32 v170, v156, v157
	v_cvt_pk_bf16_f32 v171, v158, v159
	global_store_dwordx4 v184, v[168:171], s[66:67] offset:256
	global_load_dwordx4 v[116:119], v178, s[64:65] offset:256
	global_load_dwordx4 v[112:115], v186, s[68:69] offset:256
	s_waitcnt vmcnt(8)
	v_lshlrev_b32_e32 v152, 16, v208
	v_and_b32_e32 v153, 0xffff0000, v208
	v_lshlrev_b32_e32 v154, 16, v209
	v_and_b32_e32 v155, 0xffff0000, v209
	v_lshlrev_b32_e32 v156, 16, v210
	v_and_b32_e32 v157, 0xffff0000, v210
	v_lshlrev_b32_e32 v158, 16, v211
	v_and_b32_e32 v159, 0xffff0000, v211
	v_mul_f32_e32 v152, 0xbfb8aa3b, v152
	v_mul_f32_e32 v153, 0xbfb8aa3b, v153
	v_mul_f32_e32 v154, 0xbfb8aa3b, v154
	v_mul_f32_e32 v155, 0xbfb8aa3b, v155
	v_mul_f32_e32 v156, 0xbfb8aa3b, v156
	v_mul_f32_e32 v157, 0xbfb8aa3b, v157
	v_mul_f32_e32 v158, 0xbfb8aa3b, v158
	v_mul_f32_e32 v159, 0xbfb8aa3b, v159
	v_exp_f32_e32 v152, v152
	v_exp_f32_e32 v153, v153
	v_exp_f32_e32 v154, v154
	v_exp_f32_e32 v155, v155
	v_exp_f32_e32 v156, v156
	v_exp_f32_e32 v157, v157
	v_exp_f32_e32 v158, v158
	v_exp_f32_e32 v159, v159
	v_pk_add_f32 v[152:153], v[152:153], 1.0 op_sel_hi:[1,0]
	v_pk_add_f32 v[154:155], v[154:155], 1.0 op_sel_hi:[1,0]
	v_pk_add_f32 v[156:157], v[156:157], 1.0 op_sel_hi:[1,0]
	v_pk_add_f32 v[158:159], v[158:159], 1.0 op_sel_hi:[1,0]
	v_div_scale_f32 v160, s[2:3], v152, v152, 1.0
	v_rcp_f32_e32 v161, v160
	s_nop 0
	v_fma_f32 v162, -v160, v161, 1.0
	v_fmac_f32_e32 v161, v162, v161
	v_div_scale_f32 v163, vcc, 1.0, v152, 1.0
	v_mul_f32_e32 v164, v163, v161
	v_div_scale_f32 v128, s[2:3], v153, v153, 1.0
	v_fma_f32 v162, -v160, v164, v163
	v_rcp_f32_e32 v129, v128
	v_fmac_f32_e32 v164, v162, v161
	s_nop 0
	v_fma_f32 v160, -v160, v164, v163
	v_fma_f32 v130, -v128, v129, 1.0
	v_div_fmas_f32 v160, v160, v161, v164
	v_fmac_f32_e32 v129, v130, v129
	v_div_fixup_f32 v152, v160, v152, 1.0
	v_div_scale_f32 v131, vcc, 1.0, v153, 1.0
	v_mul_f32_e32 v165, v131, v129
	v_div_scale_f32 v160, s[2:3], v154, v154, 1.0
	v_fma_f32 v130, -v128, v165, v131
	v_rcp_f32_e32 v161, v160
	v_fmac_f32_e32 v165, v130, v129
	s_nop 0
	v_fma_f32 v128, -v128, v165, v131
	v_fma_f32 v162, -v160, v161, 1.0
	v_div_fmas_f32 v128, v128, v129, v165
	v_fmac_f32_e32 v161, v162, v161
	v_div_fixup_f32 v153, v128, v153, 1.0
	v_div_scale_f32 v163, vcc, 1.0, v154, 1.0
	v_mul_f32_e32 v164, v163, v161
	v_div_scale_f32 v128, s[2:3], v155, v155, 1.0
	v_fma_f32 v162, -v160, v164, v163
	v_rcp_f32_e32 v129, v128
	v_fmac_f32_e32 v164, v162, v161
	s_nop 0
	v_fma_f32 v160, -v160, v164, v163
	v_fma_f32 v130, -v128, v129, 1.0
	v_div_fmas_f32 v160, v160, v161, v164
	v_fmac_f32_e32 v129, v130, v129
	v_div_fixup_f32 v154, v160, v154, 1.0
	v_div_scale_f32 v131, vcc, 1.0, v155, 1.0
	v_mul_f32_e32 v165, v131, v129
	v_div_scale_f32 v160, s[2:3], v156, v156, 1.0
	v_fma_f32 v130, -v128, v165, v131
	v_rcp_f32_e32 v161, v160
	v_fmac_f32_e32 v165, v130, v129
	s_nop 0
	v_fma_f32 v128, -v128, v165, v131
	v_fma_f32 v162, -v160, v161, 1.0
	v_div_fmas_f32 v128, v128, v129, v165
	v_fmac_f32_e32 v161, v162, v161
	v_div_fixup_f32 v155, v128, v155, 1.0
	v_div_scale_f32 v163, vcc, 1.0, v156, 1.0
	v_mul_f32_e32 v164, v163, v161
	v_div_scale_f32 v128, s[2:3], v157, v157, 1.0
	v_fma_f32 v162, -v160, v164, v163
	v_rcp_f32_e32 v129, v128
	v_fmac_f32_e32 v164, v162, v161
	s_nop 0
	v_fma_f32 v160, -v160, v164, v163
	v_fma_f32 v130, -v128, v129, 1.0
	v_div_fmas_f32 v160, v160, v161, v164
	v_fmac_f32_e32 v129, v130, v129
	v_div_fixup_f32 v156, v160, v156, 1.0
	v_div_scale_f32 v131, vcc, 1.0, v157, 1.0
	v_mul_f32_e32 v165, v131, v129
	v_div_scale_f32 v160, s[2:3], v158, v158, 1.0
	v_fma_f32 v130, -v128, v165, v131
	v_rcp_f32_e32 v161, v160
	v_fmac_f32_e32 v165, v130, v129
	s_nop 0
	v_fma_f32 v128, -v128, v165, v131
	v_fma_f32 v162, -v160, v161, 1.0
	v_div_fmas_f32 v128, v128, v129, v165
	v_fmac_f32_e32 v161, v162, v161
	v_div_fixup_f32 v157, v128, v157, 1.0
	v_div_scale_f32 v163, vcc, 1.0, v158, 1.0
	v_mul_f32_e32 v164, v163, v161
	v_div_scale_f32 v128, s[2:3], v159, v159, 1.0
	v_fma_f32 v162, -v160, v164, v163
	v_rcp_f32_e32 v129, v128
	v_fmac_f32_e32 v164, v162, v161
	s_nop 0
	v_fma_f32 v160, -v160, v164, v163
	v_fma_f32 v130, -v128, v129, 1.0
	v_div_fmas_f32 v160, v160, v161, v164
	v_fmac_f32_e32 v129, v130, v129
	v_div_fixup_f32 v158, v160, v158, 1.0
	v_div_scale_f32 v131, vcc, 1.0, v159, 1.0
	v_mul_f32_e32 v165, v131, v129
	v_fma_f32 v130, -v128, v165, v131
	v_fmac_f32_e32 v165, v130, v129
	v_fma_f32 v128, -v128, v165, v131
	v_div_fmas_f32 v128, v128, v129, v165
	v_div_fixup_f32 v159, v128, v159, 1.0
	v_lshlrev_b32_e32 v166, 16, v212
	v_and_b32_e32 v167, 0xffff0000, v212
	v_pk_fma_f32 v[152:153], v[108:109], v[152:153], v[166:167]
	v_lshlrev_b32_e32 v166, 16, v213
	v_and_b32_e32 v167, 0xffff0000, v213
	v_pk_fma_f32 v[154:155], v[110:111], v[154:155], v[166:167]
	v_lshlrev_b32_e32 v166, 16, v214
	v_and_b32_e32 v167, 0xffff0000, v214
	v_pk_fma_f32 v[156:157], v[104:105], v[156:157], v[166:167]
	v_lshlrev_b32_e32 v166, 16, v215
	v_and_b32_e32 v167, 0xffff0000, v215
	v_pk_fma_f32 v[158:159], v[106:107], v[158:159], v[166:167]
	v_cvt_pk_bf16_f32 v168, v152, v153
	v_cvt_pk_bf16_f32 v169, v154, v155
	v_cvt_pk_bf16_f32 v170, v156, v157
	v_cvt_pk_bf16_f32 v171, v158, v159
	global_store_dwordx4 v185, v[168:171], s[66:67]
	global_load_dwordx4 v[108:111], v179, s[64:65]
	global_load_dwordx4 v[104:107], v187, s[68:69]
	s_waitcnt vmcnt(9)
	v_lshlrev_b32_e32 v152, 16, v216
	v_and_b32_e32 v153, 0xffff0000, v216
	v_lshlrev_b32_e32 v154, 16, v217
	v_and_b32_e32 v155, 0xffff0000, v217
	v_lshlrev_b32_e32 v156, 16, v218
	v_and_b32_e32 v157, 0xffff0000, v218
	v_lshlrev_b32_e32 v158, 16, v219
	v_and_b32_e32 v159, 0xffff0000, v219
	v_mul_f32_e32 v152, 0xbfb8aa3b, v152
	v_mul_f32_e32 v153, 0xbfb8aa3b, v153
	v_mul_f32_e32 v154, 0xbfb8aa3b, v154
	v_mul_f32_e32 v155, 0xbfb8aa3b, v155
	v_mul_f32_e32 v156, 0xbfb8aa3b, v156
	v_mul_f32_e32 v157, 0xbfb8aa3b, v157
	v_mul_f32_e32 v158, 0xbfb8aa3b, v158
	v_mul_f32_e32 v159, 0xbfb8aa3b, v159
	v_exp_f32_e32 v152, v152
	v_exp_f32_e32 v153, v153
	v_exp_f32_e32 v154, v154
	v_exp_f32_e32 v155, v155
	v_exp_f32_e32 v156, v156
	v_exp_f32_e32 v157, v157
	v_exp_f32_e32 v158, v158
	v_exp_f32_e32 v159, v159
	v_pk_add_f32 v[152:153], v[152:153], 1.0 op_sel_hi:[1,0]
	v_pk_add_f32 v[154:155], v[154:155], 1.0 op_sel_hi:[1,0]
	v_pk_add_f32 v[156:157], v[156:157], 1.0 op_sel_hi:[1,0]
	v_pk_add_f32 v[158:159], v[158:159], 1.0 op_sel_hi:[1,0]
	v_div_scale_f32 v160, s[2:3], v152, v152, 1.0
	v_rcp_f32_e32 v161, v160
	s_nop 0
	v_fma_f32 v162, -v160, v161, 1.0
	v_fmac_f32_e32 v161, v162, v161
	v_div_scale_f32 v163, vcc, 1.0, v152, 1.0
	v_mul_f32_e32 v164, v163, v161
	v_div_scale_f32 v128, s[2:3], v153, v153, 1.0
	v_fma_f32 v162, -v160, v164, v163
	v_rcp_f32_e32 v129, v128
	v_fmac_f32_e32 v164, v162, v161
	s_nop 0
	v_fma_f32 v160, -v160, v164, v163
	v_fma_f32 v130, -v128, v129, 1.0
	v_div_fmas_f32 v160, v160, v161, v164
	v_fmac_f32_e32 v129, v130, v129
	v_div_fixup_f32 v152, v160, v152, 1.0
	v_div_scale_f32 v131, vcc, 1.0, v153, 1.0
	v_mul_f32_e32 v165, v131, v129
	v_div_scale_f32 v160, s[2:3], v154, v154, 1.0
	v_fma_f32 v130, -v128, v165, v131
	v_rcp_f32_e32 v161, v160
	v_fmac_f32_e32 v165, v130, v129
	s_nop 0
	v_fma_f32 v128, -v128, v165, v131
	v_fma_f32 v162, -v160, v161, 1.0
	v_div_fmas_f32 v128, v128, v129, v165
	v_fmac_f32_e32 v161, v162, v161
	v_div_fixup_f32 v153, v128, v153, 1.0
	v_div_scale_f32 v163, vcc, 1.0, v154, 1.0
	v_mul_f32_e32 v164, v163, v161
	v_div_scale_f32 v128, s[2:3], v155, v155, 1.0
	v_fma_f32 v162, -v160, v164, v163
	v_rcp_f32_e32 v129, v128
	v_fmac_f32_e32 v164, v162, v161
	s_nop 0
	v_fma_f32 v160, -v160, v164, v163
	v_fma_f32 v130, -v128, v129, 1.0
	v_div_fmas_f32 v160, v160, v161, v164
	v_fmac_f32_e32 v129, v130, v129
	v_div_fixup_f32 v154, v160, v154, 1.0
	v_div_scale_f32 v131, vcc, 1.0, v155, 1.0
	v_mul_f32_e32 v165, v131, v129
	v_div_scale_f32 v160, s[2:3], v156, v156, 1.0
	v_fma_f32 v130, -v128, v165, v131
	v_rcp_f32_e32 v161, v160
	v_fmac_f32_e32 v165, v130, v129
	s_nop 0
	v_fma_f32 v128, -v128, v165, v131
	v_fma_f32 v162, -v160, v161, 1.0
	v_div_fmas_f32 v128, v128, v129, v165
	v_fmac_f32_e32 v161, v162, v161
	v_div_fixup_f32 v155, v128, v155, 1.0
	v_div_scale_f32 v163, vcc, 1.0, v156, 1.0
	v_mul_f32_e32 v164, v163, v161
	v_div_scale_f32 v128, s[2:3], v157, v157, 1.0
	v_fma_f32 v162, -v160, v164, v163
	v_rcp_f32_e32 v129, v128
	v_fmac_f32_e32 v164, v162, v161
	s_nop 0
	v_fma_f32 v160, -v160, v164, v163
	v_fma_f32 v130, -v128, v129, 1.0
	v_div_fmas_f32 v160, v160, v161, v164
	v_fmac_f32_e32 v129, v130, v129
	v_div_fixup_f32 v156, v160, v156, 1.0
	v_div_scale_f32 v131, vcc, 1.0, v157, 1.0
	v_mul_f32_e32 v165, v131, v129
	v_div_scale_f32 v160, s[2:3], v158, v158, 1.0
	v_fma_f32 v130, -v128, v165, v131
	v_rcp_f32_e32 v161, v160
	v_fmac_f32_e32 v165, v130, v129
	s_nop 0
	v_fma_f32 v128, -v128, v165, v131
	v_fma_f32 v162, -v160, v161, 1.0
	v_div_fmas_f32 v128, v128, v129, v165
	v_fmac_f32_e32 v161, v162, v161
	v_div_fixup_f32 v157, v128, v157, 1.0
	v_div_scale_f32 v163, vcc, 1.0, v158, 1.0
	v_mul_f32_e32 v164, v163, v161
	v_div_scale_f32 v128, s[2:3], v159, v159, 1.0
	v_fma_f32 v162, -v160, v164, v163
	v_rcp_f32_e32 v129, v128
	v_fmac_f32_e32 v164, v162, v161
	s_nop 0
	v_fma_f32 v160, -v160, v164, v163
	v_fma_f32 v130, -v128, v129, 1.0
	v_div_fmas_f32 v160, v160, v161, v164
	v_fmac_f32_e32 v129, v130, v129
	v_div_fixup_f32 v158, v160, v158, 1.0
	v_div_scale_f32 v131, vcc, 1.0, v159, 1.0
	v_mul_f32_e32 v165, v131, v129
	v_fma_f32 v130, -v128, v165, v131
	v_fmac_f32_e32 v165, v130, v129
	v_fma_f32 v128, -v128, v165, v131
	v_div_fmas_f32 v128, v128, v129, v165
	v_div_fixup_f32 v159, v128, v159, 1.0
	v_lshlrev_b32_e32 v166, 16, v220
	v_and_b32_e32 v167, 0xffff0000, v220
	v_pk_fma_f32 v[152:153], v[100:101], v[152:153], v[166:167]
	v_lshlrev_b32_e32 v166, 16, v221
	v_and_b32_e32 v167, 0xffff0000, v221
	v_pk_fma_f32 v[154:155], v[102:103], v[154:155], v[166:167]
	v_lshlrev_b32_e32 v166, 16, v222
	v_and_b32_e32 v167, 0xffff0000, v222
	v_pk_fma_f32 v[156:157], v[96:97], v[156:157], v[166:167]
	v_lshlrev_b32_e32 v166, 16, v223
	v_and_b32_e32 v167, 0xffff0000, v223
	v_pk_fma_f32 v[158:159], v[98:99], v[158:159], v[166:167]
	v_cvt_pk_bf16_f32 v168, v152, v153
	v_cvt_pk_bf16_f32 v169, v154, v155
	v_cvt_pk_bf16_f32 v170, v156, v157
	v_cvt_pk_bf16_f32 v171, v158, v159
	global_store_dwordx4 v185, v[168:171], s[66:67] offset:256
	global_load_dwordx4 v[100:103], v179, s[64:65] offset:256
	global_load_dwordx4 v[96:99], v187, s[68:69] offset:256
	s_waitcnt vmcnt(9)
	v_lshlrev_b32_e32 v152, 16, v124
	v_and_b32_e32 v153, 0xffff0000, v124
	v_lshlrev_b32_e32 v154, 16, v125
	v_and_b32_e32 v155, 0xffff0000, v125
	v_lshlrev_b32_e32 v156, 16, v126
	v_and_b32_e32 v157, 0xffff0000, v126
	v_lshlrev_b32_e32 v158, 16, v127
	v_and_b32_e32 v159, 0xffff0000, v127
	v_mul_f32_e32 v152, 0xbfb8aa3b, v152
	v_mul_f32_e32 v153, 0xbfb8aa3b, v153
	v_mul_f32_e32 v154, 0xbfb8aa3b, v154
	v_mul_f32_e32 v155, 0xbfb8aa3b, v155
	v_mul_f32_e32 v156, 0xbfb8aa3b, v156
	v_mul_f32_e32 v157, 0xbfb8aa3b, v157
	v_mul_f32_e32 v158, 0xbfb8aa3b, v158
	v_mul_f32_e32 v159, 0xbfb8aa3b, v159
	v_exp_f32_e32 v152, v152
	v_exp_f32_e32 v153, v153
	v_exp_f32_e32 v154, v154
	v_exp_f32_e32 v155, v155
	v_exp_f32_e32 v156, v156
	v_exp_f32_e32 v157, v157
	v_exp_f32_e32 v158, v158
	v_exp_f32_e32 v159, v159
	v_pk_add_f32 v[152:153], v[152:153], 1.0 op_sel_hi:[1,0]
	v_pk_add_f32 v[154:155], v[154:155], 1.0 op_sel_hi:[1,0]
	v_pk_add_f32 v[156:157], v[156:157], 1.0 op_sel_hi:[1,0]
	v_pk_add_f32 v[158:159], v[158:159], 1.0 op_sel_hi:[1,0]
	v_div_scale_f32 v160, s[2:3], v152, v152, 1.0
	v_rcp_f32_e32 v161, v160
	s_nop 0
	v_fma_f32 v162, -v160, v161, 1.0
	v_fmac_f32_e32 v161, v162, v161
	v_div_scale_f32 v163, vcc, 1.0, v152, 1.0
	v_mul_f32_e32 v164, v163, v161
	v_div_scale_f32 v128, s[2:3], v153, v153, 1.0
	v_fma_f32 v162, -v160, v164, v163
	v_rcp_f32_e32 v129, v128
	v_fmac_f32_e32 v164, v162, v161
	s_nop 0
	v_fma_f32 v160, -v160, v164, v163
	v_fma_f32 v130, -v128, v129, 1.0
	v_div_fmas_f32 v160, v160, v161, v164
	v_fmac_f32_e32 v129, v130, v129
	v_div_fixup_f32 v152, v160, v152, 1.0
	v_div_scale_f32 v131, vcc, 1.0, v153, 1.0
	v_mul_f32_e32 v165, v131, v129
	v_div_scale_f32 v160, s[2:3], v154, v154, 1.0
	v_fma_f32 v130, -v128, v165, v131
	v_rcp_f32_e32 v161, v160
	v_fmac_f32_e32 v165, v130, v129
	s_nop 0
	v_fma_f32 v128, -v128, v165, v131
	v_fma_f32 v162, -v160, v161, 1.0
	v_div_fmas_f32 v128, v128, v129, v165
	v_fmac_f32_e32 v161, v162, v161
	v_div_fixup_f32 v153, v128, v153, 1.0
	v_div_scale_f32 v163, vcc, 1.0, v154, 1.0
	v_mul_f32_e32 v164, v163, v161
	v_div_scale_f32 v128, s[2:3], v155, v155, 1.0
	v_fma_f32 v162, -v160, v164, v163
	v_rcp_f32_e32 v129, v128
	v_fmac_f32_e32 v164, v162, v161
	s_nop 0
	v_fma_f32 v160, -v160, v164, v163
	v_fma_f32 v130, -v128, v129, 1.0
	v_div_fmas_f32 v160, v160, v161, v164
	v_fmac_f32_e32 v129, v130, v129
	v_div_fixup_f32 v154, v160, v154, 1.0
	v_div_scale_f32 v131, vcc, 1.0, v155, 1.0
	v_mul_f32_e32 v165, v131, v129
	v_div_scale_f32 v160, s[2:3], v156, v156, 1.0
	v_fma_f32 v130, -v128, v165, v131
	v_rcp_f32_e32 v161, v160
	v_fmac_f32_e32 v165, v130, v129
	s_nop 0
	v_fma_f32 v128, -v128, v165, v131
	v_fma_f32 v162, -v160, v161, 1.0
	v_div_fmas_f32 v128, v128, v129, v165
	v_fmac_f32_e32 v161, v162, v161
	v_div_fixup_f32 v155, v128, v155, 1.0
	v_div_scale_f32 v163, vcc, 1.0, v156, 1.0
	v_mul_f32_e32 v164, v163, v161
	v_div_scale_f32 v128, s[2:3], v157, v157, 1.0
	v_fma_f32 v162, -v160, v164, v163
	v_rcp_f32_e32 v129, v128
	v_fmac_f32_e32 v164, v162, v161
	s_nop 0
	v_fma_f32 v160, -v160, v164, v163
	v_fma_f32 v130, -v128, v129, 1.0
	v_div_fmas_f32 v160, v160, v161, v164
	v_fmac_f32_e32 v129, v130, v129
	v_div_fixup_f32 v156, v160, v156, 1.0
	v_div_scale_f32 v131, vcc, 1.0, v157, 1.0
	v_mul_f32_e32 v165, v131, v129
	v_div_scale_f32 v160, s[2:3], v158, v158, 1.0
	v_fma_f32 v130, -v128, v165, v131
	v_rcp_f32_e32 v161, v160
	v_fmac_f32_e32 v165, v130, v129
	s_nop 0
	v_fma_f32 v128, -v128, v165, v131
	v_fma_f32 v162, -v160, v161, 1.0
	v_div_fmas_f32 v128, v128, v129, v165
	v_fmac_f32_e32 v161, v162, v161
	v_div_fixup_f32 v157, v128, v157, 1.0
	v_div_scale_f32 v163, vcc, 1.0, v158, 1.0
	v_mul_f32_e32 v164, v163, v161
	v_div_scale_f32 v128, s[2:3], v159, v159, 1.0
	v_fma_f32 v162, -v160, v164, v163
	v_rcp_f32_e32 v129, v128
	v_fmac_f32_e32 v164, v162, v161
	s_nop 0
	v_fma_f32 v160, -v160, v164, v163
	v_fma_f32 v130, -v128, v129, 1.0
	v_div_fmas_f32 v160, v160, v161, v164
	v_fmac_f32_e32 v129, v130, v129
	v_div_fixup_f32 v158, v160, v158, 1.0
	v_div_scale_f32 v131, vcc, 1.0, v159, 1.0
	v_mul_f32_e32 v165, v131, v129
	v_fma_f32 v130, -v128, v165, v131
	v_fmac_f32_e32 v165, v130, v129
	v_fma_f32 v128, -v128, v165, v131
	v_div_fmas_f32 v128, v128, v129, v165
	v_div_fixup_f32 v159, v128, v159, 1.0
	v_lshlrev_b32_e32 v166, 16, v120
	v_and_b32_e32 v167, 0xffff0000, v120
	v_pk_fma_f32 v[152:153], v[92:93], v[152:153], v[166:167]
	v_lshlrev_b32_e32 v166, 16, v121
	v_and_b32_e32 v167, 0xffff0000, v121
	v_pk_fma_f32 v[154:155], v[94:95], v[154:155], v[166:167]
	v_lshlrev_b32_e32 v166, 16, v122
	v_and_b32_e32 v167, 0xffff0000, v122
	v_pk_fma_f32 v[156:157], v[88:89], v[156:157], v[166:167]
	v_lshlrev_b32_e32 v166, 16, v123
	v_and_b32_e32 v167, 0xffff0000, v123
	v_pk_fma_f32 v[158:159], v[90:91], v[158:159], v[166:167]
	v_cvt_pk_bf16_f32 v168, v152, v153
	v_cvt_pk_bf16_f32 v169, v154, v155
	v_cvt_pk_bf16_f32 v170, v156, v157
	v_cvt_pk_bf16_f32 v171, v158, v159
	global_store_dwordx4 v186, v[168:171], s[66:67]
	global_load_dwordx4 v[92:95], v180, s[64:65]
	global_load_dwordx4 v[88:91], v188, s[68:69]
	s_waitcnt vmcnt(9)
	v_lshlrev_b32_e32 v152, 16, v116
	v_and_b32_e32 v153, 0xffff0000, v116
	v_lshlrev_b32_e32 v154, 16, v117
	v_and_b32_e32 v155, 0xffff0000, v117
	v_lshlrev_b32_e32 v156, 16, v118
	v_and_b32_e32 v157, 0xffff0000, v118
	v_lshlrev_b32_e32 v158, 16, v119
	v_and_b32_e32 v159, 0xffff0000, v119
	v_mul_f32_e32 v152, 0xbfb8aa3b, v152
	v_mul_f32_e32 v153, 0xbfb8aa3b, v153
	v_mul_f32_e32 v154, 0xbfb8aa3b, v154
	v_mul_f32_e32 v155, 0xbfb8aa3b, v155
	v_mul_f32_e32 v156, 0xbfb8aa3b, v156
	v_mul_f32_e32 v157, 0xbfb8aa3b, v157
	v_mul_f32_e32 v158, 0xbfb8aa3b, v158
	v_mul_f32_e32 v159, 0xbfb8aa3b, v159
	v_exp_f32_e32 v152, v152
	v_exp_f32_e32 v153, v153
	v_exp_f32_e32 v154, v154
	v_exp_f32_e32 v155, v155
	v_exp_f32_e32 v156, v156
	v_exp_f32_e32 v157, v157
	v_exp_f32_e32 v158, v158
	v_exp_f32_e32 v159, v159
	v_pk_add_f32 v[152:153], v[152:153], 1.0 op_sel_hi:[1,0]
	v_pk_add_f32 v[154:155], v[154:155], 1.0 op_sel_hi:[1,0]
	v_pk_add_f32 v[156:157], v[156:157], 1.0 op_sel_hi:[1,0]
	v_pk_add_f32 v[158:159], v[158:159], 1.0 op_sel_hi:[1,0]
	v_div_scale_f32 v160, s[2:3], v152, v152, 1.0
	v_rcp_f32_e32 v161, v160
	s_nop 0
	v_fma_f32 v162, -v160, v161, 1.0
	v_fmac_f32_e32 v161, v162, v161
	v_div_scale_f32 v163, vcc, 1.0, v152, 1.0
	v_mul_f32_e32 v164, v163, v161
	v_div_scale_f32 v128, s[2:3], v153, v153, 1.0
	v_fma_f32 v162, -v160, v164, v163
	v_rcp_f32_e32 v129, v128
	v_fmac_f32_e32 v164, v162, v161
	s_nop 0
	v_fma_f32 v160, -v160, v164, v163
	v_fma_f32 v130, -v128, v129, 1.0
	v_div_fmas_f32 v160, v160, v161, v164
	v_fmac_f32_e32 v129, v130, v129
	v_div_fixup_f32 v152, v160, v152, 1.0
	v_div_scale_f32 v131, vcc, 1.0, v153, 1.0
	v_mul_f32_e32 v165, v131, v129
	v_div_scale_f32 v160, s[2:3], v154, v154, 1.0
	v_fma_f32 v130, -v128, v165, v131
	v_rcp_f32_e32 v161, v160
	v_fmac_f32_e32 v165, v130, v129
	s_nop 0
	v_fma_f32 v128, -v128, v165, v131
	v_fma_f32 v162, -v160, v161, 1.0
	v_div_fmas_f32 v128, v128, v129, v165
	v_fmac_f32_e32 v161, v162, v161
	v_div_fixup_f32 v153, v128, v153, 1.0
	v_div_scale_f32 v163, vcc, 1.0, v154, 1.0
	v_mul_f32_e32 v164, v163, v161
	v_div_scale_f32 v128, s[2:3], v155, v155, 1.0
	v_fma_f32 v162, -v160, v164, v163
	v_rcp_f32_e32 v129, v128
	v_fmac_f32_e32 v164, v162, v161
	s_nop 0
	v_fma_f32 v160, -v160, v164, v163
	v_fma_f32 v130, -v128, v129, 1.0
	v_div_fmas_f32 v160, v160, v161, v164
	v_fmac_f32_e32 v129, v130, v129
	v_div_fixup_f32 v154, v160, v154, 1.0
	v_div_scale_f32 v131, vcc, 1.0, v155, 1.0
	v_mul_f32_e32 v165, v131, v129
	v_div_scale_f32 v160, s[2:3], v156, v156, 1.0
	v_fma_f32 v130, -v128, v165, v131
	v_rcp_f32_e32 v161, v160
	v_fmac_f32_e32 v165, v130, v129
	s_nop 0
	v_fma_f32 v128, -v128, v165, v131
	v_fma_f32 v162, -v160, v161, 1.0
	v_div_fmas_f32 v128, v128, v129, v165
	v_fmac_f32_e32 v161, v162, v161
	v_div_fixup_f32 v155, v128, v155, 1.0
	v_div_scale_f32 v163, vcc, 1.0, v156, 1.0
	v_mul_f32_e32 v164, v163, v161
	v_div_scale_f32 v128, s[2:3], v157, v157, 1.0
	v_fma_f32 v162, -v160, v164, v163
	v_rcp_f32_e32 v129, v128
	v_fmac_f32_e32 v164, v162, v161
	s_nop 0
	v_fma_f32 v160, -v160, v164, v163
	v_fma_f32 v130, -v128, v129, 1.0
	v_div_fmas_f32 v160, v160, v161, v164
	v_fmac_f32_e32 v129, v130, v129
	v_div_fixup_f32 v156, v160, v156, 1.0
	v_div_scale_f32 v131, vcc, 1.0, v157, 1.0
	v_mul_f32_e32 v165, v131, v129
	v_div_scale_f32 v160, s[2:3], v158, v158, 1.0
	v_fma_f32 v130, -v128, v165, v131
	v_rcp_f32_e32 v161, v160
	v_fmac_f32_e32 v165, v130, v129
	s_nop 0
	v_fma_f32 v128, -v128, v165, v131
	v_fma_f32 v162, -v160, v161, 1.0
	v_div_fmas_f32 v128, v128, v129, v165
	v_fmac_f32_e32 v161, v162, v161
	v_div_fixup_f32 v157, v128, v157, 1.0
	v_div_scale_f32 v163, vcc, 1.0, v158, 1.0
	v_mul_f32_e32 v164, v163, v161
	v_div_scale_f32 v128, s[2:3], v159, v159, 1.0
	v_fma_f32 v162, -v160, v164, v163
	v_rcp_f32_e32 v129, v128
	v_fmac_f32_e32 v164, v162, v161
	s_nop 0
	v_fma_f32 v160, -v160, v164, v163
	v_fma_f32 v130, -v128, v129, 1.0
	v_div_fmas_f32 v160, v160, v161, v164
	v_fmac_f32_e32 v129, v130, v129
	v_div_fixup_f32 v158, v160, v158, 1.0
	v_div_scale_f32 v131, vcc, 1.0, v159, 1.0
	v_mul_f32_e32 v165, v131, v129
	v_fma_f32 v130, -v128, v165, v131
	v_fmac_f32_e32 v165, v130, v129
	v_fma_f32 v128, -v128, v165, v131
	v_div_fmas_f32 v128, v128, v129, v165
	v_div_fixup_f32 v159, v128, v159, 1.0
	v_lshlrev_b32_e32 v166, 16, v112
	v_and_b32_e32 v167, 0xffff0000, v112
	v_pk_fma_f32 v[152:153], v[84:85], v[152:153], v[166:167]
	v_lshlrev_b32_e32 v166, 16, v113
	v_and_b32_e32 v167, 0xffff0000, v113
	v_pk_fma_f32 v[154:155], v[86:87], v[154:155], v[166:167]
	v_lshlrev_b32_e32 v166, 16, v114
	v_and_b32_e32 v167, 0xffff0000, v114
	v_pk_fma_f32 v[156:157], v[80:81], v[156:157], v[166:167]
	v_lshlrev_b32_e32 v166, 16, v115
	v_and_b32_e32 v167, 0xffff0000, v115
	v_pk_fma_f32 v[158:159], v[82:83], v[158:159], v[166:167]
	v_cvt_pk_bf16_f32 v168, v152, v153
	v_cvt_pk_bf16_f32 v169, v154, v155
	v_cvt_pk_bf16_f32 v170, v156, v157
	v_cvt_pk_bf16_f32 v171, v158, v159
	global_store_dwordx4 v186, v[168:171], s[66:67] offset:256
	global_load_dwordx4 v[84:87], v180, s[64:65] offset:256
	global_load_dwordx4 v[80:83], v188, s[68:69] offset:256
	s_waitcnt vmcnt(9)
	v_lshlrev_b32_e32 v152, 16, v108
	v_and_b32_e32 v153, 0xffff0000, v108
	v_lshlrev_b32_e32 v154, 16, v109
	v_and_b32_e32 v155, 0xffff0000, v109
	v_lshlrev_b32_e32 v156, 16, v110
	v_and_b32_e32 v157, 0xffff0000, v110
	v_lshlrev_b32_e32 v158, 16, v111
	v_and_b32_e32 v159, 0xffff0000, v111
	v_mul_f32_e32 v152, 0xbfb8aa3b, v152
	v_mul_f32_e32 v153, 0xbfb8aa3b, v153
	v_mul_f32_e32 v154, 0xbfb8aa3b, v154
	v_mul_f32_e32 v155, 0xbfb8aa3b, v155
	v_mul_f32_e32 v156, 0xbfb8aa3b, v156
	v_mul_f32_e32 v157, 0xbfb8aa3b, v157
	v_mul_f32_e32 v158, 0xbfb8aa3b, v158
	v_mul_f32_e32 v159, 0xbfb8aa3b, v159
	v_exp_f32_e32 v152, v152
	v_exp_f32_e32 v153, v153
	v_exp_f32_e32 v154, v154
	v_exp_f32_e32 v155, v155
	v_exp_f32_e32 v156, v156
	v_exp_f32_e32 v157, v157
	v_exp_f32_e32 v158, v158
	v_exp_f32_e32 v159, v159
	v_pk_add_f32 v[152:153], v[152:153], 1.0 op_sel_hi:[1,0]
	v_pk_add_f32 v[154:155], v[154:155], 1.0 op_sel_hi:[1,0]
	v_pk_add_f32 v[156:157], v[156:157], 1.0 op_sel_hi:[1,0]
	v_pk_add_f32 v[158:159], v[158:159], 1.0 op_sel_hi:[1,0]
	v_div_scale_f32 v160, s[2:3], v152, v152, 1.0
	v_rcp_f32_e32 v161, v160
	s_nop 0
	v_fma_f32 v162, -v160, v161, 1.0
	v_fmac_f32_e32 v161, v162, v161
	v_div_scale_f32 v163, vcc, 1.0, v152, 1.0
	v_mul_f32_e32 v164, v163, v161
	v_div_scale_f32 v128, s[2:3], v153, v153, 1.0
	v_fma_f32 v162, -v160, v164, v163
	v_rcp_f32_e32 v129, v128
	v_fmac_f32_e32 v164, v162, v161
	s_nop 0
	v_fma_f32 v160, -v160, v164, v163
	v_fma_f32 v130, -v128, v129, 1.0
	v_div_fmas_f32 v160, v160, v161, v164
	v_fmac_f32_e32 v129, v130, v129
	v_div_fixup_f32 v152, v160, v152, 1.0
	v_div_scale_f32 v131, vcc, 1.0, v153, 1.0
	v_mul_f32_e32 v165, v131, v129
	v_div_scale_f32 v160, s[2:3], v154, v154, 1.0
	v_fma_f32 v130, -v128, v165, v131
	v_rcp_f32_e32 v161, v160
	v_fmac_f32_e32 v165, v130, v129
	s_nop 0
	v_fma_f32 v128, -v128, v165, v131
	v_fma_f32 v162, -v160, v161, 1.0
	v_div_fmas_f32 v128, v128, v129, v165
	v_fmac_f32_e32 v161, v162, v161
	v_div_fixup_f32 v153, v128, v153, 1.0
	v_div_scale_f32 v163, vcc, 1.0, v154, 1.0
	v_mul_f32_e32 v164, v163, v161
	v_div_scale_f32 v128, s[2:3], v155, v155, 1.0
	v_fma_f32 v162, -v160, v164, v163
	v_rcp_f32_e32 v129, v128
	v_fmac_f32_e32 v164, v162, v161
	s_nop 0
	v_fma_f32 v160, -v160, v164, v163
	v_fma_f32 v130, -v128, v129, 1.0
	v_div_fmas_f32 v160, v160, v161, v164
	v_fmac_f32_e32 v129, v130, v129
	v_div_fixup_f32 v154, v160, v154, 1.0
	v_div_scale_f32 v131, vcc, 1.0, v155, 1.0
	v_mul_f32_e32 v165, v131, v129
	v_div_scale_f32 v160, s[2:3], v156, v156, 1.0
	v_fma_f32 v130, -v128, v165, v131
	v_rcp_f32_e32 v161, v160
	v_fmac_f32_e32 v165, v130, v129
	s_nop 0
	v_fma_f32 v128, -v128, v165, v131
	v_fma_f32 v162, -v160, v161, 1.0
	v_div_fmas_f32 v128, v128, v129, v165
	v_fmac_f32_e32 v161, v162, v161
	v_div_fixup_f32 v155, v128, v155, 1.0
	v_div_scale_f32 v163, vcc, 1.0, v156, 1.0
	v_mul_f32_e32 v164, v163, v161
	v_div_scale_f32 v128, s[2:3], v157, v157, 1.0
	v_fma_f32 v162, -v160, v164, v163
	v_rcp_f32_e32 v129, v128
	v_fmac_f32_e32 v164, v162, v161
	s_nop 0
	v_fma_f32 v160, -v160, v164, v163
	v_fma_f32 v130, -v128, v129, 1.0
	v_div_fmas_f32 v160, v160, v161, v164
	v_fmac_f32_e32 v129, v130, v129
	v_div_fixup_f32 v156, v160, v156, 1.0
	v_div_scale_f32 v131, vcc, 1.0, v157, 1.0
	v_mul_f32_e32 v165, v131, v129
	v_div_scale_f32 v160, s[2:3], v158, v158, 1.0
	v_fma_f32 v130, -v128, v165, v131
	v_rcp_f32_e32 v161, v160
	v_fmac_f32_e32 v165, v130, v129
	s_nop 0
	v_fma_f32 v128, -v128, v165, v131
	v_fma_f32 v162, -v160, v161, 1.0
	v_div_fmas_f32 v128, v128, v129, v165
	v_fmac_f32_e32 v161, v162, v161
	v_div_fixup_f32 v157, v128, v157, 1.0
	v_div_scale_f32 v163, vcc, 1.0, v158, 1.0
	v_mul_f32_e32 v164, v163, v161
	v_div_scale_f32 v128, s[2:3], v159, v159, 1.0
	v_fma_f32 v162, -v160, v164, v163
	v_rcp_f32_e32 v129, v128
	v_fmac_f32_e32 v164, v162, v161
	s_nop 0
	v_fma_f32 v160, -v160, v164, v163
	v_fma_f32 v130, -v128, v129, 1.0
	v_div_fmas_f32 v160, v160, v161, v164
	v_fmac_f32_e32 v129, v130, v129
	v_div_fixup_f32 v158, v160, v158, 1.0
	v_div_scale_f32 v131, vcc, 1.0, v159, 1.0
	v_mul_f32_e32 v165, v131, v129
	v_fma_f32 v130, -v128, v165, v131
	v_fmac_f32_e32 v165, v130, v129
	v_fma_f32 v128, -v128, v165, v131
	v_div_fmas_f32 v128, v128, v129, v165
	v_div_fixup_f32 v159, v128, v159, 1.0
	v_lshlrev_b32_e32 v166, 16, v104
	v_and_b32_e32 v167, 0xffff0000, v104
	v_pk_fma_f32 v[152:153], v[76:77], v[152:153], v[166:167]
	v_lshlrev_b32_e32 v166, 16, v105
	v_and_b32_e32 v167, 0xffff0000, v105
	v_pk_fma_f32 v[154:155], v[78:79], v[154:155], v[166:167]
	v_lshlrev_b32_e32 v166, 16, v106
	v_and_b32_e32 v167, 0xffff0000, v106
	v_pk_fma_f32 v[156:157], v[72:73], v[156:157], v[166:167]
	v_lshlrev_b32_e32 v166, 16, v107
	v_and_b32_e32 v167, 0xffff0000, v107
	v_pk_fma_f32 v[158:159], v[74:75], v[158:159], v[166:167]
	v_cvt_pk_bf16_f32 v168, v152, v153
	v_cvt_pk_bf16_f32 v169, v154, v155
	v_cvt_pk_bf16_f32 v170, v156, v157
	v_cvt_pk_bf16_f32 v171, v158, v159
	global_store_dwordx4 v187, v[168:171], s[66:67]
	global_load_dwordx4 v[76:79], v181, s[64:65]
	global_load_dwordx4 v[72:75], v189, s[68:69]
	s_waitcnt vmcnt(9)
	v_lshlrev_b32_e32 v152, 16, v100
	v_and_b32_e32 v153, 0xffff0000, v100
	v_lshlrev_b32_e32 v154, 16, v101
	v_and_b32_e32 v155, 0xffff0000, v101
	v_lshlrev_b32_e32 v156, 16, v102
	v_and_b32_e32 v157, 0xffff0000, v102
	v_lshlrev_b32_e32 v158, 16, v103
	v_and_b32_e32 v159, 0xffff0000, v103
	v_mul_f32_e32 v152, 0xbfb8aa3b, v152
	v_mul_f32_e32 v153, 0xbfb8aa3b, v153
	v_mul_f32_e32 v154, 0xbfb8aa3b, v154
	v_mul_f32_e32 v155, 0xbfb8aa3b, v155
	v_mul_f32_e32 v156, 0xbfb8aa3b, v156
	v_mul_f32_e32 v157, 0xbfb8aa3b, v157
	v_mul_f32_e32 v158, 0xbfb8aa3b, v158
	v_mul_f32_e32 v159, 0xbfb8aa3b, v159
	v_exp_f32_e32 v152, v152
	v_exp_f32_e32 v153, v153
	v_exp_f32_e32 v154, v154
	v_exp_f32_e32 v155, v155
	v_exp_f32_e32 v156, v156
	v_exp_f32_e32 v157, v157
	v_exp_f32_e32 v158, v158
	v_exp_f32_e32 v159, v159
	v_pk_add_f32 v[152:153], v[152:153], 1.0 op_sel_hi:[1,0]
	v_pk_add_f32 v[154:155], v[154:155], 1.0 op_sel_hi:[1,0]
	v_pk_add_f32 v[156:157], v[156:157], 1.0 op_sel_hi:[1,0]
	v_pk_add_f32 v[158:159], v[158:159], 1.0 op_sel_hi:[1,0]
	v_div_scale_f32 v160, s[2:3], v152, v152, 1.0
	v_rcp_f32_e32 v161, v160
	s_nop 0
	v_fma_f32 v162, -v160, v161, 1.0
	v_fmac_f32_e32 v161, v162, v161
	v_div_scale_f32 v163, vcc, 1.0, v152, 1.0
	v_mul_f32_e32 v164, v163, v161
	v_div_scale_f32 v128, s[2:3], v153, v153, 1.0
	v_fma_f32 v162, -v160, v164, v163
	v_rcp_f32_e32 v129, v128
	v_fmac_f32_e32 v164, v162, v161
	s_nop 0
	v_fma_f32 v160, -v160, v164, v163
	v_fma_f32 v130, -v128, v129, 1.0
	v_div_fmas_f32 v160, v160, v161, v164
	v_fmac_f32_e32 v129, v130, v129
	v_div_fixup_f32 v152, v160, v152, 1.0
	v_div_scale_f32 v131, vcc, 1.0, v153, 1.0
	v_mul_f32_e32 v165, v131, v129
	v_div_scale_f32 v160, s[2:3], v154, v154, 1.0
	v_fma_f32 v130, -v128, v165, v131
	v_rcp_f32_e32 v161, v160
	v_fmac_f32_e32 v165, v130, v129
	s_nop 0
	v_fma_f32 v128, -v128, v165, v131
	v_fma_f32 v162, -v160, v161, 1.0
	v_div_fmas_f32 v128, v128, v129, v165
	v_fmac_f32_e32 v161, v162, v161
	v_div_fixup_f32 v153, v128, v153, 1.0
	v_div_scale_f32 v163, vcc, 1.0, v154, 1.0
	v_mul_f32_e32 v164, v163, v161
	v_div_scale_f32 v128, s[2:3], v155, v155, 1.0
	v_fma_f32 v162, -v160, v164, v163
	v_rcp_f32_e32 v129, v128
	v_fmac_f32_e32 v164, v162, v161
	s_nop 0
	v_fma_f32 v160, -v160, v164, v163
	v_fma_f32 v130, -v128, v129, 1.0
	v_div_fmas_f32 v160, v160, v161, v164
	v_fmac_f32_e32 v129, v130, v129
	v_div_fixup_f32 v154, v160, v154, 1.0
	v_div_scale_f32 v131, vcc, 1.0, v155, 1.0
	v_mul_f32_e32 v165, v131, v129
	v_div_scale_f32 v160, s[2:3], v156, v156, 1.0
	v_fma_f32 v130, -v128, v165, v131
	v_rcp_f32_e32 v161, v160
	v_fmac_f32_e32 v165, v130, v129
	s_nop 0
	v_fma_f32 v128, -v128, v165, v131
	v_fma_f32 v162, -v160, v161, 1.0
	v_div_fmas_f32 v128, v128, v129, v165
	v_fmac_f32_e32 v161, v162, v161
	v_div_fixup_f32 v155, v128, v155, 1.0
	v_div_scale_f32 v163, vcc, 1.0, v156, 1.0
	v_mul_f32_e32 v164, v163, v161
	v_div_scale_f32 v128, s[2:3], v157, v157, 1.0
	v_fma_f32 v162, -v160, v164, v163
	v_rcp_f32_e32 v129, v128
	v_fmac_f32_e32 v164, v162, v161
	s_nop 0
	v_fma_f32 v160, -v160, v164, v163
	v_fma_f32 v130, -v128, v129, 1.0
	v_div_fmas_f32 v160, v160, v161, v164
	v_fmac_f32_e32 v129, v130, v129
	v_div_fixup_f32 v156, v160, v156, 1.0
	v_div_scale_f32 v131, vcc, 1.0, v157, 1.0
	v_mul_f32_e32 v165, v131, v129
	v_div_scale_f32 v160, s[2:3], v158, v158, 1.0
	v_fma_f32 v130, -v128, v165, v131
	v_rcp_f32_e32 v161, v160
	v_fmac_f32_e32 v165, v130, v129
	s_nop 0
	v_fma_f32 v128, -v128, v165, v131
	v_fma_f32 v162, -v160, v161, 1.0
	v_div_fmas_f32 v128, v128, v129, v165
	v_fmac_f32_e32 v161, v162, v161
	v_div_fixup_f32 v157, v128, v157, 1.0
	v_div_scale_f32 v163, vcc, 1.0, v158, 1.0
	v_mul_f32_e32 v164, v163, v161
	v_div_scale_f32 v128, s[2:3], v159, v159, 1.0
	v_fma_f32 v162, -v160, v164, v163
	v_rcp_f32_e32 v129, v128
	v_fmac_f32_e32 v164, v162, v161
	s_nop 0
	v_fma_f32 v160, -v160, v164, v163
	v_fma_f32 v130, -v128, v129, 1.0
	v_div_fmas_f32 v160, v160, v161, v164
	v_fmac_f32_e32 v129, v130, v129
	v_div_fixup_f32 v158, v160, v158, 1.0
	v_div_scale_f32 v131, vcc, 1.0, v159, 1.0
	v_mul_f32_e32 v165, v131, v129
	v_fma_f32 v130, -v128, v165, v131
	v_fmac_f32_e32 v165, v130, v129
	v_fma_f32 v128, -v128, v165, v131
	v_div_fmas_f32 v128, v128, v129, v165
	v_div_fixup_f32 v159, v128, v159, 1.0
	v_lshlrev_b32_e32 v166, 16, v96
	v_and_b32_e32 v167, 0xffff0000, v96
	v_pk_fma_f32 v[152:153], v[68:69], v[152:153], v[166:167]
	v_lshlrev_b32_e32 v166, 16, v97
	v_and_b32_e32 v167, 0xffff0000, v97
	v_pk_fma_f32 v[154:155], v[70:71], v[154:155], v[166:167]
	v_lshlrev_b32_e32 v166, 16, v98
	v_and_b32_e32 v167, 0xffff0000, v98
	v_pk_fma_f32 v[156:157], v[64:65], v[156:157], v[166:167]
	v_lshlrev_b32_e32 v166, 16, v99
	v_and_b32_e32 v167, 0xffff0000, v99
	v_pk_fma_f32 v[158:159], v[66:67], v[158:159], v[166:167]
	v_cvt_pk_bf16_f32 v168, v152, v153
	v_cvt_pk_bf16_f32 v169, v154, v155
	v_cvt_pk_bf16_f32 v170, v156, v157
	v_cvt_pk_bf16_f32 v171, v158, v159
	global_store_dwordx4 v187, v[168:171], s[66:67] offset:256
	global_load_dwordx4 v[68:71], v181, s[64:65] offset:256
	global_load_dwordx4 v[64:67], v189, s[68:69] offset:256
	s_waitcnt vmcnt(9)
	v_lshlrev_b32_e32 v152, 16, v92
	v_and_b32_e32 v153, 0xffff0000, v92
	v_lshlrev_b32_e32 v154, 16, v93
	v_and_b32_e32 v155, 0xffff0000, v93
	v_lshlrev_b32_e32 v156, 16, v94
	v_and_b32_e32 v157, 0xffff0000, v94
	v_lshlrev_b32_e32 v158, 16, v95
	v_and_b32_e32 v159, 0xffff0000, v95
	v_mul_f32_e32 v152, 0xbfb8aa3b, v152
	v_mul_f32_e32 v153, 0xbfb8aa3b, v153
	v_mul_f32_e32 v154, 0xbfb8aa3b, v154
	v_mul_f32_e32 v155, 0xbfb8aa3b, v155
	v_mul_f32_e32 v156, 0xbfb8aa3b, v156
	v_mul_f32_e32 v157, 0xbfb8aa3b, v157
	v_mul_f32_e32 v158, 0xbfb8aa3b, v158
	v_mul_f32_e32 v159, 0xbfb8aa3b, v159
	v_exp_f32_e32 v152, v152
	v_exp_f32_e32 v153, v153
	v_exp_f32_e32 v154, v154
	v_exp_f32_e32 v155, v155
	v_exp_f32_e32 v156, v156
	v_exp_f32_e32 v157, v157
	v_exp_f32_e32 v158, v158
	v_exp_f32_e32 v159, v159
	v_pk_add_f32 v[152:153], v[152:153], 1.0 op_sel_hi:[1,0]
	v_pk_add_f32 v[154:155], v[154:155], 1.0 op_sel_hi:[1,0]
	v_pk_add_f32 v[156:157], v[156:157], 1.0 op_sel_hi:[1,0]
	v_pk_add_f32 v[158:159], v[158:159], 1.0 op_sel_hi:[1,0]
	v_div_scale_f32 v160, s[2:3], v152, v152, 1.0
	v_rcp_f32_e32 v161, v160
	s_nop 0
	v_fma_f32 v162, -v160, v161, 1.0
	v_fmac_f32_e32 v161, v162, v161
	v_div_scale_f32 v163, vcc, 1.0, v152, 1.0
	v_mul_f32_e32 v164, v163, v161
	v_div_scale_f32 v128, s[2:3], v153, v153, 1.0
	v_fma_f32 v162, -v160, v164, v163
	v_rcp_f32_e32 v129, v128
	v_fmac_f32_e32 v164, v162, v161
	s_nop 0
	v_fma_f32 v160, -v160, v164, v163
	v_fma_f32 v130, -v128, v129, 1.0
	v_div_fmas_f32 v160, v160, v161, v164
	v_fmac_f32_e32 v129, v130, v129
	v_div_fixup_f32 v152, v160, v152, 1.0
	v_div_scale_f32 v131, vcc, 1.0, v153, 1.0
	v_mul_f32_e32 v165, v131, v129
	v_div_scale_f32 v160, s[2:3], v154, v154, 1.0
	v_fma_f32 v130, -v128, v165, v131
	v_rcp_f32_e32 v161, v160
	v_fmac_f32_e32 v165, v130, v129
	s_nop 0
	v_fma_f32 v128, -v128, v165, v131
	v_fma_f32 v162, -v160, v161, 1.0
	v_div_fmas_f32 v128, v128, v129, v165
	v_fmac_f32_e32 v161, v162, v161
	v_div_fixup_f32 v153, v128, v153, 1.0
	v_div_scale_f32 v163, vcc, 1.0, v154, 1.0
	v_mul_f32_e32 v164, v163, v161
	v_div_scale_f32 v128, s[2:3], v155, v155, 1.0
	v_fma_f32 v162, -v160, v164, v163
	v_rcp_f32_e32 v129, v128
	v_fmac_f32_e32 v164, v162, v161
	s_nop 0
	v_fma_f32 v160, -v160, v164, v163
	v_fma_f32 v130, -v128, v129, 1.0
	v_div_fmas_f32 v160, v160, v161, v164
	v_fmac_f32_e32 v129, v130, v129
	v_div_fixup_f32 v154, v160, v154, 1.0
	v_div_scale_f32 v131, vcc, 1.0, v155, 1.0
	v_mul_f32_e32 v165, v131, v129
	v_div_scale_f32 v160, s[2:3], v156, v156, 1.0
	v_fma_f32 v130, -v128, v165, v131
	v_rcp_f32_e32 v161, v160
	v_fmac_f32_e32 v165, v130, v129
	s_nop 0
	v_fma_f32 v128, -v128, v165, v131
	v_fma_f32 v162, -v160, v161, 1.0
	v_div_fmas_f32 v128, v128, v129, v165
	v_fmac_f32_e32 v161, v162, v161
	v_div_fixup_f32 v155, v128, v155, 1.0
	v_div_scale_f32 v163, vcc, 1.0, v156, 1.0
	v_mul_f32_e32 v164, v163, v161
	v_div_scale_f32 v128, s[2:3], v157, v157, 1.0
	v_fma_f32 v162, -v160, v164, v163
	v_rcp_f32_e32 v129, v128
	v_fmac_f32_e32 v164, v162, v161
	s_nop 0
	v_fma_f32 v160, -v160, v164, v163
	v_fma_f32 v130, -v128, v129, 1.0
	v_div_fmas_f32 v160, v160, v161, v164
	v_fmac_f32_e32 v129, v130, v129
	v_div_fixup_f32 v156, v160, v156, 1.0
	v_div_scale_f32 v131, vcc, 1.0, v157, 1.0
	v_mul_f32_e32 v165, v131, v129
	v_div_scale_f32 v160, s[2:3], v158, v158, 1.0
	v_fma_f32 v130, -v128, v165, v131
	v_rcp_f32_e32 v161, v160
	v_fmac_f32_e32 v165, v130, v129
	s_nop 0
	v_fma_f32 v128, -v128, v165, v131
	v_fma_f32 v162, -v160, v161, 1.0
	v_div_fmas_f32 v128, v128, v129, v165
	v_fmac_f32_e32 v161, v162, v161
	v_div_fixup_f32 v157, v128, v157, 1.0
	v_div_scale_f32 v163, vcc, 1.0, v158, 1.0
	v_mul_f32_e32 v164, v163, v161
	v_div_scale_f32 v128, s[2:3], v159, v159, 1.0
	v_fma_f32 v162, -v160, v164, v163
	v_rcp_f32_e32 v129, v128
	v_fmac_f32_e32 v164, v162, v161
	s_nop 0
	v_fma_f32 v160, -v160, v164, v163
	v_fma_f32 v130, -v128, v129, 1.0
	v_div_fmas_f32 v160, v160, v161, v164
	v_fmac_f32_e32 v129, v130, v129
	v_div_fixup_f32 v158, v160, v158, 1.0
	v_div_scale_f32 v131, vcc, 1.0, v159, 1.0
	v_mul_f32_e32 v165, v131, v129
	v_fma_f32 v130, -v128, v165, v131
	v_fmac_f32_e32 v165, v130, v129
	v_fma_f32 v128, -v128, v165, v131
	v_div_fmas_f32 v128, v128, v129, v165
	v_div_fixup_f32 v159, v128, v159, 1.0
	v_lshlrev_b32_e32 v166, 16, v88
	v_and_b32_e32 v167, 0xffff0000, v88
	v_pk_fma_f32 v[152:153], v[60:61], v[152:153], v[166:167]
	v_lshlrev_b32_e32 v166, 16, v89
	v_and_b32_e32 v167, 0xffff0000, v89
	v_pk_fma_f32 v[154:155], v[62:63], v[154:155], v[166:167]
	v_lshlrev_b32_e32 v166, 16, v90
	v_and_b32_e32 v167, 0xffff0000, v90
	v_pk_fma_f32 v[156:157], v[56:57], v[156:157], v[166:167]
	v_lshlrev_b32_e32 v166, 16, v91
	v_and_b32_e32 v167, 0xffff0000, v91
	v_pk_fma_f32 v[158:159], v[58:59], v[158:159], v[166:167]
	v_cvt_pk_bf16_f32 v168, v152, v153
	v_cvt_pk_bf16_f32 v169, v154, v155
	v_cvt_pk_bf16_f32 v170, v156, v157
	v_cvt_pk_bf16_f32 v171, v158, v159
	global_store_dwordx4 v188, v[168:171], s[66:67]
	global_load_dwordx4 v[60:63], v182, s[64:65]
	global_load_dwordx4 v[56:59], v190, s[68:69]
	s_waitcnt vmcnt(9)
	v_lshlrev_b32_e32 v152, 16, v84
	v_and_b32_e32 v153, 0xffff0000, v84
	v_lshlrev_b32_e32 v154, 16, v85
	v_and_b32_e32 v155, 0xffff0000, v85
	v_lshlrev_b32_e32 v156, 16, v86
	v_and_b32_e32 v157, 0xffff0000, v86
	v_lshlrev_b32_e32 v158, 16, v87
	v_and_b32_e32 v159, 0xffff0000, v87
	v_mul_f32_e32 v152, 0xbfb8aa3b, v152
	v_mul_f32_e32 v153, 0xbfb8aa3b, v153
	v_mul_f32_e32 v154, 0xbfb8aa3b, v154
	v_mul_f32_e32 v155, 0xbfb8aa3b, v155
	v_mul_f32_e32 v156, 0xbfb8aa3b, v156
	v_mul_f32_e32 v157, 0xbfb8aa3b, v157
	v_mul_f32_e32 v158, 0xbfb8aa3b, v158
	v_mul_f32_e32 v159, 0xbfb8aa3b, v159
	v_exp_f32_e32 v152, v152
	v_exp_f32_e32 v153, v153
	v_exp_f32_e32 v154, v154
	v_exp_f32_e32 v155, v155
	v_exp_f32_e32 v156, v156
	v_exp_f32_e32 v157, v157
	v_exp_f32_e32 v158, v158
	v_exp_f32_e32 v159, v159
	v_pk_add_f32 v[152:153], v[152:153], 1.0 op_sel_hi:[1,0]
	v_pk_add_f32 v[154:155], v[154:155], 1.0 op_sel_hi:[1,0]
	v_pk_add_f32 v[156:157], v[156:157], 1.0 op_sel_hi:[1,0]
	v_pk_add_f32 v[158:159], v[158:159], 1.0 op_sel_hi:[1,0]
	v_div_scale_f32 v160, s[2:3], v152, v152, 1.0
	v_rcp_f32_e32 v161, v160
	s_nop 0
	v_fma_f32 v162, -v160, v161, 1.0
	v_fmac_f32_e32 v161, v162, v161
	v_div_scale_f32 v163, vcc, 1.0, v152, 1.0
	v_mul_f32_e32 v164, v163, v161
	v_div_scale_f32 v128, s[2:3], v153, v153, 1.0
	v_fma_f32 v162, -v160, v164, v163
	v_rcp_f32_e32 v129, v128
	v_fmac_f32_e32 v164, v162, v161
	s_nop 0
	v_fma_f32 v160, -v160, v164, v163
	v_fma_f32 v130, -v128, v129, 1.0
	v_div_fmas_f32 v160, v160, v161, v164
	v_fmac_f32_e32 v129, v130, v129
	v_div_fixup_f32 v152, v160, v152, 1.0
	v_div_scale_f32 v131, vcc, 1.0, v153, 1.0
	v_mul_f32_e32 v165, v131, v129
	v_div_scale_f32 v160, s[2:3], v154, v154, 1.0
	v_fma_f32 v130, -v128, v165, v131
	v_rcp_f32_e32 v161, v160
	v_fmac_f32_e32 v165, v130, v129
	s_nop 0
	v_fma_f32 v128, -v128, v165, v131
	v_fma_f32 v162, -v160, v161, 1.0
	v_div_fmas_f32 v128, v128, v129, v165
	v_fmac_f32_e32 v161, v162, v161
	v_div_fixup_f32 v153, v128, v153, 1.0
	v_div_scale_f32 v163, vcc, 1.0, v154, 1.0
	v_mul_f32_e32 v164, v163, v161
	v_div_scale_f32 v128, s[2:3], v155, v155, 1.0
	v_fma_f32 v162, -v160, v164, v163
	v_rcp_f32_e32 v129, v128
	v_fmac_f32_e32 v164, v162, v161
	s_nop 0
	v_fma_f32 v160, -v160, v164, v163
	v_fma_f32 v130, -v128, v129, 1.0
	v_div_fmas_f32 v160, v160, v161, v164
	v_fmac_f32_e32 v129, v130, v129
	v_div_fixup_f32 v154, v160, v154, 1.0
	v_div_scale_f32 v131, vcc, 1.0, v155, 1.0
	v_mul_f32_e32 v165, v131, v129
	v_div_scale_f32 v160, s[2:3], v156, v156, 1.0
	v_fma_f32 v130, -v128, v165, v131
	v_rcp_f32_e32 v161, v160
	v_fmac_f32_e32 v165, v130, v129
	s_nop 0
	v_fma_f32 v128, -v128, v165, v131
	v_fma_f32 v162, -v160, v161, 1.0
	v_div_fmas_f32 v128, v128, v129, v165
	v_fmac_f32_e32 v161, v162, v161
	v_div_fixup_f32 v155, v128, v155, 1.0
	v_div_scale_f32 v163, vcc, 1.0, v156, 1.0
	v_mul_f32_e32 v164, v163, v161
	v_div_scale_f32 v128, s[2:3], v157, v157, 1.0
	v_fma_f32 v162, -v160, v164, v163
	v_rcp_f32_e32 v129, v128
	v_fmac_f32_e32 v164, v162, v161
	s_nop 0
	v_fma_f32 v160, -v160, v164, v163
	v_fma_f32 v130, -v128, v129, 1.0
	v_div_fmas_f32 v160, v160, v161, v164
	v_fmac_f32_e32 v129, v130, v129
	v_div_fixup_f32 v156, v160, v156, 1.0
	v_div_scale_f32 v131, vcc, 1.0, v157, 1.0
	v_mul_f32_e32 v165, v131, v129
	v_div_scale_f32 v160, s[2:3], v158, v158, 1.0
	v_fma_f32 v130, -v128, v165, v131
	v_rcp_f32_e32 v161, v160
	v_fmac_f32_e32 v165, v130, v129
	s_nop 0
	v_fma_f32 v128, -v128, v165, v131
	v_fma_f32 v162, -v160, v161, 1.0
	v_div_fmas_f32 v128, v128, v129, v165
	v_fmac_f32_e32 v161, v162, v161
	v_div_fixup_f32 v157, v128, v157, 1.0
	v_div_scale_f32 v163, vcc, 1.0, v158, 1.0
	v_mul_f32_e32 v164, v163, v161
	v_div_scale_f32 v128, s[2:3], v159, v159, 1.0
	v_fma_f32 v162, -v160, v164, v163
	v_rcp_f32_e32 v129, v128
	v_fmac_f32_e32 v164, v162, v161
	s_nop 0
	v_fma_f32 v160, -v160, v164, v163
	v_fma_f32 v130, -v128, v129, 1.0
	v_div_fmas_f32 v160, v160, v161, v164
	v_fmac_f32_e32 v129, v130, v129
	v_div_fixup_f32 v158, v160, v158, 1.0
	v_div_scale_f32 v131, vcc, 1.0, v159, 1.0
	v_mul_f32_e32 v165, v131, v129
	v_fma_f32 v130, -v128, v165, v131
	v_fmac_f32_e32 v165, v130, v129
	v_fma_f32 v128, -v128, v165, v131
	v_div_fmas_f32 v128, v128, v129, v165
	v_div_fixup_f32 v159, v128, v159, 1.0
	v_lshlrev_b32_e32 v166, 16, v80
	v_and_b32_e32 v167, 0xffff0000, v80
	v_pk_fma_f32 v[152:153], v[52:53], v[152:153], v[166:167]
	v_lshlrev_b32_e32 v166, 16, v81
	v_and_b32_e32 v167, 0xffff0000, v81
	v_pk_fma_f32 v[154:155], v[54:55], v[154:155], v[166:167]
	v_lshlrev_b32_e32 v166, 16, v82
	v_and_b32_e32 v167, 0xffff0000, v82
	v_pk_fma_f32 v[156:157], v[48:49], v[156:157], v[166:167]
	v_lshlrev_b32_e32 v166, 16, v83
	v_and_b32_e32 v167, 0xffff0000, v83
	v_pk_fma_f32 v[158:159], v[50:51], v[158:159], v[166:167]
	v_cvt_pk_bf16_f32 v168, v152, v153
	v_cvt_pk_bf16_f32 v169, v154, v155
	v_cvt_pk_bf16_f32 v170, v156, v157
	v_cvt_pk_bf16_f32 v171, v158, v159
	global_store_dwordx4 v188, v[168:171], s[66:67] offset:256
	global_load_dwordx4 v[52:55], v182, s[64:65] offset:256
	global_load_dwordx4 v[48:51], v190, s[68:69] offset:256
	s_waitcnt vmcnt(9)
	v_lshlrev_b32_e32 v152, 16, v76
	v_and_b32_e32 v153, 0xffff0000, v76
	v_lshlrev_b32_e32 v154, 16, v77
	v_and_b32_e32 v155, 0xffff0000, v77
	v_lshlrev_b32_e32 v156, 16, v78
	v_and_b32_e32 v157, 0xffff0000, v78
	v_lshlrev_b32_e32 v158, 16, v79
	v_and_b32_e32 v159, 0xffff0000, v79
	v_mul_f32_e32 v152, 0xbfb8aa3b, v152
	v_mul_f32_e32 v153, 0xbfb8aa3b, v153
	v_mul_f32_e32 v154, 0xbfb8aa3b, v154
	v_mul_f32_e32 v155, 0xbfb8aa3b, v155
	v_mul_f32_e32 v156, 0xbfb8aa3b, v156
	v_mul_f32_e32 v157, 0xbfb8aa3b, v157
	v_mul_f32_e32 v158, 0xbfb8aa3b, v158
	v_mul_f32_e32 v159, 0xbfb8aa3b, v159
	v_exp_f32_e32 v152, v152
	v_exp_f32_e32 v153, v153
	v_exp_f32_e32 v154, v154
	v_exp_f32_e32 v155, v155
	v_exp_f32_e32 v156, v156
	v_exp_f32_e32 v157, v157
	v_exp_f32_e32 v158, v158
	v_exp_f32_e32 v159, v159
	v_pk_add_f32 v[152:153], v[152:153], 1.0 op_sel_hi:[1,0]
	v_pk_add_f32 v[154:155], v[154:155], 1.0 op_sel_hi:[1,0]
	v_pk_add_f32 v[156:157], v[156:157], 1.0 op_sel_hi:[1,0]
	v_pk_add_f32 v[158:159], v[158:159], 1.0 op_sel_hi:[1,0]
	v_div_scale_f32 v160, s[2:3], v152, v152, 1.0
	v_rcp_f32_e32 v161, v160
	s_nop 0
	v_fma_f32 v162, -v160, v161, 1.0
	v_fmac_f32_e32 v161, v162, v161
	v_div_scale_f32 v163, vcc, 1.0, v152, 1.0
	v_mul_f32_e32 v164, v163, v161
	v_div_scale_f32 v128, s[2:3], v153, v153, 1.0
	v_fma_f32 v162, -v160, v164, v163
	v_rcp_f32_e32 v129, v128
	v_fmac_f32_e32 v164, v162, v161
	s_nop 0
	v_fma_f32 v160, -v160, v164, v163
	v_fma_f32 v130, -v128, v129, 1.0
	v_div_fmas_f32 v160, v160, v161, v164
	v_fmac_f32_e32 v129, v130, v129
	v_div_fixup_f32 v152, v160, v152, 1.0
	v_div_scale_f32 v131, vcc, 1.0, v153, 1.0
	v_mul_f32_e32 v165, v131, v129
	v_div_scale_f32 v160, s[2:3], v154, v154, 1.0
	v_fma_f32 v130, -v128, v165, v131
	v_rcp_f32_e32 v161, v160
	v_fmac_f32_e32 v165, v130, v129
	s_nop 0
	v_fma_f32 v128, -v128, v165, v131
	v_fma_f32 v162, -v160, v161, 1.0
	v_div_fmas_f32 v128, v128, v129, v165
	v_fmac_f32_e32 v161, v162, v161
	v_div_fixup_f32 v153, v128, v153, 1.0
	v_div_scale_f32 v163, vcc, 1.0, v154, 1.0
	v_mul_f32_e32 v164, v163, v161
	v_div_scale_f32 v128, s[2:3], v155, v155, 1.0
	v_fma_f32 v162, -v160, v164, v163
	v_rcp_f32_e32 v129, v128
	v_fmac_f32_e32 v164, v162, v161
	s_nop 0
	v_fma_f32 v160, -v160, v164, v163
	v_fma_f32 v130, -v128, v129, 1.0
	v_div_fmas_f32 v160, v160, v161, v164
	v_fmac_f32_e32 v129, v130, v129
	v_div_fixup_f32 v154, v160, v154, 1.0
	v_div_scale_f32 v131, vcc, 1.0, v155, 1.0
	v_mul_f32_e32 v165, v131, v129
	v_div_scale_f32 v160, s[2:3], v156, v156, 1.0
	v_fma_f32 v130, -v128, v165, v131
	v_rcp_f32_e32 v161, v160
	v_fmac_f32_e32 v165, v130, v129
	s_nop 0
	v_fma_f32 v128, -v128, v165, v131
	v_fma_f32 v162, -v160, v161, 1.0
	v_div_fmas_f32 v128, v128, v129, v165
	v_fmac_f32_e32 v161, v162, v161
	v_div_fixup_f32 v155, v128, v155, 1.0
	v_div_scale_f32 v163, vcc, 1.0, v156, 1.0
	v_mul_f32_e32 v164, v163, v161
	v_div_scale_f32 v128, s[2:3], v157, v157, 1.0
	v_fma_f32 v162, -v160, v164, v163
	v_rcp_f32_e32 v129, v128
	v_fmac_f32_e32 v164, v162, v161
	s_nop 0
	v_fma_f32 v160, -v160, v164, v163
	v_fma_f32 v130, -v128, v129, 1.0
	v_div_fmas_f32 v160, v160, v161, v164
	v_fmac_f32_e32 v129, v130, v129
	v_div_fixup_f32 v156, v160, v156, 1.0
	v_div_scale_f32 v131, vcc, 1.0, v157, 1.0
	v_mul_f32_e32 v165, v131, v129
	v_div_scale_f32 v160, s[2:3], v158, v158, 1.0
	v_fma_f32 v130, -v128, v165, v131
	v_rcp_f32_e32 v161, v160
	v_fmac_f32_e32 v165, v130, v129
	s_nop 0
	v_fma_f32 v128, -v128, v165, v131
	v_fma_f32 v162, -v160, v161, 1.0
	v_div_fmas_f32 v128, v128, v129, v165
	v_fmac_f32_e32 v161, v162, v161
	v_div_fixup_f32 v157, v128, v157, 1.0
	v_div_scale_f32 v163, vcc, 1.0, v158, 1.0
	v_mul_f32_e32 v164, v163, v161
	v_div_scale_f32 v128, s[2:3], v159, v159, 1.0
	v_fma_f32 v162, -v160, v164, v163
	v_rcp_f32_e32 v129, v128
	v_fmac_f32_e32 v164, v162, v161
	s_nop 0
	v_fma_f32 v160, -v160, v164, v163
	v_fma_f32 v130, -v128, v129, 1.0
	v_div_fmas_f32 v160, v160, v161, v164
	v_fmac_f32_e32 v129, v130, v129
	v_div_fixup_f32 v158, v160, v158, 1.0
	v_div_scale_f32 v131, vcc, 1.0, v159, 1.0
	v_mul_f32_e32 v165, v131, v129
	v_fma_f32 v130, -v128, v165, v131
	v_fmac_f32_e32 v165, v130, v129
	v_fma_f32 v128, -v128, v165, v131
	v_div_fmas_f32 v128, v128, v129, v165
	v_div_fixup_f32 v159, v128, v159, 1.0
	v_lshlrev_b32_e32 v166, 16, v72
	v_and_b32_e32 v167, 0xffff0000, v72
	v_pk_fma_f32 v[152:153], v[44:45], v[152:153], v[166:167]
	v_lshlrev_b32_e32 v166, 16, v73
	v_and_b32_e32 v167, 0xffff0000, v73
	v_pk_fma_f32 v[154:155], v[46:47], v[154:155], v[166:167]
	v_lshlrev_b32_e32 v166, 16, v74
	v_and_b32_e32 v167, 0xffff0000, v74
	v_pk_fma_f32 v[156:157], v[40:41], v[156:157], v[166:167]
	v_lshlrev_b32_e32 v166, 16, v75
	v_and_b32_e32 v167, 0xffff0000, v75
	v_pk_fma_f32 v[158:159], v[42:43], v[158:159], v[166:167]
	v_cvt_pk_bf16_f32 v168, v152, v153
	v_cvt_pk_bf16_f32 v169, v154, v155
	v_cvt_pk_bf16_f32 v170, v156, v157
	v_cvt_pk_bf16_f32 v171, v158, v159
	global_store_dwordx4 v189, v[168:171], s[66:67]
	global_load_dwordx4 v[44:47], v183, s[64:65]
	global_load_dwordx4 v[40:43], v191, s[68:69]
	s_waitcnt vmcnt(9)
	v_lshlrev_b32_e32 v152, 16, v68
	v_and_b32_e32 v153, 0xffff0000, v68
	v_lshlrev_b32_e32 v154, 16, v69
	v_and_b32_e32 v155, 0xffff0000, v69
	v_lshlrev_b32_e32 v156, 16, v70
	v_and_b32_e32 v157, 0xffff0000, v70
	v_lshlrev_b32_e32 v158, 16, v71
	v_and_b32_e32 v159, 0xffff0000, v71
	v_mul_f32_e32 v152, 0xbfb8aa3b, v152
	v_mul_f32_e32 v153, 0xbfb8aa3b, v153
	v_mul_f32_e32 v154, 0xbfb8aa3b, v154
	v_mul_f32_e32 v155, 0xbfb8aa3b, v155
	v_mul_f32_e32 v156, 0xbfb8aa3b, v156
	v_mul_f32_e32 v157, 0xbfb8aa3b, v157
	v_mul_f32_e32 v158, 0xbfb8aa3b, v158
	v_mul_f32_e32 v159, 0xbfb8aa3b, v159
	v_exp_f32_e32 v152, v152
	v_exp_f32_e32 v153, v153
	v_exp_f32_e32 v154, v154
	v_exp_f32_e32 v155, v155
	v_exp_f32_e32 v156, v156
	v_exp_f32_e32 v157, v157
	v_exp_f32_e32 v158, v158
	v_exp_f32_e32 v159, v159
	v_pk_add_f32 v[152:153], v[152:153], 1.0 op_sel_hi:[1,0]
	v_pk_add_f32 v[154:155], v[154:155], 1.0 op_sel_hi:[1,0]
	v_pk_add_f32 v[156:157], v[156:157], 1.0 op_sel_hi:[1,0]
	v_pk_add_f32 v[158:159], v[158:159], 1.0 op_sel_hi:[1,0]
	v_div_scale_f32 v160, s[2:3], v152, v152, 1.0
	v_rcp_f32_e32 v161, v160
	s_nop 0
	v_fma_f32 v162, -v160, v161, 1.0
	v_fmac_f32_e32 v161, v162, v161
	v_div_scale_f32 v163, vcc, 1.0, v152, 1.0
	v_mul_f32_e32 v164, v163, v161
	v_div_scale_f32 v128, s[2:3], v153, v153, 1.0
	v_fma_f32 v162, -v160, v164, v163
	v_rcp_f32_e32 v129, v128
	v_fmac_f32_e32 v164, v162, v161
	s_nop 0
	v_fma_f32 v160, -v160, v164, v163
	v_fma_f32 v130, -v128, v129, 1.0
	v_div_fmas_f32 v160, v160, v161, v164
	v_fmac_f32_e32 v129, v130, v129
	v_div_fixup_f32 v152, v160, v152, 1.0
	v_div_scale_f32 v131, vcc, 1.0, v153, 1.0
	v_mul_f32_e32 v165, v131, v129
	v_div_scale_f32 v160, s[2:3], v154, v154, 1.0
	v_fma_f32 v130, -v128, v165, v131
	v_rcp_f32_e32 v161, v160
	v_fmac_f32_e32 v165, v130, v129
	s_nop 0
	v_fma_f32 v128, -v128, v165, v131
	v_fma_f32 v162, -v160, v161, 1.0
	v_div_fmas_f32 v128, v128, v129, v165
	v_fmac_f32_e32 v161, v162, v161
	v_div_fixup_f32 v153, v128, v153, 1.0
	v_div_scale_f32 v163, vcc, 1.0, v154, 1.0
	v_mul_f32_e32 v164, v163, v161
	v_div_scale_f32 v128, s[2:3], v155, v155, 1.0
	v_fma_f32 v162, -v160, v164, v163
	v_rcp_f32_e32 v129, v128
	v_fmac_f32_e32 v164, v162, v161
	s_nop 0
	v_fma_f32 v160, -v160, v164, v163
	v_fma_f32 v130, -v128, v129, 1.0
	v_div_fmas_f32 v160, v160, v161, v164
	v_fmac_f32_e32 v129, v130, v129
	v_div_fixup_f32 v154, v160, v154, 1.0
	v_div_scale_f32 v131, vcc, 1.0, v155, 1.0
	v_mul_f32_e32 v165, v131, v129
	v_div_scale_f32 v160, s[2:3], v156, v156, 1.0
	v_fma_f32 v130, -v128, v165, v131
	v_rcp_f32_e32 v161, v160
	v_fmac_f32_e32 v165, v130, v129
	s_nop 0
	v_fma_f32 v128, -v128, v165, v131
	v_fma_f32 v162, -v160, v161, 1.0
	v_div_fmas_f32 v128, v128, v129, v165
	v_fmac_f32_e32 v161, v162, v161
	v_div_fixup_f32 v155, v128, v155, 1.0
	v_div_scale_f32 v163, vcc, 1.0, v156, 1.0
	v_mul_f32_e32 v164, v163, v161
	v_div_scale_f32 v128, s[2:3], v157, v157, 1.0
	v_fma_f32 v162, -v160, v164, v163
	v_rcp_f32_e32 v129, v128
	v_fmac_f32_e32 v164, v162, v161
	s_nop 0
	v_fma_f32 v160, -v160, v164, v163
	v_fma_f32 v130, -v128, v129, 1.0
	v_div_fmas_f32 v160, v160, v161, v164
	v_fmac_f32_e32 v129, v130, v129
	v_div_fixup_f32 v156, v160, v156, 1.0
	v_div_scale_f32 v131, vcc, 1.0, v157, 1.0
	v_mul_f32_e32 v165, v131, v129
	v_div_scale_f32 v160, s[2:3], v158, v158, 1.0
	v_fma_f32 v130, -v128, v165, v131
	v_rcp_f32_e32 v161, v160
	v_fmac_f32_e32 v165, v130, v129
	s_nop 0
	v_fma_f32 v128, -v128, v165, v131
	v_fma_f32 v162, -v160, v161, 1.0
	v_div_fmas_f32 v128, v128, v129, v165
	v_fmac_f32_e32 v161, v162, v161
	v_div_fixup_f32 v157, v128, v157, 1.0
	v_div_scale_f32 v163, vcc, 1.0, v158, 1.0
	v_mul_f32_e32 v164, v163, v161
	v_div_scale_f32 v128, s[2:3], v159, v159, 1.0
	v_fma_f32 v162, -v160, v164, v163
	v_rcp_f32_e32 v129, v128
	v_fmac_f32_e32 v164, v162, v161
	s_nop 0
	v_fma_f32 v160, -v160, v164, v163
	v_fma_f32 v130, -v128, v129, 1.0
	v_div_fmas_f32 v160, v160, v161, v164
	v_fmac_f32_e32 v129, v130, v129
	v_div_fixup_f32 v158, v160, v158, 1.0
	v_div_scale_f32 v131, vcc, 1.0, v159, 1.0
	v_mul_f32_e32 v165, v131, v129
	v_fma_f32 v130, -v128, v165, v131
	v_fmac_f32_e32 v165, v130, v129
	v_fma_f32 v128, -v128, v165, v131
	v_div_fmas_f32 v128, v128, v129, v165
	v_div_fixup_f32 v159, v128, v159, 1.0
	v_lshlrev_b32_e32 v166, 16, v64
	v_and_b32_e32 v167, 0xffff0000, v64
	v_pk_fma_f32 v[152:153], v[36:37], v[152:153], v[166:167]
	v_lshlrev_b32_e32 v166, 16, v65
	v_and_b32_e32 v167, 0xffff0000, v65
	v_pk_fma_f32 v[154:155], v[38:39], v[154:155], v[166:167]
	v_lshlrev_b32_e32 v166, 16, v66
	v_and_b32_e32 v167, 0xffff0000, v66
	v_pk_fma_f32 v[156:157], v[32:33], v[156:157], v[166:167]
	v_lshlrev_b32_e32 v166, 16, v67
	v_and_b32_e32 v167, 0xffff0000, v67
	v_pk_fma_f32 v[158:159], v[34:35], v[158:159], v[166:167]
	v_cvt_pk_bf16_f32 v168, v152, v153
	v_cvt_pk_bf16_f32 v169, v154, v155
	v_cvt_pk_bf16_f32 v170, v156, v157
	v_cvt_pk_bf16_f32 v171, v158, v159
	global_store_dwordx4 v189, v[168:171], s[66:67] offset:256
	global_load_dwordx4 v[36:39], v183, s[64:65] offset:256
	global_load_dwordx4 v[32:35], v191, s[68:69] offset:256
	s_waitcnt vmcnt(9)
	v_lshlrev_b32_e32 v152, 16, v60
	v_and_b32_e32 v153, 0xffff0000, v60
	v_lshlrev_b32_e32 v154, 16, v61
	v_and_b32_e32 v155, 0xffff0000, v61
	v_lshlrev_b32_e32 v156, 16, v62
	v_and_b32_e32 v157, 0xffff0000, v62
	v_lshlrev_b32_e32 v158, 16, v63
	v_and_b32_e32 v159, 0xffff0000, v63
	v_mul_f32_e32 v152, 0xbfb8aa3b, v152
	v_mul_f32_e32 v153, 0xbfb8aa3b, v153
	v_mul_f32_e32 v154, 0xbfb8aa3b, v154
	v_mul_f32_e32 v155, 0xbfb8aa3b, v155
	v_mul_f32_e32 v156, 0xbfb8aa3b, v156
	v_mul_f32_e32 v157, 0xbfb8aa3b, v157
	v_mul_f32_e32 v158, 0xbfb8aa3b, v158
	v_mul_f32_e32 v159, 0xbfb8aa3b, v159
	v_exp_f32_e32 v152, v152
	v_exp_f32_e32 v153, v153
	v_exp_f32_e32 v154, v154
	v_exp_f32_e32 v155, v155
	v_exp_f32_e32 v156, v156
	v_exp_f32_e32 v157, v157
	v_exp_f32_e32 v158, v158
	v_exp_f32_e32 v159, v159
	v_pk_add_f32 v[152:153], v[152:153], 1.0 op_sel_hi:[1,0]
	v_pk_add_f32 v[154:155], v[154:155], 1.0 op_sel_hi:[1,0]
	v_pk_add_f32 v[156:157], v[156:157], 1.0 op_sel_hi:[1,0]
	v_pk_add_f32 v[158:159], v[158:159], 1.0 op_sel_hi:[1,0]
	v_div_scale_f32 v160, s[2:3], v152, v152, 1.0
	v_rcp_f32_e32 v161, v160
	s_nop 0
	v_fma_f32 v162, -v160, v161, 1.0
	v_fmac_f32_e32 v161, v162, v161
	v_div_scale_f32 v163, vcc, 1.0, v152, 1.0
	v_mul_f32_e32 v164, v163, v161
	v_div_scale_f32 v128, s[2:3], v153, v153, 1.0
	v_fma_f32 v162, -v160, v164, v163
	v_rcp_f32_e32 v129, v128
	v_fmac_f32_e32 v164, v162, v161
	s_nop 0
	v_fma_f32 v160, -v160, v164, v163
	v_fma_f32 v130, -v128, v129, 1.0
	v_div_fmas_f32 v160, v160, v161, v164
	v_fmac_f32_e32 v129, v130, v129
	v_div_fixup_f32 v152, v160, v152, 1.0
	v_div_scale_f32 v131, vcc, 1.0, v153, 1.0
	v_mul_f32_e32 v165, v131, v129
	v_div_scale_f32 v160, s[2:3], v154, v154, 1.0
	v_fma_f32 v130, -v128, v165, v131
	v_rcp_f32_e32 v161, v160
	v_fmac_f32_e32 v165, v130, v129
	s_nop 0
	v_fma_f32 v128, -v128, v165, v131
	v_fma_f32 v162, -v160, v161, 1.0
	v_div_fmas_f32 v128, v128, v129, v165
	v_fmac_f32_e32 v161, v162, v161
	v_div_fixup_f32 v153, v128, v153, 1.0
	v_div_scale_f32 v163, vcc, 1.0, v154, 1.0
	v_mul_f32_e32 v164, v163, v161
	v_div_scale_f32 v128, s[2:3], v155, v155, 1.0
	v_fma_f32 v162, -v160, v164, v163
	v_rcp_f32_e32 v129, v128
	v_fmac_f32_e32 v164, v162, v161
	s_nop 0
	v_fma_f32 v160, -v160, v164, v163
	v_fma_f32 v130, -v128, v129, 1.0
	v_div_fmas_f32 v160, v160, v161, v164
	v_fmac_f32_e32 v129, v130, v129
	v_div_fixup_f32 v154, v160, v154, 1.0
	v_div_scale_f32 v131, vcc, 1.0, v155, 1.0
	v_mul_f32_e32 v165, v131, v129
	v_div_scale_f32 v160, s[2:3], v156, v156, 1.0
	v_fma_f32 v130, -v128, v165, v131
	v_rcp_f32_e32 v161, v160
	v_fmac_f32_e32 v165, v130, v129
	s_nop 0
	v_fma_f32 v128, -v128, v165, v131
	v_fma_f32 v162, -v160, v161, 1.0
	v_div_fmas_f32 v128, v128, v129, v165
	v_fmac_f32_e32 v161, v162, v161
	v_div_fixup_f32 v155, v128, v155, 1.0
	v_div_scale_f32 v163, vcc, 1.0, v156, 1.0
	v_mul_f32_e32 v164, v163, v161
	v_div_scale_f32 v128, s[2:3], v157, v157, 1.0
	v_fma_f32 v162, -v160, v164, v163
	v_rcp_f32_e32 v129, v128
	v_fmac_f32_e32 v164, v162, v161
	s_nop 0
	v_fma_f32 v160, -v160, v164, v163
	v_fma_f32 v130, -v128, v129, 1.0
	v_div_fmas_f32 v160, v160, v161, v164
	v_fmac_f32_e32 v129, v130, v129
	v_div_fixup_f32 v156, v160, v156, 1.0
	v_div_scale_f32 v131, vcc, 1.0, v157, 1.0
	v_mul_f32_e32 v165, v131, v129
	v_div_scale_f32 v160, s[2:3], v158, v158, 1.0
	v_fma_f32 v130, -v128, v165, v131
	v_rcp_f32_e32 v161, v160
	v_fmac_f32_e32 v165, v130, v129
	s_nop 0
	v_fma_f32 v128, -v128, v165, v131
	v_fma_f32 v162, -v160, v161, 1.0
	v_div_fmas_f32 v128, v128, v129, v165
	v_fmac_f32_e32 v161, v162, v161
	v_div_fixup_f32 v157, v128, v157, 1.0
	v_div_scale_f32 v163, vcc, 1.0, v158, 1.0
	v_mul_f32_e32 v164, v163, v161
	v_div_scale_f32 v128, s[2:3], v159, v159, 1.0
	v_fma_f32 v162, -v160, v164, v163
	v_rcp_f32_e32 v129, v128
	v_fmac_f32_e32 v164, v162, v161
	s_nop 0
	v_fma_f32 v160, -v160, v164, v163
	v_fma_f32 v130, -v128, v129, 1.0
	v_div_fmas_f32 v160, v160, v161, v164
	v_fmac_f32_e32 v129, v130, v129
	v_div_fixup_f32 v158, v160, v158, 1.0
	v_div_scale_f32 v131, vcc, 1.0, v159, 1.0
	v_mul_f32_e32 v165, v131, v129
	v_fma_f32 v130, -v128, v165, v131
	v_fmac_f32_e32 v165, v130, v129
	v_fma_f32 v128, -v128, v165, v131
	v_div_fmas_f32 v128, v128, v129, v165
	v_div_fixup_f32 v159, v128, v159, 1.0
	v_lshlrev_b32_e32 v166, 16, v56
	v_and_b32_e32 v167, 0xffff0000, v56
	v_pk_fma_f32 v[152:153], v[28:29], v[152:153], v[166:167]
	v_lshlrev_b32_e32 v166, 16, v57
	v_and_b32_e32 v167, 0xffff0000, v57
	v_pk_fma_f32 v[154:155], v[30:31], v[154:155], v[166:167]
	v_lshlrev_b32_e32 v166, 16, v58
	v_and_b32_e32 v167, 0xffff0000, v58
	v_pk_fma_f32 v[156:157], v[24:25], v[156:157], v[166:167]
	v_lshlrev_b32_e32 v166, 16, v59
	v_and_b32_e32 v167, 0xffff0000, v59
	v_pk_fma_f32 v[158:159], v[26:27], v[158:159], v[166:167]
	v_cvt_pk_bf16_f32 v168, v152, v153
	v_cvt_pk_bf16_f32 v169, v154, v155
	v_cvt_pk_bf16_f32 v170, v156, v157
	v_cvt_pk_bf16_f32 v171, v158, v159
	global_store_dwordx4 v190, v[168:171], s[66:67]
	s_waitcnt vmcnt(7)
	v_lshlrev_b32_e32 v152, 16, v52
	v_and_b32_e32 v153, 0xffff0000, v52
	v_lshlrev_b32_e32 v154, 16, v53
	v_and_b32_e32 v155, 0xffff0000, v53
	v_lshlrev_b32_e32 v156, 16, v54
	v_and_b32_e32 v157, 0xffff0000, v54
	v_lshlrev_b32_e32 v158, 16, v55
	v_and_b32_e32 v159, 0xffff0000, v55
	v_mul_f32_e32 v152, 0xbfb8aa3b, v152
	v_mul_f32_e32 v153, 0xbfb8aa3b, v153
	v_mul_f32_e32 v154, 0xbfb8aa3b, v154
	v_mul_f32_e32 v155, 0xbfb8aa3b, v155
	v_mul_f32_e32 v156, 0xbfb8aa3b, v156
	v_mul_f32_e32 v157, 0xbfb8aa3b, v157
	v_mul_f32_e32 v158, 0xbfb8aa3b, v158
	v_mul_f32_e32 v159, 0xbfb8aa3b, v159
	v_exp_f32_e32 v152, v152
	v_exp_f32_e32 v153, v153
	v_exp_f32_e32 v154, v154
	v_exp_f32_e32 v155, v155
	v_exp_f32_e32 v156, v156
	v_exp_f32_e32 v157, v157
	v_exp_f32_e32 v158, v158
	v_exp_f32_e32 v159, v159
	v_pk_add_f32 v[152:153], v[152:153], 1.0 op_sel_hi:[1,0]
	v_pk_add_f32 v[154:155], v[154:155], 1.0 op_sel_hi:[1,0]
	v_pk_add_f32 v[156:157], v[156:157], 1.0 op_sel_hi:[1,0]
	v_pk_add_f32 v[158:159], v[158:159], 1.0 op_sel_hi:[1,0]
	v_div_scale_f32 v160, s[2:3], v152, v152, 1.0
	v_rcp_f32_e32 v161, v160
	s_nop 0
	v_fma_f32 v162, -v160, v161, 1.0
	v_fmac_f32_e32 v161, v162, v161
	v_div_scale_f32 v163, vcc, 1.0, v152, 1.0
	v_mul_f32_e32 v164, v163, v161
	v_div_scale_f32 v128, s[2:3], v153, v153, 1.0
	v_fma_f32 v162, -v160, v164, v163
	v_rcp_f32_e32 v129, v128
	v_fmac_f32_e32 v164, v162, v161
	s_nop 0
	v_fma_f32 v160, -v160, v164, v163
	v_fma_f32 v130, -v128, v129, 1.0
	v_div_fmas_f32 v160, v160, v161, v164
	v_fmac_f32_e32 v129, v130, v129
	v_div_fixup_f32 v152, v160, v152, 1.0
	v_div_scale_f32 v131, vcc, 1.0, v153, 1.0
	v_mul_f32_e32 v165, v131, v129
	v_div_scale_f32 v160, s[2:3], v154, v154, 1.0
	v_fma_f32 v130, -v128, v165, v131
	v_rcp_f32_e32 v161, v160
	v_fmac_f32_e32 v165, v130, v129
	s_nop 0
	v_fma_f32 v128, -v128, v165, v131
	v_fma_f32 v162, -v160, v161, 1.0
	v_div_fmas_f32 v128, v128, v129, v165
	v_fmac_f32_e32 v161, v162, v161
	v_div_fixup_f32 v153, v128, v153, 1.0
	v_div_scale_f32 v163, vcc, 1.0, v154, 1.0
	v_mul_f32_e32 v164, v163, v161
	v_div_scale_f32 v128, s[2:3], v155, v155, 1.0
	v_fma_f32 v162, -v160, v164, v163
	v_rcp_f32_e32 v129, v128
	v_fmac_f32_e32 v164, v162, v161
	s_nop 0
	v_fma_f32 v160, -v160, v164, v163
	v_fma_f32 v130, -v128, v129, 1.0
	v_div_fmas_f32 v160, v160, v161, v164
	v_fmac_f32_e32 v129, v130, v129
	v_div_fixup_f32 v154, v160, v154, 1.0
	v_div_scale_f32 v131, vcc, 1.0, v155, 1.0
	v_mul_f32_e32 v165, v131, v129
	v_div_scale_f32 v160, s[2:3], v156, v156, 1.0
	v_fma_f32 v130, -v128, v165, v131
	v_rcp_f32_e32 v161, v160
	v_fmac_f32_e32 v165, v130, v129
	s_nop 0
	v_fma_f32 v128, -v128, v165, v131
	v_fma_f32 v162, -v160, v161, 1.0
	v_div_fmas_f32 v128, v128, v129, v165
	v_fmac_f32_e32 v161, v162, v161
	v_div_fixup_f32 v155, v128, v155, 1.0
	v_div_scale_f32 v163, vcc, 1.0, v156, 1.0
	v_mul_f32_e32 v164, v163, v161
	v_div_scale_f32 v128, s[2:3], v157, v157, 1.0
	v_fma_f32 v162, -v160, v164, v163
	v_rcp_f32_e32 v129, v128
	v_fmac_f32_e32 v164, v162, v161
	s_nop 0
	v_fma_f32 v160, -v160, v164, v163
	v_fma_f32 v130, -v128, v129, 1.0
	v_div_fmas_f32 v160, v160, v161, v164
	v_fmac_f32_e32 v129, v130, v129
	v_div_fixup_f32 v156, v160, v156, 1.0
	v_div_scale_f32 v131, vcc, 1.0, v157, 1.0
	v_mul_f32_e32 v165, v131, v129
	v_div_scale_f32 v160, s[2:3], v158, v158, 1.0
	v_fma_f32 v130, -v128, v165, v131
	v_rcp_f32_e32 v161, v160
	v_fmac_f32_e32 v165, v130, v129
	s_nop 0
	v_fma_f32 v128, -v128, v165, v131
	v_fma_f32 v162, -v160, v161, 1.0
	v_div_fmas_f32 v128, v128, v129, v165
	v_fmac_f32_e32 v161, v162, v161
	v_div_fixup_f32 v157, v128, v157, 1.0
	v_div_scale_f32 v163, vcc, 1.0, v158, 1.0
	v_mul_f32_e32 v164, v163, v161
	v_div_scale_f32 v128, s[2:3], v159, v159, 1.0
	v_fma_f32 v162, -v160, v164, v163
	v_rcp_f32_e32 v129, v128
	v_fmac_f32_e32 v164, v162, v161
	s_nop 0
	v_fma_f32 v160, -v160, v164, v163
	v_fma_f32 v130, -v128, v129, 1.0
	v_div_fmas_f32 v160, v160, v161, v164
	v_fmac_f32_e32 v129, v130, v129
	v_div_fixup_f32 v158, v160, v158, 1.0
	v_div_scale_f32 v131, vcc, 1.0, v159, 1.0
	v_mul_f32_e32 v165, v131, v129
	v_fma_f32 v130, -v128, v165, v131
	v_fmac_f32_e32 v165, v130, v129
	v_fma_f32 v128, -v128, v165, v131
	v_div_fmas_f32 v128, v128, v129, v165
	v_div_fixup_f32 v159, v128, v159, 1.0
	v_lshlrev_b32_e32 v166, 16, v48
	v_and_b32_e32 v167, 0xffff0000, v48
	v_pk_fma_f32 v[152:153], v[20:21], v[152:153], v[166:167]
	v_lshlrev_b32_e32 v166, 16, v49
	v_and_b32_e32 v167, 0xffff0000, v49
	v_pk_fma_f32 v[154:155], v[22:23], v[154:155], v[166:167]
	v_lshlrev_b32_e32 v166, 16, v50
	v_and_b32_e32 v167, 0xffff0000, v50
	v_pk_fma_f32 v[156:157], v[16:17], v[156:157], v[166:167]
	v_lshlrev_b32_e32 v166, 16, v51
	v_and_b32_e32 v167, 0xffff0000, v51
	v_pk_fma_f32 v[158:159], v[18:19], v[158:159], v[166:167]
	v_cvt_pk_bf16_f32 v168, v152, v153
	v_cvt_pk_bf16_f32 v169, v154, v155
	v_cvt_pk_bf16_f32 v170, v156, v157
	v_cvt_pk_bf16_f32 v171, v158, v159
	global_store_dwordx4 v190, v[168:171], s[66:67] offset:256
	s_waitcnt vmcnt(5)
	v_lshlrev_b32_e32 v152, 16, v44
	v_and_b32_e32 v153, 0xffff0000, v44
	v_lshlrev_b32_e32 v154, 16, v45
	v_and_b32_e32 v155, 0xffff0000, v45
	v_lshlrev_b32_e32 v156, 16, v46
	v_and_b32_e32 v157, 0xffff0000, v46
	v_lshlrev_b32_e32 v158, 16, v47
	v_and_b32_e32 v159, 0xffff0000, v47
	v_mul_f32_e32 v152, 0xbfb8aa3b, v152
	v_mul_f32_e32 v153, 0xbfb8aa3b, v153
	v_mul_f32_e32 v154, 0xbfb8aa3b, v154
	v_mul_f32_e32 v155, 0xbfb8aa3b, v155
	v_mul_f32_e32 v156, 0xbfb8aa3b, v156
	v_mul_f32_e32 v157, 0xbfb8aa3b, v157
	v_mul_f32_e32 v158, 0xbfb8aa3b, v158
	v_mul_f32_e32 v159, 0xbfb8aa3b, v159
	v_exp_f32_e32 v152, v152
	v_exp_f32_e32 v153, v153
	v_exp_f32_e32 v154, v154
	v_exp_f32_e32 v155, v155
	v_exp_f32_e32 v156, v156
	v_exp_f32_e32 v157, v157
	v_exp_f32_e32 v158, v158
	v_exp_f32_e32 v159, v159
	v_pk_add_f32 v[152:153], v[152:153], 1.0 op_sel_hi:[1,0]
	v_pk_add_f32 v[154:155], v[154:155], 1.0 op_sel_hi:[1,0]
	v_pk_add_f32 v[156:157], v[156:157], 1.0 op_sel_hi:[1,0]
	v_pk_add_f32 v[158:159], v[158:159], 1.0 op_sel_hi:[1,0]
	v_div_scale_f32 v160, s[2:3], v152, v152, 1.0
	v_rcp_f32_e32 v161, v160
	s_nop 0
	v_fma_f32 v162, -v160, v161, 1.0
	v_fmac_f32_e32 v161, v162, v161
	v_div_scale_f32 v163, vcc, 1.0, v152, 1.0
	v_mul_f32_e32 v164, v163, v161
	v_div_scale_f32 v128, s[2:3], v153, v153, 1.0
	v_fma_f32 v162, -v160, v164, v163
	v_rcp_f32_e32 v129, v128
	v_fmac_f32_e32 v164, v162, v161
	s_nop 0
	v_fma_f32 v160, -v160, v164, v163
	v_fma_f32 v130, -v128, v129, 1.0
	v_div_fmas_f32 v160, v160, v161, v164
	v_fmac_f32_e32 v129, v130, v129
	v_div_fixup_f32 v152, v160, v152, 1.0
	v_div_scale_f32 v131, vcc, 1.0, v153, 1.0
	v_mul_f32_e32 v165, v131, v129
	v_div_scale_f32 v160, s[2:3], v154, v154, 1.0
	v_fma_f32 v130, -v128, v165, v131
	v_rcp_f32_e32 v161, v160
	v_fmac_f32_e32 v165, v130, v129
	s_nop 0
	v_fma_f32 v128, -v128, v165, v131
	v_fma_f32 v162, -v160, v161, 1.0
	v_div_fmas_f32 v128, v128, v129, v165
	v_fmac_f32_e32 v161, v162, v161
	v_div_fixup_f32 v153, v128, v153, 1.0
	v_div_scale_f32 v163, vcc, 1.0, v154, 1.0
	v_mul_f32_e32 v164, v163, v161
	v_div_scale_f32 v128, s[2:3], v155, v155, 1.0
	v_fma_f32 v162, -v160, v164, v163
	v_rcp_f32_e32 v129, v128
	v_fmac_f32_e32 v164, v162, v161
	s_nop 0
	v_fma_f32 v160, -v160, v164, v163
	v_fma_f32 v130, -v128, v129, 1.0
	v_div_fmas_f32 v160, v160, v161, v164
	v_fmac_f32_e32 v129, v130, v129
	v_div_fixup_f32 v154, v160, v154, 1.0
	v_div_scale_f32 v131, vcc, 1.0, v155, 1.0
	v_mul_f32_e32 v165, v131, v129
	v_div_scale_f32 v160, s[2:3], v156, v156, 1.0
	v_fma_f32 v130, -v128, v165, v131
	v_rcp_f32_e32 v161, v160
	v_fmac_f32_e32 v165, v130, v129
	s_nop 0
	v_fma_f32 v128, -v128, v165, v131
	v_fma_f32 v162, -v160, v161, 1.0
	v_div_fmas_f32 v128, v128, v129, v165
	v_fmac_f32_e32 v161, v162, v161
	v_div_fixup_f32 v155, v128, v155, 1.0
	v_div_scale_f32 v163, vcc, 1.0, v156, 1.0
	v_mul_f32_e32 v164, v163, v161
	v_div_scale_f32 v128, s[2:3], v157, v157, 1.0
	v_fma_f32 v162, -v160, v164, v163
	v_rcp_f32_e32 v129, v128
	v_fmac_f32_e32 v164, v162, v161
	s_nop 0
	v_fma_f32 v160, -v160, v164, v163
	v_fma_f32 v130, -v128, v129, 1.0
	v_div_fmas_f32 v160, v160, v161, v164
	v_fmac_f32_e32 v129, v130, v129
	v_div_fixup_f32 v156, v160, v156, 1.0
	v_div_scale_f32 v131, vcc, 1.0, v157, 1.0
	v_mul_f32_e32 v165, v131, v129
	v_div_scale_f32 v160, s[2:3], v158, v158, 1.0
	v_fma_f32 v130, -v128, v165, v131
	v_rcp_f32_e32 v161, v160
	v_fmac_f32_e32 v165, v130, v129
	s_nop 0
	v_fma_f32 v128, -v128, v165, v131
	v_fma_f32 v162, -v160, v161, 1.0
	v_div_fmas_f32 v128, v128, v129, v165
	v_fmac_f32_e32 v161, v162, v161
	v_div_fixup_f32 v157, v128, v157, 1.0
	v_div_scale_f32 v163, vcc, 1.0, v158, 1.0
	v_mul_f32_e32 v164, v163, v161
	v_div_scale_f32 v128, s[2:3], v159, v159, 1.0
	v_fma_f32 v162, -v160, v164, v163
	v_rcp_f32_e32 v129, v128
	v_fmac_f32_e32 v164, v162, v161
	s_nop 0
	v_fma_f32 v160, -v160, v164, v163
	v_fma_f32 v130, -v128, v129, 1.0
	v_div_fmas_f32 v160, v160, v161, v164
	v_fmac_f32_e32 v129, v130, v129
	v_div_fixup_f32 v158, v160, v158, 1.0
	v_div_scale_f32 v131, vcc, 1.0, v159, 1.0
	v_mul_f32_e32 v165, v131, v129
	v_fma_f32 v130, -v128, v165, v131
	v_fmac_f32_e32 v165, v130, v129
	v_fma_f32 v128, -v128, v165, v131
	v_div_fmas_f32 v128, v128, v129, v165
	v_div_fixup_f32 v159, v128, v159, 1.0
	v_lshlrev_b32_e32 v166, 16, v40
	v_and_b32_e32 v167, 0xffff0000, v40
	v_pk_fma_f32 v[152:153], v[12:13], v[152:153], v[166:167]
	v_lshlrev_b32_e32 v166, 16, v41
	v_and_b32_e32 v167, 0xffff0000, v41
	v_pk_fma_f32 v[154:155], v[14:15], v[154:155], v[166:167]
	v_lshlrev_b32_e32 v166, 16, v42
	v_and_b32_e32 v167, 0xffff0000, v42
	v_pk_fma_f32 v[156:157], v[8:9], v[156:157], v[166:167]
	v_lshlrev_b32_e32 v166, 16, v43
	v_and_b32_e32 v167, 0xffff0000, v43
	v_pk_fma_f32 v[158:159], v[10:11], v[158:159], v[166:167]
	v_cvt_pk_bf16_f32 v168, v152, v153
	v_cvt_pk_bf16_f32 v169, v154, v155
	v_cvt_pk_bf16_f32 v170, v156, v157
	v_cvt_pk_bf16_f32 v171, v158, v159
	global_store_dwordx4 v191, v[168:171], s[66:67]
	s_waitcnt vmcnt(3)
	v_lshlrev_b32_e32 v152, 16, v36
	v_and_b32_e32 v153, 0xffff0000, v36
	v_lshlrev_b32_e32 v154, 16, v37
	v_and_b32_e32 v155, 0xffff0000, v37
	v_lshlrev_b32_e32 v156, 16, v38
	v_and_b32_e32 v157, 0xffff0000, v38
	v_lshlrev_b32_e32 v158, 16, v39
	v_and_b32_e32 v159, 0xffff0000, v39
	v_mul_f32_e32 v152, 0xbfb8aa3b, v152
	v_mul_f32_e32 v153, 0xbfb8aa3b, v153
	v_mul_f32_e32 v154, 0xbfb8aa3b, v154
	v_mul_f32_e32 v155, 0xbfb8aa3b, v155
	v_mul_f32_e32 v156, 0xbfb8aa3b, v156
	v_mul_f32_e32 v157, 0xbfb8aa3b, v157
	v_mul_f32_e32 v158, 0xbfb8aa3b, v158
	v_mul_f32_e32 v159, 0xbfb8aa3b, v159
	v_exp_f32_e32 v152, v152
	v_exp_f32_e32 v153, v153
	v_exp_f32_e32 v154, v154
	v_exp_f32_e32 v155, v155
	v_exp_f32_e32 v156, v156
	v_exp_f32_e32 v157, v157
	v_exp_f32_e32 v158, v158
	v_exp_f32_e32 v159, v159
	v_pk_add_f32 v[152:153], v[152:153], 1.0 op_sel_hi:[1,0]
	v_pk_add_f32 v[154:155], v[154:155], 1.0 op_sel_hi:[1,0]
	v_pk_add_f32 v[156:157], v[156:157], 1.0 op_sel_hi:[1,0]
	v_pk_add_f32 v[158:159], v[158:159], 1.0 op_sel_hi:[1,0]
	v_div_scale_f32 v160, s[2:3], v152, v152, 1.0
	v_rcp_f32_e32 v161, v160
	s_nop 0
	v_fma_f32 v162, -v160, v161, 1.0
	v_fmac_f32_e32 v161, v162, v161
	v_div_scale_f32 v163, vcc, 1.0, v152, 1.0
	v_mul_f32_e32 v164, v163, v161
	v_div_scale_f32 v128, s[2:3], v153, v153, 1.0
	v_fma_f32 v162, -v160, v164, v163
	v_rcp_f32_e32 v129, v128
	v_fmac_f32_e32 v164, v162, v161
	s_nop 0
	v_fma_f32 v160, -v160, v164, v163
	v_fma_f32 v130, -v128, v129, 1.0
	v_div_fmas_f32 v160, v160, v161, v164
	v_fmac_f32_e32 v129, v130, v129
	v_div_fixup_f32 v152, v160, v152, 1.0
	v_div_scale_f32 v131, vcc, 1.0, v153, 1.0
	v_mul_f32_e32 v165, v131, v129
	v_div_scale_f32 v160, s[2:3], v154, v154, 1.0
	v_fma_f32 v130, -v128, v165, v131
	v_rcp_f32_e32 v161, v160
	v_fmac_f32_e32 v165, v130, v129
	s_nop 0
	v_fma_f32 v128, -v128, v165, v131
	v_fma_f32 v162, -v160, v161, 1.0
	v_div_fmas_f32 v128, v128, v129, v165
	v_fmac_f32_e32 v161, v162, v161
	v_div_fixup_f32 v153, v128, v153, 1.0
	v_div_scale_f32 v163, vcc, 1.0, v154, 1.0
	v_mul_f32_e32 v164, v163, v161
	v_div_scale_f32 v128, s[2:3], v155, v155, 1.0
	v_fma_f32 v162, -v160, v164, v163
	v_rcp_f32_e32 v129, v128
	v_fmac_f32_e32 v164, v162, v161
	s_nop 0
	v_fma_f32 v160, -v160, v164, v163
	v_fma_f32 v130, -v128, v129, 1.0
	v_div_fmas_f32 v160, v160, v161, v164
	v_fmac_f32_e32 v129, v130, v129
	v_div_fixup_f32 v154, v160, v154, 1.0
	v_div_scale_f32 v131, vcc, 1.0, v155, 1.0
	v_mul_f32_e32 v165, v131, v129
	v_div_scale_f32 v160, s[2:3], v156, v156, 1.0
	v_fma_f32 v130, -v128, v165, v131
	v_rcp_f32_e32 v161, v160
	v_fmac_f32_e32 v165, v130, v129
	s_nop 0
	v_fma_f32 v128, -v128, v165, v131
	v_fma_f32 v162, -v160, v161, 1.0
	v_div_fmas_f32 v128, v128, v129, v165
	v_fmac_f32_e32 v161, v162, v161
	v_div_fixup_f32 v155, v128, v155, 1.0
	v_div_scale_f32 v163, vcc, 1.0, v156, 1.0
	v_mul_f32_e32 v164, v163, v161
	v_div_scale_f32 v128, s[2:3], v157, v157, 1.0
	v_fma_f32 v162, -v160, v164, v163
	v_rcp_f32_e32 v129, v128
	v_fmac_f32_e32 v164, v162, v161
	s_nop 0
	v_fma_f32 v160, -v160, v164, v163
	v_fma_f32 v130, -v128, v129, 1.0
	v_div_fmas_f32 v160, v160, v161, v164
	v_fmac_f32_e32 v129, v130, v129
	v_div_fixup_f32 v156, v160, v156, 1.0
	v_div_scale_f32 v131, vcc, 1.0, v157, 1.0
	v_mul_f32_e32 v165, v131, v129
	v_div_scale_f32 v160, s[2:3], v158, v158, 1.0
	v_fma_f32 v130, -v128, v165, v131
	v_rcp_f32_e32 v161, v160
	v_fmac_f32_e32 v165, v130, v129
	s_nop 0
	v_fma_f32 v128, -v128, v165, v131
	v_fma_f32 v162, -v160, v161, 1.0
	v_div_fmas_f32 v128, v128, v129, v165
	v_fmac_f32_e32 v161, v162, v161
	v_div_fixup_f32 v157, v128, v157, 1.0
	v_div_scale_f32 v163, vcc, 1.0, v158, 1.0
	v_mul_f32_e32 v164, v163, v161
	v_div_scale_f32 v128, s[2:3], v159, v159, 1.0
	v_fma_f32 v162, -v160, v164, v163
	v_rcp_f32_e32 v129, v128
	v_fmac_f32_e32 v164, v162, v161
	s_nop 0
	v_fma_f32 v160, -v160, v164, v163
	v_fma_f32 v130, -v128, v129, 1.0
	v_div_fmas_f32 v160, v160, v161, v164
	v_fmac_f32_e32 v129, v130, v129
	v_div_fixup_f32 v158, v160, v158, 1.0
	v_div_scale_f32 v131, vcc, 1.0, v159, 1.0
	v_mul_f32_e32 v165, v131, v129
	v_fma_f32 v130, -v128, v165, v131
	v_fmac_f32_e32 v165, v130, v129
	v_fma_f32 v128, -v128, v165, v131
	v_div_fmas_f32 v128, v128, v129, v165
	v_div_fixup_f32 v159, v128, v159, 1.0
	v_lshlrev_b32_e32 v166, 16, v32
	v_and_b32_e32 v167, 0xffff0000, v32
	v_pk_fma_f32 v[152:153], v[4:5], v[152:153], v[166:167]
	v_lshlrev_b32_e32 v166, 16, v33
	v_and_b32_e32 v167, 0xffff0000, v33
	v_pk_fma_f32 v[154:155], v[6:7], v[154:155], v[166:167]
	v_lshlrev_b32_e32 v166, 16, v34
	v_and_b32_e32 v167, 0xffff0000, v34
	v_pk_fma_f32 v[156:157], v[0:1], v[156:157], v[166:167]
	v_lshlrev_b32_e32 v166, 16, v35
	v_and_b32_e32 v167, 0xffff0000, v35
	v_pk_fma_f32 v[158:159], v[2:3], v[158:159], v[166:167]
	v_cvt_pk_bf16_f32 v168, v152, v153
	v_cvt_pk_bf16_f32 v169, v154, v155
	v_cvt_pk_bf16_f32 v170, v156, v157
	v_cvt_pk_bf16_f32 v171, v158, v159
	global_store_dwordx4 v191, v[168:171], s[66:67] offset:256
	s_branch .LBB0_567
